# v34 + accumulator-stationary MFMA order in all 80 MFMA groups (general DAG scheduler: chain continuation first, then shared operand; partial-overlap RAW pairs kept 6 apart)
# baseline (speedup 1.0000x reference)
; #define PG8_STAGE(bufoff, gbase, voff) do { _Pragma("unroll") for (int _i = 0; _i < 2; ++_i) \
;         __builtin_amdgcn_global_load_lds((const unsigned*)((const char*)(gbase) + (voff)[_i]), (PG8_LAS unsigned*)(lds + (bufoff) + ldsw + _i * 8192), 16, 0, 0); } while (0)
; #define PG8_LDA(dst, b, h) do { _Pragma("unroll") for (int m = 0; m < 4; ++m) _Pragma("unroll") for (int k = 0; k < 2; ++k) dst[m][k] = *(const PG8_LAS bf16x8*)(lds + PG8_SA(b, h) + aoff + m * 2048 + k * 1024); } while (0)
; #define PG8_LDB(dst, b, h) do { _Pragma("unroll") for (int n = 0; n < 2; ++n) _Pragma("unroll") for (int k = 0; k < 2; ++k) dst[n][k] = *(const PG8_LAS bf16x8*)(lds + PG8_SB(b, h) + boff + n * 2048 + k * 1024); } while (0)
; #define PG8_MMA(ai, bj, At, Bt) do { __builtin_amdgcn_s_setprio(1); _Pragma("unroll") for (int m = 0; m < 4; ++m) _Pragma("unroll") for (int n = 0; n < 2; ++n) _Pragma("unroll") for (int k = 0; k < 2; ++k) \
;         acc[ai][bj][m][n] = mma16<Epi::I8>(Bt[n][k], At[m][k], acc[ai][bj][m][n]); __builtin_amdgcn_s_setprio(0); } while (0)
; #define PG8_WAIT_V(n) asm volatile("s_waitcnt vmcnt(" #n ")" ::: "memory")
; #define PG8_WAIT_L(n) asm volatile("s_waitcnt lgkmcnt(" #n ")" ::: "memory")
; #define PG8_BAR __builtin_amdgcn_s_barrier()
; #define PG8_SCHED __builtin_amdgcn_sched_barrier(0)
; template <class Epi, class Sched, bool ALIGN_EPI = false, bool SP2 = false>
; __device__ __forceinline__ void gemm_phase(PG8_LAS unsigned char* lds, const Gemm g, const Sched& S, const Epi& E) {
;     ...
;             PG8_LDB(B0, 0, 0); PG8_LDB(B1, 0, 1); PG8_SCHED; PG8_LDA(At, 0, 0); PG8_STAGE(PG8_SA(1, 1), a1 + hstep, voffA);
;             PG8_WAIT_V(8); PG8_WAIT_L(0); PG8_BAR; PG8_MMA(0, 0, At, B0); PG8_MMA(0, 1, At, B1); PG8_BAR; PG8_SCHED;
;             PG8_LDA(At, 0, 1); PG8_STAGE(PG8_SB(0, 0), b2, voffB); PG8_STAGE(PG8_SB(0, 1), b2 + hstep, voffB); PG8_STAGE(PG8_SA(0, 0), a2, voffA);
;             PG8_WAIT_V(8); PG8_WAIT_L(0); PG8_BAR; PG8_MMA(1, 0, At, B0); PG8_MMA(1, 1, At, B1); PG8_BAR; PG8_SCHED;
.Lpeel80:
	s_add_u32 s8, s0, 0x100
	s_addc_u32 s9, s1, 0
	s_add_i32 vcc_hi, 0, 0x10000
	s_cmp_eq_u32 vcc_lo, 12
	s_cselect_b32 s13, s66, s9
	s_cselect_b32 s12, s67, s8
	s_cselect_b32 s7, s82, s97
	s_cselect_b32 s6, s83, s96
	s_add_i32 s4, 0, 0x14000
	v_add_u32_e32 v38, vcc_hi, v242
	v_add_u32_e32 v158, s4, v242
	ds_read_b128 v[18:21], v38
	ds_read_b128 v[22:25], v38 offset:1024
	ds_read_b128 v[34:37], v38 offset:2048
	ds_read_b128 v[38:41], v38 offset:3072
	ds_read_b128 v[130:133], v158
	ds_read_b128 v[134:137], v158 offset:1024
	ds_read_b128 v[154:157], v158 offset:2048
	ds_read_b128 v[158:161], v158 offset:3072
	s_add_i32 m0, s11, 0xc000
	ds_read_b128 v[162:165], v243
	ds_read_b128 v[166:169], v243 offset:1024
	ds_read_b128 v[170:173], v243 offset:2048
	ds_read_b128 v[174:177], v243 offset:3072
	ds_read_b128 v[178:181], v243 offset:4096
	ds_read_b128 v[182:185], v243 offset:5120
	ds_read_b128 v[186:189], v243 offset:6144
	ds_read_b128 v[190:193], v243 offset:7168
	global_load_lds_dwordx4 v216, s[0:1]
	s_add_i32 m0, s11, 0xe000
	s_nop 0
	global_load_lds_dwordx4 v218, s[0:1]
	s_waitcnt vmcnt(8)
	s_waitcnt lgkmcnt(0)
	s_barrier
	s_setprio 1
	s_waitcnt lgkmcnt(0)
	v_mfma_i32_16x16x64_i8 v[150:153], v[18:21], v[162:165], 0
	v_mfma_i32_16x16x64_i8 v[150:153], v[22:25], v[166:169], v[150:153]
	v_mfma_i32_16x16x64_i8 v[146:149], v[34:37], v[162:165], 0
	v_mfma_i32_16x16x64_i8 v[146:149], v[38:41], v[166:169], v[146:149]
	v_mfma_i32_16x16x64_i8 v[118:121], v[18:21], v[170:173], 0
	v_mfma_i32_16x16x64_i8 v[118:121], v[22:25], v[174:177], v[118:121]
	v_mfma_i32_16x16x64_i8 v[110:113], v[34:37], v[170:173], 0
	v_mfma_i32_16x16x64_i8 v[110:113], v[38:41], v[174:177], v[110:113]
	v_mfma_i32_16x16x64_i8 v[54:57], v[18:21], v[178:181], 0
	v_mfma_i32_16x16x64_i8 v[54:57], v[22:25], v[182:185], v[54:57]
	v_mfma_i32_16x16x64_i8 v[30:33], v[34:37], v[178:181], 0
	v_mfma_i32_16x16x64_i8 v[30:33], v[38:41], v[182:185], v[30:33]
	v_mfma_i32_16x16x64_i8 v[94:97], v[18:21], v[186:189], 0
	v_mfma_i32_16x16x64_i8 v[94:97], v[22:25], v[190:193], v[94:97]
	v_mfma_i32_16x16x64_i8 v[58:61], v[34:37], v[186:189], 0
	v_mfma_i32_16x16x64_i8 v[58:61], v[38:41], v[190:193], v[58:61]
	s_setprio 0
	s_setprio 1
	v_mfma_i32_16x16x64_i8 v[142:145], v[130:133], v[162:165], 0
	v_mfma_i32_16x16x64_i8 v[142:145], v[134:137], v[166:169], v[142:145]
	v_mfma_i32_16x16x64_i8 v[138:141], v[154:157], v[162:165], 0
	v_mfma_i32_16x16x64_i8 v[138:141], v[158:161], v[166:169], v[138:141]
	v_mfma_i32_16x16x64_i8 v[102:105], v[130:133], v[170:173], 0
	v_mfma_i32_16x16x64_i8 v[102:105], v[134:137], v[174:177], v[102:105]
	v_mfma_i32_16x16x64_i8 v[98:101], v[154:157], v[170:173], 0
	v_mfma_i32_16x16x64_i8 v[98:101], v[158:161], v[174:177], v[98:101]
	v_mfma_i32_16x16x64_i8 v[42:45], v[130:133], v[178:181], 0
	v_mfma_i32_16x16x64_i8 v[42:45], v[134:137], v[182:185], v[42:45]
	v_mfma_i32_16x16x64_i8 v[26:29], v[154:157], v[178:181], 0
	v_mfma_i32_16x16x64_i8 v[26:29], v[158:161], v[182:185], v[26:29]
	v_mfma_i32_16x16x64_i8 v[78:81], v[130:133], v[186:189], 0
	v_mfma_i32_16x16x64_i8 v[78:81], v[134:137], v[190:193], v[78:81]
	v_mfma_i32_16x16x64_i8 v[62:65], v[154:157], v[186:189], 0
	v_mfma_i32_16x16x64_i8 v[62:65], v[158:161], v[190:193], v[62:65]
	s_setprio 0
	s_barrier
	s_add_i32 s0, vcc_hi, s69
	v_lshl_add_u64 v[198:199], s[6:7], 0, v[0:1]
	s_mov_b32 m0, s0
	ds_read_b128 v[162:165], v243 offset:16384
	ds_read_b128 v[166:169], v243 offset:17408
	ds_read_b128 v[170:173], v243 offset:18432
	ds_read_b128 v[174:177], v243 offset:19456
	ds_read_b128 v[178:181], v243 offset:20480
	ds_read_b128 v[182:185], v243 offset:21504
	ds_read_b128 v[186:189], v243 offset:22528
	ds_read_b128 v[190:193], v243 offset:23552
	global_load_lds_dwordx4 v[198:199], off
	s_add_i32 m0, s0, 0x2000
	s_add_u32 s0, s6, 0x40000
	v_lshl_add_u64 v[200:201], s[6:7], 0, v[214:215]
	s_addc_u32 s1, s7, 0
	s_add_i32 s4, s4, s69
	global_load_lds_dwordx4 v[200:201], off
	s_mov_b32 m0, s4
	v_lshl_add_u64 v[206:207], s[12:13], 0, v[210:211]
	global_load_lds_dwordx4 v0, s[0:1]
	s_add_i32 m0, s4, 0x2000
	v_lshl_add_u64 v[220:221], s[12:13], 0, v[212:213]
	global_load_lds_dwordx4 v214, s[0:1]
	s_mov_b32 m0, s11
	s_nop 0
	global_load_lds_dwordx4 v[206:207], off
	s_mov_b32 m0, s71
	s_nop 0
	global_load_lds_dwordx4 v[220:221], off
	s_waitcnt vmcnt(8)
	s_waitcnt lgkmcnt(0)
	s_barrier
	s_setprio 1
	s_waitcnt lgkmcnt(0)
	v_mfma_i32_16x16x64_i8 v[106:109], v[18:21], v[162:165], 0
	v_mfma_i32_16x16x64_i8 v[106:109], v[22:25], v[166:169], v[106:109]
	v_mfma_i32_16x16x64_i8 v[46:49], v[34:37], v[162:165], 0
	v_mfma_i32_16x16x64_i8 v[46:49], v[38:41], v[166:169], v[46:49]
	v_mfma_i32_16x16x64_i8 v[14:17], v[18:21], v[170:173], 0
	v_mfma_i32_16x16x64_i8 v[14:17], v[22:25], v[174:177], v[14:17]
	v_mfma_i32_16x16x64_i8 v[6:9], v[34:37], v[170:173], 0
	v_mfma_i32_16x16x64_i8 v[6:9], v[38:41], v[174:177], v[6:9]
	v_mfma_i32_16x16x64_i8 v[90:93], v[18:21], v[178:181], 0
	v_mfma_i32_16x16x64_i8 v[90:93], v[22:25], v[182:185], v[90:93]
	v_mfma_i32_16x16x64_i8 v[86:89], v[34:37], v[178:181], 0
	v_mfma_i32_16x16x64_i8 v[86:89], v[38:41], v[182:185], v[86:89]
	v_mfma_i32_16x16x64_i8 v[18:21], v[18:21], v[186:189], 0
	v_mfma_i32_16x16x64_i8 v[18:21], v[22:25], v[190:193], v[18:21]
	v_mfma_i32_16x16x64_i8 v[22:25], v[34:37], v[186:189], 0
	v_mfma_i32_16x16x64_i8 v[22:25], v[38:41], v[190:193], v[22:25]
	s_setprio 0
	s_setprio 1
	v_mfma_i32_16x16x64_i8 v[38:41], v[154:157], v[162:165], 0
	v_mfma_i32_16x16x64_i8 v[38:41], v[158:161], v[166:169], v[38:41]
	v_mfma_i32_16x16x64_i8 v[50:53], v[130:133], v[178:181], 0
	v_mfma_i32_16x16x64_i8 v[82:85], v[134:137], v[182:185], v[50:53]
	v_mfma_i32_16x16x64_i8 v[50:53], v[154:157], v[178:181], 0
	v_mfma_i32_16x16x64_i8 v[74:77], v[158:161], v[182:185], v[50:53]
	v_mfma_i32_16x16x64_i8 v[50:53], v[130:133], v[186:189], 0
	v_mfma_i32_16x16x64_i8 v[122:125], v[134:137], v[190:193], v[50:53]
	v_mfma_i32_16x16x64_i8 v[10:13], v[130:133], v[170:173], 0
	v_mfma_i32_16x16x64_i8 v[10:13], v[134:137], v[174:177], v[10:13]
	v_mfma_i32_16x16x64_i8 v[2:5], v[154:157], v[170:173], 0
	v_mfma_i32_16x16x64_i8 v[2:5], v[158:161], v[174:177], v[2:5]
	v_mfma_i32_16x16x64_i8 v[50:53], v[154:157], v[186:189], 0
	v_mfma_i32_16x16x64_i8 v[70:73], v[158:161], v[190:193], v[50:53]
	v_mfma_i32_16x16x64_i8 v[34:37], v[130:133], v[162:165], 0
	v_mfma_i32_16x16x64_i8 v[34:37], v[134:137], v[166:169], v[34:37]
	s_setprio 0
	s_barrier
; #define PG8_STAGE(bufoff, gbase, voff) do { _Pragma("unroll") for (int _i = 0; _i < 2; ++_i) \
;         __builtin_amdgcn_global_load_lds((const unsigned*)((const char*)(gbase) + (voff)[_i]), (PG8_LAS unsigned*)(lds + (bufoff) + ldsw + _i * 8192), 16, 0, 0); } while (0)
; #define PG8_LDA(dst, b, h) do { _Pragma("unroll") for (int m = 0; m < 4; ++m) _Pragma("unroll") for (int k = 0; k < 2; ++k) dst[m][k] = *(const PG8_LAS bf16x8*)(lds + PG8_SA(b, h) + aoff + m * 2048 + k * 1024); } while (0)
; #define PG8_LDB(dst, b, h) do { _Pragma("unroll") for (int n = 0; n < 2; ++n) _Pragma("unroll") for (int k = 0; k < 2; ++k) dst[n][k] = *(const PG8_LAS bf16x8*)(lds + PG8_SB(b, h) + boff + n * 2048 + k * 1024); } while (0)
; #define PG8_MMA(ai, bj, At, Bt) do { __builtin_amdgcn_s_setprio(1); _Pragma("unroll") for (int m = 0; m < 4; ++m) _Pragma("unroll") for (int n = 0; n < 2; ++n) _Pragma("unroll") for (int k = 0; k < 2; ++k) \
;         acc[ai][bj][m][n] = mma16<Epi::I8>(Bt[n][k], At[m][k], acc[ai][bj][m][n]); __builtin_amdgcn_s_setprio(0); } while (0)
; #define PG8_WAIT_V(n) asm volatile("s_waitcnt vmcnt(" #n ")" ::: "memory")
; #define PG8_WAIT_L(n) asm volatile("s_waitcnt lgkmcnt(" #n ")" ::: "memory")
; #define PG8_BAR __builtin_amdgcn_s_barrier()
; #define PG8_SCHED __builtin_amdgcn_sched_barrier(0)
; template <class Epi, class Sched, bool ALIGN_EPI = false, bool SP2 = false>
; __device__ __forceinline__ void gemm_phase(PG8_LAS unsigned char* lds, const Gemm g, const Sched& S, const Epi& E) {
;     ...
;             PG8_LDB(B0, 1, 0); PG8_LDB(B1, 1, 1); PG8_SCHED; PG8_LDA(At, 1, 0); PG8_STAGE(PG8_SA(0, 1), a2 + hstep, voffA);
;             PG8_WAIT_V(8); PG8_WAIT_L(0); PG8_BAR; PG8_MMA(0, 0, At, B0); PG8_MMA(0, 1, At, B1); PG8_BAR; PG8_SCHED;
;             PG8_LDA(At, 1, 1); PG8_STAGE(PG8_SB(1, 0), b3, voffB); PG8_STAGE(PG8_SB(1, 1), b3 + hstep, voffB); PG8_STAGE(PG8_SA(1, 0), a3, voffA);
;             PG8_WAIT_V(8); PG8_WAIT_L(0); PG8_BAR; PG8_MMA(1, 0, At, B0); PG8_MMA(1, 1, At, B1); PG8_BAR; PG8_SCHED;
	s_add_i32 s4, 0, 0x18000
	v_add_u32_e32 v126, s4, v242
	s_add_i32 s5, 0, 0x1c000
	ds_read_b128 v[50:53], v126
	ds_read_b128 v[66:69], v126 offset:1024
	ds_read_b128 v[114:117], v126 offset:2048
	ds_read_b128 v[130:133], v126 offset:3072
	v_add_u32_e32 v126, s5, v242
	ds_read_b128 v[134:137], v126
	ds_read_b128 v[154:157], v126 offset:1024
	ds_read_b128 v[158:161], v126 offset:2048
	ds_read_b128 v[162:165], v126 offset:3072
	s_add_u32 s0, s12, 0x40000
	s_addc_u32 s1, s13, 0
	s_mov_b32 m0, s80
	ds_read_b128 v[126:129], v243 offset:32768
	ds_read_b128 v[166:169], v243 offset:33792
	ds_read_b128 v[170:173], v243 offset:34816
	ds_read_b128 v[174:177], v243 offset:35840
	ds_read_b128 v[178:181], v243 offset:36864
	ds_read_b128 v[182:185], v243 offset:37888
	ds_read_b128 v[186:189], v243 offset:38912
	ds_read_b128 v[190:193], v243 offset:39936
	global_load_lds_dwordx4 v210, s[0:1]
	s_mov_b32 m0, s81
	s_nop 0
	global_load_lds_dwordx4 v212, s[0:1]
	s_waitcnt vmcnt(8)
	s_waitcnt lgkmcnt(0)
	s_barrier
	s_setprio 1
	s_waitcnt lgkmcnt(0)
	v_mfma_i32_16x16x64_i8 v[150:153], v[50:53], v[126:129], v[150:153]
	v_mfma_i32_16x16x64_i8 v[150:153], v[66:69], v[166:169], v[150:153]
	v_mfma_i32_16x16x64_i8 v[146:149], v[114:117], v[126:129], v[146:149]
	v_mfma_i32_16x16x64_i8 v[146:149], v[130:133], v[166:169], v[146:149]
	v_mfma_i32_16x16x64_i8 v[118:121], v[50:53], v[170:173], v[118:121]
	v_mfma_i32_16x16x64_i8 v[118:121], v[66:69], v[174:177], v[118:121]
	v_mfma_i32_16x16x64_i8 v[110:113], v[114:117], v[170:173], v[110:113]
	v_mfma_i32_16x16x64_i8 v[110:113], v[130:133], v[174:177], v[110:113]
	v_mfma_i32_16x16x64_i8 v[54:57], v[50:53], v[178:181], v[54:57]
	v_mfma_i32_16x16x64_i8 v[54:57], v[66:69], v[182:185], v[54:57]
	v_mfma_i32_16x16x64_i8 v[30:33], v[114:117], v[178:181], v[30:33]
	v_mfma_i32_16x16x64_i8 v[30:33], v[130:133], v[182:185], v[30:33]
	v_mfma_i32_16x16x64_i8 v[94:97], v[50:53], v[186:189], v[94:97]
	v_mfma_i32_16x16x64_i8 v[94:97], v[66:69], v[190:193], v[94:97]
	v_mfma_i32_16x16x64_i8 v[58:61], v[114:117], v[186:189], v[58:61]
	v_mfma_i32_16x16x64_i8 v[58:61], v[130:133], v[190:193], v[58:61]
	s_setprio 0
	s_setprio 1
	v_mfma_i32_16x16x64_i8 v[142:145], v[134:137], v[126:129], v[142:145]
	v_mfma_i32_16x16x64_i8 v[142:145], v[154:157], v[166:169], v[142:145]
	v_mfma_i32_16x16x64_i8 v[126:129], v[158:161], v[126:129], v[138:141]
	v_mfma_i32_16x16x64_i8 v[138:141], v[162:165], v[166:169], v[126:129]
	v_mfma_i32_16x16x64_i8 v[102:105], v[134:137], v[170:173], v[102:105]
	v_mfma_i32_16x16x64_i8 v[102:105], v[154:157], v[174:177], v[102:105]
	v_mfma_i32_16x16x64_i8 v[98:101], v[158:161], v[170:173], v[98:101]
	v_mfma_i32_16x16x64_i8 v[98:101], v[162:165], v[174:177], v[98:101]
	v_mfma_i32_16x16x64_i8 v[42:45], v[134:137], v[178:181], v[42:45]
	v_mfma_i32_16x16x64_i8 v[42:45], v[154:157], v[182:185], v[42:45]
	v_mfma_i32_16x16x64_i8 v[26:29], v[158:161], v[178:181], v[26:29]
	v_mfma_i32_16x16x64_i8 v[26:29], v[162:165], v[182:185], v[26:29]
	v_mfma_i32_16x16x64_i8 v[78:81], v[134:137], v[186:189], v[78:81]
	v_mfma_i32_16x16x64_i8 v[78:81], v[154:157], v[190:193], v[78:81]
	v_mfma_i32_16x16x64_i8 v[62:65], v[158:161], v[186:189], v[62:65]
	v_mfma_i32_16x16x64_i8 v[62:65], v[162:165], v[190:193], v[62:65]
	s_setprio 0
	s_barrier
	s_add_i32 s0, s4, s69
	v_lshl_add_u64 v[126:127], v[198:199], 0, s[92:93]
	s_mov_b32 m0, s0
	ds_read_b128 v[166:169], v243 offset:49152
	ds_read_b128 v[170:173], v243 offset:50176
	ds_read_b128 v[174:177], v243 offset:51200
	ds_read_b128 v[178:181], v243 offset:52224
	ds_read_b128 v[182:185], v243 offset:53248
	ds_read_b128 v[186:189], v243 offset:54272
	ds_read_b128 v[190:193], v243 offset:55296
	ds_read_b128 v[194:197], v243 offset:56320
	global_load_lds_dwordx4 v[126:127], off
	s_add_i32 m0, s0, 0x2000
	s_add_u32 s0, s6, 0x40080
	v_lshl_add_u64 v[126:127], v[200:201], 0, s[92:93]
	s_addc_u32 s1, s7, 0
	s_add_i32 s4, s5, s69
	global_load_lds_dwordx4 v[126:127], off
	s_mov_b32 m0, s4
	s_nop 0
	global_load_lds_dwordx4 v0, s[0:1]
	s_add_i32 m0, s4, 0x2000
	s_nop 0
	global_load_lds_dwordx4 v214, s[0:1]
	v_lshl_add_u64 v[126:127], v[206:207], 0, s[92:93]
	s_mov_b32 m0, s84
	s_nop 0
	global_load_lds_dwordx4 v[126:127], off
	v_lshl_add_u64 v[126:127], v[220:221], 0, s[92:93]
	s_mov_b32 m0, s85
	s_nop 0
	global_load_lds_dwordx4 v[126:127], off
	s_waitcnt vmcnt(8)
	s_waitcnt lgkmcnt(0)
	s_barrier
	s_setprio 1
	s_waitcnt lgkmcnt(0)
	v_mfma_i32_16x16x64_i8 v[18:21], v[50:53], v[190:193], v[18:21]
	v_mfma_i32_16x16x64_i8 v[126:129], v[66:69], v[194:197], v[18:21]
	v_mfma_i32_16x16x64_i8 v[106:109], v[50:53], v[166:169], v[106:109]
	v_mfma_i32_16x16x64_i8 v[106:109], v[66:69], v[170:173], v[106:109]
	v_mfma_i32_16x16x64_i8 v[46:49], v[114:117], v[166:169], v[46:49]
	v_mfma_i32_16x16x64_i8 v[46:49], v[130:133], v[170:173], v[46:49]
	v_mfma_i32_16x16x64_i8 v[14:17], v[50:53], v[174:177], v[14:17]
	v_mfma_i32_16x16x64_i8 v[14:17], v[66:69], v[178:181], v[14:17]
	v_mfma_i32_16x16x64_i8 v[6:9], v[114:117], v[174:177], v[6:9]
	v_mfma_i32_16x16x64_i8 v[6:9], v[130:133], v[178:181], v[6:9]
	v_mfma_i32_16x16x64_i8 v[90:93], v[50:53], v[182:185], v[90:93]
	v_mfma_i32_16x16x64_i8 v[90:93], v[66:69], v[186:189], v[90:93]
	v_mfma_i32_16x16x64_i8 v[86:89], v[114:117], v[182:185], v[86:89]
	v_mfma_i32_16x16x64_i8 v[86:89], v[130:133], v[186:189], v[86:89]
	v_mfma_i32_16x16x64_i8 v[18:21], v[114:117], v[190:193], v[22:25]
	v_mfma_i32_16x16x64_i8 v[66:69], v[130:133], v[194:197], v[18:21]
	s_setprio 0
	s_setprio 1
	v_mfma_i32_16x16x64_i8 v[18:21], v[134:137], v[166:169], v[34:37]
	v_mfma_i32_16x16x64_i8 v[114:117], v[154:157], v[170:173], v[18:21]
	v_mfma_i32_16x16x64_i8 v[18:21], v[158:161], v[166:169], v[38:41]
	v_mfma_i32_16x16x64_i8 v[50:53], v[162:165], v[170:173], v[18:21]
	v_mfma_i32_16x16x64_i8 v[18:21], v[134:137], v[182:185], v[82:85]
	v_mfma_i32_16x16x64_i8 v[82:85], v[154:157], v[186:189], v[18:21]
	v_mfma_i32_16x16x64_i8 v[18:21], v[158:161], v[182:185], v[74:77]
	v_mfma_i32_16x16x64_i8 v[74:77], v[162:165], v[186:189], v[18:21]
	v_mfma_i32_16x16x64_i8 v[18:21], v[134:137], v[190:193], v[122:125]
	v_mfma_i32_16x16x64_i8 v[122:125], v[154:157], v[194:197], v[18:21]
	v_mfma_i32_16x16x64_i8 v[10:13], v[134:137], v[174:177], v[10:13]
	v_mfma_i32_16x16x64_i8 v[10:13], v[154:157], v[178:181], v[10:13]
	v_mfma_i32_16x16x64_i8 v[2:5], v[158:161], v[174:177], v[2:5]
	v_mfma_i32_16x16x64_i8 v[2:5], v[162:165], v[178:181], v[2:5]
	v_mfma_i32_16x16x64_i8 v[18:21], v[158:161], v[190:193], v[70:73]
	v_mfma_i32_16x16x64_i8 v[70:73], v[162:165], v[194:197], v[18:21]
	s_setprio 0
	s_barrier
	s_add_i32 vcc_lo, vcc_lo, 2
	s_add_u32 s96, s96, 0x100
	s_addc_u32 s97, s97, 0
	s_cmp_gt_u32 vcc_lo, 13
	s_mov_b64 s[0:1], s[8:9]
	s_cbranch_scc0 .LBB0_80
	s_branch .Lpeelx80
; #define PG8_STAGE(bufoff, gbase, voff) do { _Pragma("unroll") for (int _i = 0; _i < 2; ++_i) \
;         __builtin_amdgcn_global_load_lds((const unsigned*)((const char*)(gbase) + (voff)[_i]), (PG8_LAS unsigned*)(lds + (bufoff) + ldsw + _i * 8192), 16, 0, 0); } while (0)
; #define PG8_LDA(dst, b, h) do { _Pragma("unroll") for (int m = 0; m < 4; ++m) _Pragma("unroll") for (int k = 0; k < 2; ++k) dst[m][k] = *(const PG8_LAS bf16x8*)(lds + PG8_SA(b, h) + aoff + m * 2048 + k * 1024); } while (0)
; #define PG8_LDB(dst, b, h) do { _Pragma("unroll") for (int n = 0; n < 2; ++n) _Pragma("unroll") for (int k = 0; k < 2; ++k) dst[n][k] = *(const PG8_LAS bf16x8*)(lds + PG8_SB(b, h) + boff + n * 2048 + k * 1024); } while (0)
; #define PG8_MMA(ai, bj, At, Bt) do { __builtin_amdgcn_s_setprio(1); _Pragma("unroll") for (int m = 0; m < 4; ++m) _Pragma("unroll") for (int n = 0; n < 2; ++n) _Pragma("unroll") for (int k = 0; k < 2; ++k) \
;         acc[ai][bj][m][n] = mma16<Epi::I8>(Bt[n][k], At[m][k], acc[ai][bj][m][n]); __builtin_amdgcn_s_setprio(0); } while (0)
; #define PG8_WAIT_V(n) asm volatile("s_waitcnt vmcnt(" #n ")" ::: "memory")
; #define PG8_WAIT_L(n) asm volatile("s_waitcnt lgkmcnt(" #n ")" ::: "memory")
; #define PG8_BAR __builtin_amdgcn_s_barrier()
; #define PG8_SCHED __builtin_amdgcn_sched_barrier(0)
; template <class Epi, class Sched, bool ALIGN_EPI = false, bool SP2 = false>
; __device__ __forceinline__ void gemm_phase(PG8_LAS unsigned char* lds, const Gemm g, const Sched& S, const Epi& E) {
;     ...
;             PG8_LDB(B0, 0, 0); PG8_LDB(B1, 0, 1); PG8_SCHED; PG8_LDA(At, 0, 0); PG8_STAGE(PG8_SA(1, 1), a1 + hstep, voffA);
;             PG8_WAIT_V(8); PG8_WAIT_L(0); PG8_BAR; PG8_MMA(0, 0, At, B0); PG8_MMA(0, 1, At, B1); PG8_BAR; PG8_SCHED;
;             PG8_LDA(At, 0, 1); PG8_STAGE(PG8_SB(0, 0), b2, voffB); PG8_STAGE(PG8_SB(0, 1), b2 + hstep, voffB); PG8_STAGE(PG8_SA(0, 0), a2, voffA);
;             PG8_WAIT_V(8); PG8_WAIT_L(0); PG8_BAR; PG8_MMA(1, 0, At, B0); PG8_MMA(1, 1, At, B1); PG8_BAR; PG8_SCHED;
.LBB0_80:
	s_add_u32 s8, s0, 0x100
	s_addc_u32 s9, s1, 0
	s_add_i32 vcc_hi, 0, 0x10000
	s_cmp_eq_u32 vcc_lo, 12
	s_cselect_b32 s13, s66, s9
	s_cselect_b32 s12, s67, s8
	s_cselect_b32 s7, s82, s97
	s_cselect_b32 s6, s83, s96
	s_add_i32 s4, 0, 0x14000
	v_add_u32_e32 v38, vcc_hi, v242
	v_add_u32_e32 v158, s4, v242
	ds_read_b128 v[18:21], v38
	ds_read_b128 v[22:25], v38 offset:1024
	ds_read_b128 v[34:37], v38 offset:2048
	ds_read_b128 v[38:41], v38 offset:3072
	ds_read_b128 v[130:133], v158
	ds_read_b128 v[134:137], v158 offset:1024
	ds_read_b128 v[154:157], v158 offset:2048
	ds_read_b128 v[158:161], v158 offset:3072
	s_add_i32 m0, s11, 0xc000
	ds_read_b128 v[162:165], v243
	ds_read_b128 v[166:169], v243 offset:1024
	ds_read_b128 v[170:173], v243 offset:2048
	ds_read_b128 v[174:177], v243 offset:3072
	ds_read_b128 v[178:181], v243 offset:4096
	ds_read_b128 v[182:185], v243 offset:5120
	ds_read_b128 v[186:189], v243 offset:6144
	ds_read_b128 v[190:193], v243 offset:7168
	global_load_lds_dwordx4 v216, s[0:1]
	s_add_i32 m0, s11, 0xe000
	s_nop 0
	global_load_lds_dwordx4 v218, s[0:1]
	s_waitcnt vmcnt(8)
	s_waitcnt lgkmcnt(0)
	s_barrier
	s_setprio 1
	s_waitcnt lgkmcnt(0)
	v_mfma_i32_16x16x64_i8 v[150:153], v[18:21], v[162:165], v[150:153]
	v_mfma_i32_16x16x64_i8 v[150:153], v[22:25], v[166:169], v[150:153]
	v_mfma_i32_16x16x64_i8 v[146:149], v[34:37], v[162:165], v[146:149]
	v_mfma_i32_16x16x64_i8 v[146:149], v[38:41], v[166:169], v[146:149]
	v_mfma_i32_16x16x64_i8 v[118:121], v[18:21], v[170:173], v[118:121]
	v_mfma_i32_16x16x64_i8 v[118:121], v[22:25], v[174:177], v[118:121]
	v_mfma_i32_16x16x64_i8 v[110:113], v[34:37], v[170:173], v[110:113]
	v_mfma_i32_16x16x64_i8 v[110:113], v[38:41], v[174:177], v[110:113]
	v_mfma_i32_16x16x64_i8 v[54:57], v[18:21], v[178:181], v[54:57]
	v_mfma_i32_16x16x64_i8 v[54:57], v[22:25], v[182:185], v[54:57]
	v_mfma_i32_16x16x64_i8 v[30:33], v[34:37], v[178:181], v[30:33]
	v_mfma_i32_16x16x64_i8 v[30:33], v[38:41], v[182:185], v[30:33]
	v_mfma_i32_16x16x64_i8 v[94:97], v[18:21], v[186:189], v[94:97]
	v_mfma_i32_16x16x64_i8 v[94:97], v[22:25], v[190:193], v[94:97]
	v_mfma_i32_16x16x64_i8 v[58:61], v[34:37], v[186:189], v[58:61]
	v_mfma_i32_16x16x64_i8 v[58:61], v[38:41], v[190:193], v[58:61]
	s_setprio 0
	s_setprio 1
	v_mfma_i32_16x16x64_i8 v[142:145], v[130:133], v[162:165], v[142:145]
	v_mfma_i32_16x16x64_i8 v[142:145], v[134:137], v[166:169], v[142:145]
	v_mfma_i32_16x16x64_i8 v[138:141], v[154:157], v[162:165], v[138:141]
	v_mfma_i32_16x16x64_i8 v[138:141], v[158:161], v[166:169], v[138:141]
	v_mfma_i32_16x16x64_i8 v[102:105], v[130:133], v[170:173], v[102:105]
	v_mfma_i32_16x16x64_i8 v[102:105], v[134:137], v[174:177], v[102:105]
	v_mfma_i32_16x16x64_i8 v[98:101], v[154:157], v[170:173], v[98:101]
	v_mfma_i32_16x16x64_i8 v[98:101], v[158:161], v[174:177], v[98:101]
	v_mfma_i32_16x16x64_i8 v[42:45], v[130:133], v[178:181], v[42:45]
	v_mfma_i32_16x16x64_i8 v[42:45], v[134:137], v[182:185], v[42:45]
	v_mfma_i32_16x16x64_i8 v[26:29], v[154:157], v[178:181], v[26:29]
	v_mfma_i32_16x16x64_i8 v[26:29], v[158:161], v[182:185], v[26:29]
	v_mfma_i32_16x16x64_i8 v[78:81], v[130:133], v[186:189], v[78:81]
	v_mfma_i32_16x16x64_i8 v[78:81], v[134:137], v[190:193], v[78:81]
	v_mfma_i32_16x16x64_i8 v[62:65], v[154:157], v[186:189], v[62:65]
	v_mfma_i32_16x16x64_i8 v[62:65], v[158:161], v[190:193], v[62:65]
	s_setprio 0
	s_barrier
	s_add_i32 s0, vcc_hi, s69
	v_lshl_add_u64 v[198:199], s[6:7], 0, v[0:1]
	s_mov_b32 m0, s0
	ds_read_b128 v[162:165], v243 offset:16384
	ds_read_b128 v[166:169], v243 offset:17408
	ds_read_b128 v[170:173], v243 offset:18432
	ds_read_b128 v[174:177], v243 offset:19456
	ds_read_b128 v[178:181], v243 offset:20480
	ds_read_b128 v[182:185], v243 offset:21504
	ds_read_b128 v[186:189], v243 offset:22528
	ds_read_b128 v[190:193], v243 offset:23552
	global_load_lds_dwordx4 v[198:199], off
	s_add_i32 m0, s0, 0x2000
	s_add_u32 s0, s6, 0x40000
	v_lshl_add_u64 v[200:201], s[6:7], 0, v[214:215]
	s_addc_u32 s1, s7, 0
	s_add_i32 s4, s4, s69
	global_load_lds_dwordx4 v[200:201], off
	s_mov_b32 m0, s4
	v_lshl_add_u64 v[206:207], s[12:13], 0, v[210:211]
	global_load_lds_dwordx4 v0, s[0:1]
	s_add_i32 m0, s4, 0x2000
	v_lshl_add_u64 v[220:221], s[12:13], 0, v[212:213]
	global_load_lds_dwordx4 v214, s[0:1]
	s_mov_b32 m0, s11
	s_nop 0
	global_load_lds_dwordx4 v[206:207], off
	s_mov_b32 m0, s71
	s_nop 0
	global_load_lds_dwordx4 v[220:221], off
	s_waitcnt vmcnt(8)
	s_waitcnt lgkmcnt(0)
	s_barrier
	s_setprio 1
	s_waitcnt lgkmcnt(0)
	v_mfma_i32_16x16x64_i8 v[106:109], v[18:21], v[162:165], v[106:109]
	v_mfma_i32_16x16x64_i8 v[106:109], v[22:25], v[166:169], v[106:109]
	v_mfma_i32_16x16x64_i8 v[46:49], v[34:37], v[162:165], v[46:49]
	v_mfma_i32_16x16x64_i8 v[46:49], v[38:41], v[166:169], v[46:49]
	v_mfma_i32_16x16x64_i8 v[14:17], v[18:21], v[170:173], v[14:17]
	v_mfma_i32_16x16x64_i8 v[14:17], v[22:25], v[174:177], v[14:17]
	v_mfma_i32_16x16x64_i8 v[6:9], v[34:37], v[170:173], v[6:9]
	v_mfma_i32_16x16x64_i8 v[6:9], v[38:41], v[174:177], v[6:9]
	v_mfma_i32_16x16x64_i8 v[90:93], v[18:21], v[178:181], v[90:93]
	v_mfma_i32_16x16x64_i8 v[90:93], v[22:25], v[182:185], v[90:93]
	v_mfma_i32_16x16x64_i8 v[86:89], v[34:37], v[178:181], v[86:89]
	v_mfma_i32_16x16x64_i8 v[86:89], v[38:41], v[182:185], v[86:89]
	v_mfma_i32_16x16x64_i8 v[18:21], v[18:21], v[186:189], v[126:129]
	v_mfma_i32_16x16x64_i8 v[18:21], v[22:25], v[190:193], v[18:21]
	v_mfma_i32_16x16x64_i8 v[22:25], v[34:37], v[186:189], v[66:69]
	v_mfma_i32_16x16x64_i8 v[22:25], v[38:41], v[190:193], v[22:25]
	s_setprio 0
	s_setprio 1
	v_mfma_i32_16x16x64_i8 v[38:41], v[154:157], v[162:165], v[50:53]
	v_mfma_i32_16x16x64_i8 v[38:41], v[158:161], v[166:169], v[38:41]
	v_mfma_i32_16x16x64_i8 v[50:53], v[130:133], v[178:181], v[82:85]
	v_mfma_i32_16x16x64_i8 v[82:85], v[134:137], v[182:185], v[50:53]
	v_mfma_i32_16x16x64_i8 v[50:53], v[154:157], v[178:181], v[74:77]
	v_mfma_i32_16x16x64_i8 v[74:77], v[158:161], v[182:185], v[50:53]
	v_mfma_i32_16x16x64_i8 v[50:53], v[130:133], v[186:189], v[122:125]
	v_mfma_i32_16x16x64_i8 v[122:125], v[134:137], v[190:193], v[50:53]
	v_mfma_i32_16x16x64_i8 v[10:13], v[130:133], v[170:173], v[10:13]
	v_mfma_i32_16x16x64_i8 v[10:13], v[134:137], v[174:177], v[10:13]
	v_mfma_i32_16x16x64_i8 v[2:5], v[154:157], v[170:173], v[2:5]
	v_mfma_i32_16x16x64_i8 v[2:5], v[158:161], v[174:177], v[2:5]
	v_mfma_i32_16x16x64_i8 v[50:53], v[154:157], v[186:189], v[70:73]
	v_mfma_i32_16x16x64_i8 v[70:73], v[158:161], v[190:193], v[50:53]
	v_mfma_i32_16x16x64_i8 v[34:37], v[130:133], v[162:165], v[114:117]
	v_mfma_i32_16x16x64_i8 v[34:37], v[134:137], v[166:169], v[34:37]
	s_setprio 0
	s_barrier
; #define PG8_STAGE(bufoff, gbase, voff) do { _Pragma("unroll") for (int _i = 0; _i < 2; ++_i) \
;         __builtin_amdgcn_global_load_lds((const unsigned*)((const char*)(gbase) + (voff)[_i]), (PG8_LAS unsigned*)(lds + (bufoff) + ldsw + _i * 8192), 16, 0, 0); } while (0)
; #define PG8_LDA(dst, b, h) do { _Pragma("unroll") for (int m = 0; m < 4; ++m) _Pragma("unroll") for (int k = 0; k < 2; ++k) dst[m][k] = *(const PG8_LAS bf16x8*)(lds + PG8_SA(b, h) + aoff + m * 2048 + k * 1024); } while (0)
; #define PG8_LDB(dst, b, h) do { _Pragma("unroll") for (int n = 0; n < 2; ++n) _Pragma("unroll") for (int k = 0; k < 2; ++k) dst[n][k] = *(const PG8_LAS bf16x8*)(lds + PG8_SB(b, h) + boff + n * 2048 + k * 1024); } while (0)
; #define PG8_MMA(ai, bj, At, Bt) do { __builtin_amdgcn_s_setprio(1); _Pragma("unroll") for (int m = 0; m < 4; ++m) _Pragma("unroll") for (int n = 0; n < 2; ++n) _Pragma("unroll") for (int k = 0; k < 2; ++k) \
;         acc[ai][bj][m][n] = mma16<Epi::I8>(Bt[n][k], At[m][k], acc[ai][bj][m][n]); __builtin_amdgcn_s_setprio(0); } while (0)
; #define PG8_WAIT_V(n) asm volatile("s_waitcnt vmcnt(" #n ")" ::: "memory")
; #define PG8_WAIT_L(n) asm volatile("s_waitcnt lgkmcnt(" #n ")" ::: "memory")
; #define PG8_BAR __builtin_amdgcn_s_barrier()
; #define PG8_SCHED __builtin_amdgcn_sched_barrier(0)
; template <class Epi, class Sched, bool ALIGN_EPI = false, bool SP2 = false>
; __device__ __forceinline__ void gemm_phase(PG8_LAS unsigned char* lds, const Gemm g, const Sched& S, const Epi& E) {
;     ...
;             PG8_LDB(B0, 1, 0); PG8_LDB(B1, 1, 1); PG8_SCHED; PG8_LDA(At, 1, 0); PG8_STAGE(PG8_SA(0, 1), a2 + hstep, voffA);
;             PG8_WAIT_V(8); PG8_WAIT_L(0); PG8_BAR; PG8_MMA(0, 0, At, B0); PG8_MMA(0, 1, At, B1); PG8_BAR; PG8_SCHED;
;             PG8_LDA(At, 1, 1); PG8_STAGE(PG8_SB(1, 0), b3, voffB); PG8_STAGE(PG8_SB(1, 1), b3 + hstep, voffB); PG8_STAGE(PG8_SA(1, 0), a3, voffA);
;             PG8_WAIT_V(8); PG8_WAIT_L(0); PG8_BAR; PG8_MMA(1, 0, At, B0); PG8_MMA(1, 1, At, B1); PG8_BAR; PG8_SCHED;
	s_add_i32 s4, 0, 0x18000
	v_add_u32_e32 v126, s4, v242
	s_add_i32 s5, 0, 0x1c000
	ds_read_b128 v[50:53], v126
	ds_read_b128 v[66:69], v126 offset:1024
	ds_read_b128 v[114:117], v126 offset:2048
	ds_read_b128 v[130:133], v126 offset:3072
	v_add_u32_e32 v126, s5, v242
	ds_read_b128 v[134:137], v126
	ds_read_b128 v[154:157], v126 offset:1024
	ds_read_b128 v[158:161], v126 offset:2048
	ds_read_b128 v[162:165], v126 offset:3072
	s_add_u32 s0, s12, 0x40000
	s_addc_u32 s1, s13, 0
	s_mov_b32 m0, s80
	ds_read_b128 v[126:129], v243 offset:32768
	ds_read_b128 v[166:169], v243 offset:33792
	ds_read_b128 v[170:173], v243 offset:34816
	ds_read_b128 v[174:177], v243 offset:35840
	ds_read_b128 v[178:181], v243 offset:36864
	ds_read_b128 v[182:185], v243 offset:37888
	ds_read_b128 v[186:189], v243 offset:38912
	ds_read_b128 v[190:193], v243 offset:39936
	global_load_lds_dwordx4 v210, s[0:1]
	s_mov_b32 m0, s81
	s_nop 0
	global_load_lds_dwordx4 v212, s[0:1]
	s_waitcnt vmcnt(8)
	s_waitcnt lgkmcnt(0)
	s_barrier
	s_setprio 1
	s_waitcnt lgkmcnt(0)
	v_mfma_i32_16x16x64_i8 v[150:153], v[50:53], v[126:129], v[150:153]
	v_mfma_i32_16x16x64_i8 v[150:153], v[66:69], v[166:169], v[150:153]
	v_mfma_i32_16x16x64_i8 v[146:149], v[114:117], v[126:129], v[146:149]
	v_mfma_i32_16x16x64_i8 v[146:149], v[130:133], v[166:169], v[146:149]
	v_mfma_i32_16x16x64_i8 v[118:121], v[50:53], v[170:173], v[118:121]
	v_mfma_i32_16x16x64_i8 v[118:121], v[66:69], v[174:177], v[118:121]
	v_mfma_i32_16x16x64_i8 v[110:113], v[114:117], v[170:173], v[110:113]
	v_mfma_i32_16x16x64_i8 v[110:113], v[130:133], v[174:177], v[110:113]
	v_mfma_i32_16x16x64_i8 v[54:57], v[50:53], v[178:181], v[54:57]
	v_mfma_i32_16x16x64_i8 v[54:57], v[66:69], v[182:185], v[54:57]
	v_mfma_i32_16x16x64_i8 v[30:33], v[114:117], v[178:181], v[30:33]
	v_mfma_i32_16x16x64_i8 v[30:33], v[130:133], v[182:185], v[30:33]
	v_mfma_i32_16x16x64_i8 v[94:97], v[50:53], v[186:189], v[94:97]
	v_mfma_i32_16x16x64_i8 v[94:97], v[66:69], v[190:193], v[94:97]
	v_mfma_i32_16x16x64_i8 v[58:61], v[114:117], v[186:189], v[58:61]
	v_mfma_i32_16x16x64_i8 v[58:61], v[130:133], v[190:193], v[58:61]
	s_setprio 0
	s_setprio 1
	v_mfma_i32_16x16x64_i8 v[142:145], v[134:137], v[126:129], v[142:145]
	v_mfma_i32_16x16x64_i8 v[142:145], v[154:157], v[166:169], v[142:145]
	v_mfma_i32_16x16x64_i8 v[126:129], v[158:161], v[126:129], v[138:141]
	v_mfma_i32_16x16x64_i8 v[138:141], v[162:165], v[166:169], v[126:129]
	v_mfma_i32_16x16x64_i8 v[102:105], v[134:137], v[170:173], v[102:105]
	v_mfma_i32_16x16x64_i8 v[102:105], v[154:157], v[174:177], v[102:105]
	v_mfma_i32_16x16x64_i8 v[98:101], v[158:161], v[170:173], v[98:101]
	v_mfma_i32_16x16x64_i8 v[98:101], v[162:165], v[174:177], v[98:101]
	v_mfma_i32_16x16x64_i8 v[42:45], v[134:137], v[178:181], v[42:45]
	v_mfma_i32_16x16x64_i8 v[42:45], v[154:157], v[182:185], v[42:45]
	v_mfma_i32_16x16x64_i8 v[26:29], v[158:161], v[178:181], v[26:29]
	v_mfma_i32_16x16x64_i8 v[26:29], v[162:165], v[182:185], v[26:29]
	v_mfma_i32_16x16x64_i8 v[78:81], v[134:137], v[186:189], v[78:81]
	v_mfma_i32_16x16x64_i8 v[78:81], v[154:157], v[190:193], v[78:81]
	v_mfma_i32_16x16x64_i8 v[62:65], v[158:161], v[186:189], v[62:65]
	v_mfma_i32_16x16x64_i8 v[62:65], v[162:165], v[190:193], v[62:65]
	s_setprio 0
	s_barrier
	s_add_i32 s0, s4, s69
	v_lshl_add_u64 v[126:127], v[198:199], 0, s[92:93]
	s_mov_b32 m0, s0
	ds_read_b128 v[166:169], v243 offset:49152
	ds_read_b128 v[170:173], v243 offset:50176
	ds_read_b128 v[174:177], v243 offset:51200
	ds_read_b128 v[178:181], v243 offset:52224
	ds_read_b128 v[182:185], v243 offset:53248
	ds_read_b128 v[186:189], v243 offset:54272
	ds_read_b128 v[190:193], v243 offset:55296
	ds_read_b128 v[194:197], v243 offset:56320
	global_load_lds_dwordx4 v[126:127], off
	s_add_i32 m0, s0, 0x2000
	s_add_u32 s0, s6, 0x40080
	v_lshl_add_u64 v[126:127], v[200:201], 0, s[92:93]
	s_addc_u32 s1, s7, 0
	s_add_i32 s4, s5, s69
	global_load_lds_dwordx4 v[126:127], off
	s_mov_b32 m0, s4
	s_nop 0
	global_load_lds_dwordx4 v0, s[0:1]
	s_add_i32 m0, s4, 0x2000
	s_nop 0
	global_load_lds_dwordx4 v214, s[0:1]
	v_lshl_add_u64 v[126:127], v[206:207], 0, s[92:93]
	s_mov_b32 m0, s84
	s_nop 0
	global_load_lds_dwordx4 v[126:127], off
	v_lshl_add_u64 v[126:127], v[220:221], 0, s[92:93]
	s_mov_b32 m0, s85
	s_nop 0
	global_load_lds_dwordx4 v[126:127], off
	s_waitcnt vmcnt(8)
	s_waitcnt lgkmcnt(0)
	s_barrier
	s_setprio 1
	s_waitcnt lgkmcnt(0)
	v_mfma_i32_16x16x64_i8 v[18:21], v[50:53], v[190:193], v[18:21]
	v_mfma_i32_16x16x64_i8 v[126:129], v[66:69], v[194:197], v[18:21]
	v_mfma_i32_16x16x64_i8 v[106:109], v[50:53], v[166:169], v[106:109]
	v_mfma_i32_16x16x64_i8 v[106:109], v[66:69], v[170:173], v[106:109]
	v_mfma_i32_16x16x64_i8 v[46:49], v[114:117], v[166:169], v[46:49]
	v_mfma_i32_16x16x64_i8 v[46:49], v[130:133], v[170:173], v[46:49]
	v_mfma_i32_16x16x64_i8 v[14:17], v[50:53], v[174:177], v[14:17]
	v_mfma_i32_16x16x64_i8 v[14:17], v[66:69], v[178:181], v[14:17]
	v_mfma_i32_16x16x64_i8 v[6:9], v[114:117], v[174:177], v[6:9]
	v_mfma_i32_16x16x64_i8 v[6:9], v[130:133], v[178:181], v[6:9]
	v_mfma_i32_16x16x64_i8 v[90:93], v[50:53], v[182:185], v[90:93]
	v_mfma_i32_16x16x64_i8 v[90:93], v[66:69], v[186:189], v[90:93]
	v_mfma_i32_16x16x64_i8 v[86:89], v[114:117], v[182:185], v[86:89]
	v_mfma_i32_16x16x64_i8 v[86:89], v[130:133], v[186:189], v[86:89]
	v_mfma_i32_16x16x64_i8 v[18:21], v[114:117], v[190:193], v[22:25]
	v_mfma_i32_16x16x64_i8 v[66:69], v[130:133], v[194:197], v[18:21]
	s_setprio 0
	s_setprio 1
	v_mfma_i32_16x16x64_i8 v[18:21], v[134:137], v[166:169], v[34:37]
	v_mfma_i32_16x16x64_i8 v[114:117], v[154:157], v[170:173], v[18:21]
	v_mfma_i32_16x16x64_i8 v[18:21], v[158:161], v[166:169], v[38:41]
	v_mfma_i32_16x16x64_i8 v[50:53], v[162:165], v[170:173], v[18:21]
	v_mfma_i32_16x16x64_i8 v[18:21], v[134:137], v[182:185], v[82:85]
	v_mfma_i32_16x16x64_i8 v[82:85], v[154:157], v[186:189], v[18:21]
	v_mfma_i32_16x16x64_i8 v[18:21], v[158:161], v[182:185], v[74:77]
	v_mfma_i32_16x16x64_i8 v[74:77], v[162:165], v[186:189], v[18:21]
	v_mfma_i32_16x16x64_i8 v[18:21], v[134:137], v[190:193], v[122:125]
	v_mfma_i32_16x16x64_i8 v[122:125], v[154:157], v[194:197], v[18:21]
	v_mfma_i32_16x16x64_i8 v[10:13], v[134:137], v[174:177], v[10:13]
	v_mfma_i32_16x16x64_i8 v[10:13], v[154:157], v[178:181], v[10:13]
	v_mfma_i32_16x16x64_i8 v[2:5], v[158:161], v[174:177], v[2:5]
	v_mfma_i32_16x16x64_i8 v[2:5], v[162:165], v[178:181], v[2:5]
	v_mfma_i32_16x16x64_i8 v[18:21], v[158:161], v[190:193], v[70:73]
	v_mfma_i32_16x16x64_i8 v[70:73], v[162:165], v[194:197], v[18:21]
	s_setprio 0
	s_barrier
	s_add_i32 vcc_lo, vcc_lo, 2
	s_add_u32 s96, s96, 0x100
	s_addc_u32 s97, s97, 0
	s_cmp_gt_u32 vcc_lo, 13
	s_mov_b64 s[0:1], s[8:9]
	s_cbranch_scc0 .LBB0_80

; #define PG8_STAGE(bufoff, gbase, voff) do { _Pragma("unroll") for (int _i = 0; _i < 2; ++_i) \
;         __builtin_amdgcn_global_load_lds((const unsigned*)((const char*)(gbase) + (voff)[_i]), (PG8_LAS unsigned*)(lds + (bufoff) + ldsw + _i * 8192), 16, 0, 0); } while (0)
; #define PG8_LDA(dst, b, h) do { _Pragma("unroll") for (int m = 0; m < 4; ++m) _Pragma("unroll") for (int k = 0; k < 2; ++k) dst[m][k] = *(const PG8_LAS bf16x8*)(lds + PG8_SA(b, h) + aoff + m * 2048 + k * 1024); } while (0)
; #define PG8_LDB(dst, b, h) do { _Pragma("unroll") for (int n = 0; n < 2; ++n) _Pragma("unroll") for (int k = 0; k < 2; ++k) dst[n][k] = *(const PG8_LAS bf16x8*)(lds + PG8_SB(b, h) + boff + n * 2048 + k * 1024); } while (0)
; #define PG8_MMA(ai, bj, At, Bt) do { __builtin_amdgcn_s_setprio(1); _Pragma("unroll") for (int m = 0; m < 4; ++m) _Pragma("unroll") for (int n = 0; n < 2; ++n) _Pragma("unroll") for (int k = 0; k < 2; ++k) \
;         acc[ai][bj][m][n] = mma16<Epi::I8>(Bt[n][k], At[m][k], acc[ai][bj][m][n]); __builtin_amdgcn_s_setprio(0); } while (0)
; #define PG8_WAIT_V(n) asm volatile("s_waitcnt vmcnt(" #n ")" ::: "memory")
; #define PG8_WAIT_L(n) asm volatile("s_waitcnt lgkmcnt(" #n ")" ::: "memory")
; #define PG8_BAR __builtin_amdgcn_s_barrier()
; #define PG8_SCHED __builtin_amdgcn_sched_barrier(0)
; template <class Epi, class Sched, bool ALIGN_EPI = false, bool SP2 = false>
; __device__ __forceinline__ void gemm_phase(PG8_LAS unsigned char* lds, const Gemm g, const Sched& S, const Epi& E) {
;     ...
;             PG8_LDB(B0, 0, 0); PG8_LDB(B1, 0, 1); PG8_SCHED; PG8_LDA(At, 0, 0); PG8_STAGE(PG8_SA(1, 1), a1 + hstep, voffA);
;             PG8_WAIT_V(8); PG8_WAIT_L(0); PG8_BAR; PG8_MMA(0, 0, At, B0); PG8_MMA(0, 1, At, B1); PG8_BAR; PG8_SCHED;
;             PG8_LDA(At, 0, 1); PG8_STAGE(PG8_SB(0, 0), b2, voffB); PG8_STAGE(PG8_SB(0, 1), b2 + hstep, voffB); PG8_STAGE(PG8_SA(0, 0), a2, voffA);
.Lpeel175:
	s_add_i32 vcc_lo, s8, 2
	s_add_u32 s4, s6, 0x80
	s_addc_u32 s5, s7, 0
	s_add_i32 vcc_hi, 0, 0x10000
	s_cmp_eq_u32 s13, s8
	s_cselect_b32 s9, s1, s5
	s_cselect_b32 s8, s0, s4
	s_cselect_b32 s5, s97, s85
	s_cselect_b32 s4, s96, s67
	s_add_i32 s84, 0, 0x14000
	v_add_u32_e32 v122, vcc_hi, v248
	v_add_u32_e32 v154, s84, v248
	ds_read_b128 v[98:101], v122
	ds_read_b128 v[102:105], v122 offset:1024
	ds_read_b128 v[114:117], v122 offset:2048
	ds_read_b128 v[122:125], v122 offset:3072
	ds_read_b128 v[130:133], v154
	ds_read_b128 v[138:141], v154 offset:1024
	ds_read_b128 v[146:149], v154 offset:2048
	ds_read_b128 v[154:157], v154 offset:3072
	v_lshl_add_u64 v[206:207], s[6:7], 0, v[200:201]
	s_add_i32 m0, s81, 0xc000
	ds_read_b128 v[162:165], v249
	ds_read_b128 v[166:169], v249 offset:1024
	ds_read_b128 v[170:173], v249 offset:2048
	ds_read_b128 v[174:177], v249 offset:3072
	ds_read_b128 v[178:181], v249 offset:4096
	ds_read_b128 v[182:185], v249 offset:5120
	ds_read_b128 v[186:189], v249 offset:6144
	ds_read_b128 v[190:193], v249 offset:7168
	global_load_lds_dwordx4 v[206:207], off
	v_lshl_add_u64 v[206:207], s[6:7], 0, v[210:211]
	s_add_i32 m0, s81, 0xe000
	s_nop 0
	global_load_lds_dwordx4 v[206:207], off
	s_waitcnt vmcnt(8)
	s_waitcnt lgkmcnt(0)
	s_barrier
	s_setprio 1
	s_waitcnt lgkmcnt(0)
	v_mfma_f32_16x16x32_bf16 v[158:161], v[98:101], v[162:165], 0
	v_mfma_f32_16x16x32_bf16 v[158:161], v[102:105], v[166:169], v[158:161]
	v_mfma_f32_16x16x32_bf16 v[150:153], v[114:117], v[162:165], 0
	v_mfma_f32_16x16x32_bf16 v[150:153], v[122:125], v[166:169], v[150:153]
	v_mfma_f32_16x16x32_bf16 v[126:129], v[98:101], v[170:173], 0
	v_mfma_f32_16x16x32_bf16 v[126:129], v[102:105], v[174:177], v[126:129]
	v_mfma_f32_16x16x32_bf16 v[118:121], v[114:117], v[170:173], 0
	v_mfma_f32_16x16x32_bf16 v[118:121], v[122:125], v[174:177], v[118:121]
	v_mfma_f32_16x16x32_bf16 v[94:97], v[98:101], v[178:181], 0
	v_mfma_f32_16x16x32_bf16 v[94:97], v[102:105], v[182:185], v[94:97]
	v_mfma_f32_16x16x32_bf16 v[90:93], v[114:117], v[178:181], 0
	v_mfma_f32_16x16x32_bf16 v[90:93], v[122:125], v[182:185], v[90:93]
	v_mfma_f32_16x16x32_bf16 v[78:81], v[98:101], v[186:189], 0
	v_mfma_f32_16x16x32_bf16 v[78:81], v[102:105], v[190:193], v[78:81]
	v_mfma_f32_16x16x32_bf16 v[74:77], v[114:117], v[186:189], 0
	v_mfma_f32_16x16x32_bf16 v[74:77], v[122:125], v[190:193], v[74:77]
	s_setprio 0
	s_setprio 1
	v_mfma_f32_16x16x32_bf16 v[142:145], v[130:133], v[162:165], 0
	v_mfma_f32_16x16x32_bf16 v[142:145], v[138:141], v[166:169], v[142:145]
	v_mfma_f32_16x16x32_bf16 v[134:137], v[146:149], v[162:165], 0
	v_mfma_f32_16x16x32_bf16 v[134:137], v[154:157], v[166:169], v[134:137]
	v_mfma_f32_16x16x32_bf16 v[110:113], v[130:133], v[170:173], 0
	v_mfma_f32_16x16x32_bf16 v[110:113], v[138:141], v[174:177], v[110:113]
	v_mfma_f32_16x16x32_bf16 v[106:109], v[146:149], v[170:173], 0
	v_mfma_f32_16x16x32_bf16 v[106:109], v[154:157], v[174:177], v[106:109]
	v_mfma_f32_16x16x32_bf16 v[86:89], v[130:133], v[178:181], 0
	v_mfma_f32_16x16x32_bf16 v[86:89], v[138:141], v[182:185], v[86:89]
	v_mfma_f32_16x16x32_bf16 v[82:85], v[146:149], v[178:181], 0
	v_mfma_f32_16x16x32_bf16 v[82:85], v[154:157], v[182:185], v[82:85]
	v_mfma_f32_16x16x32_bf16 v[70:73], v[130:133], v[186:189], 0
	v_mfma_f32_16x16x32_bf16 v[70:73], v[138:141], v[190:193], v[70:73]
	v_mfma_f32_16x16x32_bf16 v[66:69], v[146:149], v[186:189], 0
	v_mfma_f32_16x16x32_bf16 v[66:69], v[154:157], v[190:193], v[66:69]
	s_setprio 0
	s_barrier
	s_add_i32 vcc_hi, vcc_hi, s80
	v_lshl_add_u64 v[206:207], s[4:5], 0, v[0:1]
	s_mov_b32 m0, vcc_hi
	ds_read_b128 v[162:165], v249 offset:16384
	ds_read_b128 v[166:169], v249 offset:17408
	ds_read_b128 v[170:173], v249 offset:18432
	ds_read_b128 v[174:177], v249 offset:19456
	ds_read_b128 v[178:181], v249 offset:20480
	ds_read_b128 v[182:185], v249 offset:21504
	ds_read_b128 v[186:189], v249 offset:22528
	ds_read_b128 v[190:193], v249 offset:23552
	global_load_lds_dwordx4 v[206:207], off
	s_add_i32 m0, vcc_hi, 0x2000
	v_lshl_add_u64 v[212:213], s[4:5], 0, v[198:199]
	s_add_u32 s4, s4, s58
	s_addc_u32 s5, s5, 0
	s_add_i32 s84, s84, s80
	global_load_lds_dwordx4 v[212:213], off
	v_lshl_add_u64 v[214:215], s[4:5], 0, v[0:1]
	s_mov_b32 m0, s84
	v_lshl_add_u64 v[216:217], s[4:5], 0, v[198:199]
	global_load_lds_dwordx4 v[214:215], off
	s_add_i32 m0, s84, 0x2000
	v_lshl_add_u64 v[218:219], s[8:9], 0, v[194:195]
	global_load_lds_dwordx4 v[216:217], off
	s_mov_b32 m0, s81
	v_lshl_add_u64 v[220:221], s[8:9], 0, v[196:197]
	global_load_lds_dwordx4 v[218:219], off
	s_mov_b32 m0, s70
	s_nop 0
	global_load_lds_dwordx4 v[220:221], off
	s_waitcnt vmcnt(8)
	s_waitcnt lgkmcnt(0)
	s_barrier
; #define PG8_STAGE(bufoff, gbase, voff) do { _Pragma("unroll") for (int _i = 0; _i < 2; ++_i) \
;         __builtin_amdgcn_global_load_lds((const unsigned*)((const char*)(gbase) + (voff)[_i]), (PG8_LAS unsigned*)(lds + (bufoff) + ldsw + _i * 8192), 16, 0, 0); } while (0)
; #define PG8_LDA(dst, b, h) do { _Pragma("unroll") for (int m = 0; m < 4; ++m) _Pragma("unroll") for (int k = 0; k < 2; ++k) dst[m][k] = *(const PG8_LAS bf16x8*)(lds + PG8_SA(b, h) + aoff + m * 2048 + k * 1024); } while (0)
; #define PG8_LDB(dst, b, h) do { _Pragma("unroll") for (int n = 0; n < 2; ++n) _Pragma("unroll") for (int k = 0; k < 2; ++k) dst[n][k] = *(const PG8_LAS bf16x8*)(lds + PG8_SB(b, h) + boff + n * 2048 + k * 1024); } while (0)
; #define PG8_MMA(ai, bj, At, Bt) do { __builtin_amdgcn_s_setprio(1); _Pragma("unroll") for (int m = 0; m < 4; ++m) _Pragma("unroll") for (int n = 0; n < 2; ++n) _Pragma("unroll") for (int k = 0; k < 2; ++k) \
;         acc[ai][bj][m][n] = mma16<Epi::I8>(Bt[n][k], At[m][k], acc[ai][bj][m][n]); __builtin_amdgcn_s_setprio(0); } while (0)
; #define PG8_WAIT_V(n) asm volatile("s_waitcnt vmcnt(" #n ")" ::: "memory")
; #define PG8_WAIT_L(n) asm volatile("s_waitcnt lgkmcnt(" #n ")" ::: "memory")
; #define PG8_BAR __builtin_amdgcn_s_barrier()
; #define PG8_SCHED __builtin_amdgcn_sched_barrier(0)
; template <class Epi, class Sched, bool ALIGN_EPI = false, bool SP2 = false>
; __device__ __forceinline__ void gemm_phase(PG8_LAS unsigned char* lds, const Gemm g, const Sched& S, const Epi& E) {
;     ...
;             PG8_WAIT_V(8); PG8_WAIT_L(0); PG8_BAR; PG8_MMA(1, 0, At, B0); PG8_MMA(1, 1, At, B1); PG8_BAR; PG8_SCHED;
;             PG8_LDB(B0, 1, 0); PG8_LDB(B1, 1, 1); PG8_SCHED; PG8_LDA(At, 1, 0); PG8_STAGE(PG8_SA(0, 1), a2 + hstep, voffA);
;             PG8_WAIT_V(8); PG8_WAIT_L(0); PG8_BAR; PG8_MMA(0, 0, At, B0); PG8_MMA(0, 1, At, B1); PG8_BAR; PG8_SCHED;
	s_setprio 1
	s_waitcnt lgkmcnt(0)
	v_mfma_f32_16x16x32_bf16 v[62:65], v[98:101], v[162:165], 0
	v_mfma_f32_16x16x32_bf16 v[62:65], v[102:105], v[166:169], v[62:65]
	v_mfma_f32_16x16x32_bf16 v[58:61], v[114:117], v[162:165], 0
	v_mfma_f32_16x16x32_bf16 v[58:61], v[122:125], v[166:169], v[58:61]
	v_mfma_f32_16x16x32_bf16 v[46:49], v[98:101], v[170:173], 0
	v_mfma_f32_16x16x32_bf16 v[46:49], v[102:105], v[174:177], v[46:49]
	v_mfma_f32_16x16x32_bf16 v[42:45], v[114:117], v[170:173], 0
	v_mfma_f32_16x16x32_bf16 v[42:45], v[122:125], v[174:177], v[42:45]
	v_mfma_f32_16x16x32_bf16 v[30:33], v[98:101], v[178:181], 0
	v_mfma_f32_16x16x32_bf16 v[30:33], v[102:105], v[182:185], v[30:33]
	v_mfma_f32_16x16x32_bf16 v[26:29], v[114:117], v[178:181], 0
	v_mfma_f32_16x16x32_bf16 v[26:29], v[122:125], v[182:185], v[26:29]
	v_mfma_f32_16x16x32_bf16 v[14:17], v[98:101], v[186:189], 0
	v_mfma_f32_16x16x32_bf16 v[14:17], v[102:105], v[190:193], v[14:17]
	v_mfma_f32_16x16x32_bf16 v[10:13], v[114:117], v[186:189], 0
	v_mfma_f32_16x16x32_bf16 v[10:13], v[122:125], v[190:193], v[10:13]
	s_setprio 0
	s_setprio 1
	v_mfma_f32_16x16x32_bf16 v[54:57], v[130:133], v[162:165], 0
	v_mfma_f32_16x16x32_bf16 v[54:57], v[138:141], v[166:169], v[54:57]
	v_mfma_f32_16x16x32_bf16 v[50:53], v[146:149], v[162:165], 0
	v_mfma_f32_16x16x32_bf16 v[50:53], v[154:157], v[166:169], v[50:53]
	v_mfma_f32_16x16x32_bf16 v[38:41], v[130:133], v[170:173], 0
	v_mfma_f32_16x16x32_bf16 v[38:41], v[138:141], v[174:177], v[38:41]
	v_mfma_f32_16x16x32_bf16 v[34:37], v[146:149], v[170:173], 0
	v_mfma_f32_16x16x32_bf16 v[34:37], v[154:157], v[174:177], v[34:37]
	v_mfma_f32_16x16x32_bf16 v[22:25], v[130:133], v[178:181], 0
	v_mfma_f32_16x16x32_bf16 v[22:25], v[138:141], v[182:185], v[22:25]
	v_mfma_f32_16x16x32_bf16 v[18:21], v[146:149], v[178:181], 0
	v_mfma_f32_16x16x32_bf16 v[18:21], v[154:157], v[182:185], v[18:21]
	v_mfma_f32_16x16x32_bf16 v[6:9], v[130:133], v[186:189], 0
	v_mfma_f32_16x16x32_bf16 v[6:9], v[138:141], v[190:193], v[6:9]
	v_mfma_f32_16x16x32_bf16 v[2:5], v[146:149], v[186:189], 0
	v_mfma_f32_16x16x32_bf16 v[2:5], v[154:157], v[190:193], v[2:5]
	s_setprio 0
	s_barrier
	s_add_i32 s84, 0, 0x18000
	s_add_i32 vcc_hi, 0, 0x1c000
	v_add_u32_e32 v122, s84, v248
	v_add_u32_e32 v154, vcc_hi, v248
	ds_read_b128 v[98:101], v122
	ds_read_b128 v[102:105], v122 offset:1024
	ds_read_b128 v[114:117], v122 offset:2048
	ds_read_b128 v[122:125], v122 offset:3072
	ds_read_b128 v[130:133], v154
	ds_read_b128 v[138:141], v154 offset:1024
	ds_read_b128 v[146:149], v154 offset:2048
	ds_read_b128 v[154:157], v154 offset:3072
	s_add_u32 s4, s8, s58
	s_addc_u32 s5, s9, 0
	s_mov_b32 m0, s71
	v_lshl_add_u64 v[222:223], s[4:5], 0, v[194:195]
	ds_read_b128 v[162:165], v249 offset:32768
	ds_read_b128 v[166:169], v249 offset:33792
	ds_read_b128 v[170:173], v249 offset:34816
	ds_read_b128 v[174:177], v249 offset:35840
	ds_read_b128 v[178:181], v249 offset:36864
	ds_read_b128 v[182:185], v249 offset:37888
	ds_read_b128 v[186:189], v249 offset:38912
	ds_read_b128 v[190:193], v249 offset:39936
	global_load_lds_dwordx4 v[222:223], off
	v_lshl_add_u64 v[222:223], s[4:5], 0, v[196:197]
	s_mov_b32 m0, s12
	s_nop 0
	global_load_lds_dwordx4 v[222:223], off
	s_waitcnt vmcnt(8)
	s_waitcnt lgkmcnt(0)
	s_barrier
	s_setprio 1
	s_waitcnt lgkmcnt(0)
	v_mfma_f32_16x16x32_bf16 v[158:161], v[98:101], v[162:165], v[158:161]
	v_mfma_f32_16x16x32_bf16 v[158:161], v[102:105], v[166:169], v[158:161]
	v_mfma_f32_16x16x32_bf16 v[150:153], v[114:117], v[162:165], v[150:153]
	v_mfma_f32_16x16x32_bf16 v[150:153], v[122:125], v[166:169], v[150:153]
	v_mfma_f32_16x16x32_bf16 v[126:129], v[98:101], v[170:173], v[126:129]
	v_mfma_f32_16x16x32_bf16 v[126:129], v[102:105], v[174:177], v[126:129]
	v_mfma_f32_16x16x32_bf16 v[118:121], v[114:117], v[170:173], v[118:121]
	v_mfma_f32_16x16x32_bf16 v[118:121], v[122:125], v[174:177], v[118:121]
	v_mfma_f32_16x16x32_bf16 v[94:97], v[98:101], v[178:181], v[94:97]
	v_mfma_f32_16x16x32_bf16 v[94:97], v[102:105], v[182:185], v[94:97]
	v_mfma_f32_16x16x32_bf16 v[90:93], v[114:117], v[178:181], v[90:93]
	v_mfma_f32_16x16x32_bf16 v[90:93], v[122:125], v[182:185], v[90:93]
	v_mfma_f32_16x16x32_bf16 v[78:81], v[98:101], v[186:189], v[78:81]
	v_mfma_f32_16x16x32_bf16 v[78:81], v[102:105], v[190:193], v[78:81]
	v_mfma_f32_16x16x32_bf16 v[74:77], v[114:117], v[186:189], v[74:77]
	v_mfma_f32_16x16x32_bf16 v[74:77], v[122:125], v[190:193], v[74:77]
	s_setprio 0
	s_setprio 1
	v_mfma_f32_16x16x32_bf16 v[142:145], v[130:133], v[162:165], v[142:145]
	v_mfma_f32_16x16x32_bf16 v[142:145], v[138:141], v[166:169], v[142:145]
	v_mfma_f32_16x16x32_bf16 v[134:137], v[146:149], v[162:165], v[134:137]
	v_mfma_f32_16x16x32_bf16 v[134:137], v[154:157], v[166:169], v[134:137]
	v_mfma_f32_16x16x32_bf16 v[110:113], v[130:133], v[170:173], v[110:113]
	v_mfma_f32_16x16x32_bf16 v[110:113], v[138:141], v[174:177], v[110:113]
	v_mfma_f32_16x16x32_bf16 v[106:109], v[146:149], v[170:173], v[106:109]
	v_mfma_f32_16x16x32_bf16 v[106:109], v[154:157], v[174:177], v[106:109]
	v_mfma_f32_16x16x32_bf16 v[86:89], v[130:133], v[178:181], v[86:89]
	v_mfma_f32_16x16x32_bf16 v[86:89], v[138:141], v[182:185], v[86:89]
	v_mfma_f32_16x16x32_bf16 v[82:85], v[146:149], v[178:181], v[82:85]
	v_mfma_f32_16x16x32_bf16 v[82:85], v[154:157], v[182:185], v[82:85]
	v_mfma_f32_16x16x32_bf16 v[70:73], v[130:133], v[186:189], v[70:73]
	v_mfma_f32_16x16x32_bf16 v[70:73], v[138:141], v[190:193], v[70:73]
	v_mfma_f32_16x16x32_bf16 v[66:69], v[146:149], v[186:189], v[66:69]
	v_mfma_f32_16x16x32_bf16 v[66:69], v[154:157], v[190:193], v[66:69]
	s_setprio 0
	s_barrier
; #define PG8_STAGE(bufoff, gbase, voff) do { _Pragma("unroll") for (int _i = 0; _i < 2; ++_i) \
;         __builtin_amdgcn_global_load_lds((const unsigned*)((const char*)(gbase) + (voff)[_i]), (PG8_LAS unsigned*)(lds + (bufoff) + ldsw + _i * 8192), 16, 0, 0); } while (0)
; #define PG8_LDA(dst, b, h) do { _Pragma("unroll") for (int m = 0; m < 4; ++m) _Pragma("unroll") for (int k = 0; k < 2; ++k) dst[m][k] = *(const PG8_LAS bf16x8*)(lds + PG8_SA(b, h) + aoff + m * 2048 + k * 1024); } while (0)
; #define PG8_LDB(dst, b, h) do { _Pragma("unroll") for (int n = 0; n < 2; ++n) _Pragma("unroll") for (int k = 0; k < 2; ++k) dst[n][k] = *(const PG8_LAS bf16x8*)(lds + PG8_SB(b, h) + boff + n * 2048 + k * 1024); } while (0)
; #define PG8_MMA(ai, bj, At, Bt) do { __builtin_amdgcn_s_setprio(1); _Pragma("unroll") for (int m = 0; m < 4; ++m) _Pragma("unroll") for (int n = 0; n < 2; ++n) _Pragma("unroll") for (int k = 0; k < 2; ++k) \
;         acc[ai][bj][m][n] = mma16<Epi::I8>(Bt[n][k], At[m][k], acc[ai][bj][m][n]); __builtin_amdgcn_s_setprio(0); } while (0)
; #define PG8_WAIT_V(n) asm volatile("s_waitcnt vmcnt(" #n ")" ::: "memory")
; template <class Epi, class Sched, bool ALIGN_EPI = false, bool SP2 = false>
; __device__ __forceinline__ void gemm_phase(PG8_LAS unsigned char* lds, const Gemm g, const Sched& S, const Epi& E) {
;     ...
;             PG8_LDB(B0, 0, 0); PG8_LDB(B1, 0, 1); PG8_SCHED; PG8_LDA(At, 0, 0); PG8_STAGE(PG8_SA(1, 1), a1 + hstep, voffA);
;             PG8_WAIT_V(8); PG8_WAIT_L(0); PG8_BAR; PG8_MMA(0, 0, At, B0); PG8_MMA(0, 1, At, B1); PG8_BAR; PG8_SCHED;
;             PG8_LDA(At, 0, 1); PG8_STAGE(PG8_SB(0, 0), b2, voffB); PG8_STAGE(PG8_SB(0, 1), b2 + hstep, voffB); PG8_STAGE(PG8_SA(0, 0), a2, voffA);
;             PG8_WAIT_V(8); PG8_WAIT_L(0); PG8_BAR; PG8_MMA(1, 0, At, B0); PG8_MMA(1, 1, At, B1); PG8_BAR; PG8_SCHED;
;             PG8_LDB(B0, 1, 0); PG8_LDB(B1, 1, 1); PG8_SCHED; PG8_LDA(At, 1, 0); PG8_STAGE(PG8_SA(0, 1), a2 + hstep, voffA);
;             PG8_WAIT_V(8); PG8_WAIT_L(0); PG8_BAR; PG8_MMA(0, 0, At, B0); PG8_MMA(0, 1, At, B1); PG8_BAR; PG8_SCHED;
;             PG8_LDA(At, 1, 1); PG8_STAGE(PG8_SB(1, 0), b3, voffB); PG8_STAGE(PG8_SB(1, 1), b3 + hstep, voffB); PG8_STAGE(PG8_SA(1, 0), a3, voffA);
;             PG8_WAIT_V(8); PG8_WAIT_L(0); PG8_BAR; PG8_MMA(1, 0, At, B0); PG8_MMA(1, 1, At, B1); PG8_BAR; PG8_SCHED;
	s_add_i32 s4, s84, s80
	v_lshl_add_u64 v[206:207], v[206:207], 0, s[92:93]
	s_mov_b32 m0, s4
	ds_read_b128 v[162:165], v249 offset:49152
	ds_read_b128 v[166:169], v249 offset:50176
	ds_read_b128 v[170:173], v249 offset:51200
	ds_read_b128 v[174:177], v249 offset:52224
	ds_read_b128 v[178:181], v249 offset:53248
	ds_read_b128 v[182:185], v249 offset:54272
	ds_read_b128 v[186:189], v249 offset:55296
	ds_read_b128 v[190:193], v249 offset:56320
	global_load_lds_dwordx4 v[206:207], off
	v_lshl_add_u64 v[206:207], v[212:213], 0, s[92:93]
	s_add_i32 m0, s4, 0x2000
	s_add_i32 s4, vcc_hi, s80
	global_load_lds_dwordx4 v[206:207], off
	v_lshl_add_u64 v[206:207], v[214:215], 0, s[92:93]
	s_mov_b32 m0, s4
	s_nop 0
	global_load_lds_dwordx4 v[206:207], off
	v_lshl_add_u64 v[206:207], v[216:217], 0, s[92:93]
	s_add_i32 m0, s4, 0x2000
	s_nop 0
	global_load_lds_dwordx4 v[206:207], off
	v_lshl_add_u64 v[206:207], v[218:219], 0, s[92:93]
	s_mov_b32 m0, s10
	s_nop 0
	global_load_lds_dwordx4 v[206:207], off
	v_lshl_add_u64 v[206:207], v[220:221], 0, s[92:93]
	s_mov_b32 m0, s11
	s_nop 0
	global_load_lds_dwordx4 v[206:207], off
	s_waitcnt vmcnt(8)
	s_waitcnt lgkmcnt(0)
	s_barrier
	s_setprio 1
	s_waitcnt lgkmcnt(0)
	v_mfma_f32_16x16x32_bf16 v[62:65], v[98:101], v[162:165], v[62:65]
	v_mfma_f32_16x16x32_bf16 v[62:65], v[102:105], v[166:169], v[62:65]
	v_mfma_f32_16x16x32_bf16 v[58:61], v[114:117], v[162:165], v[58:61]
	v_mfma_f32_16x16x32_bf16 v[58:61], v[122:125], v[166:169], v[58:61]
	v_mfma_f32_16x16x32_bf16 v[46:49], v[98:101], v[170:173], v[46:49]
	v_mfma_f32_16x16x32_bf16 v[46:49], v[102:105], v[174:177], v[46:49]
	v_mfma_f32_16x16x32_bf16 v[42:45], v[114:117], v[170:173], v[42:45]
	v_mfma_f32_16x16x32_bf16 v[42:45], v[122:125], v[174:177], v[42:45]
	v_mfma_f32_16x16x32_bf16 v[30:33], v[98:101], v[178:181], v[30:33]
	v_mfma_f32_16x16x32_bf16 v[30:33], v[102:105], v[182:185], v[30:33]
	v_mfma_f32_16x16x32_bf16 v[26:29], v[114:117], v[178:181], v[26:29]
	v_mfma_f32_16x16x32_bf16 v[26:29], v[122:125], v[182:185], v[26:29]
	v_mfma_f32_16x16x32_bf16 v[14:17], v[98:101], v[186:189], v[14:17]
	v_mfma_f32_16x16x32_bf16 v[14:17], v[102:105], v[190:193], v[14:17]
	v_mfma_f32_16x16x32_bf16 v[10:13], v[114:117], v[186:189], v[10:13]
	v_mfma_f32_16x16x32_bf16 v[10:13], v[122:125], v[190:193], v[10:13]
	s_setprio 0
	s_setprio 1
	v_mfma_f32_16x16x32_bf16 v[54:57], v[130:133], v[162:165], v[54:57]
	v_mfma_f32_16x16x32_bf16 v[54:57], v[138:141], v[166:169], v[54:57]
	v_mfma_f32_16x16x32_bf16 v[50:53], v[146:149], v[162:165], v[50:53]
	v_mfma_f32_16x16x32_bf16 v[50:53], v[154:157], v[166:169], v[50:53]
	v_mfma_f32_16x16x32_bf16 v[38:41], v[130:133], v[170:173], v[38:41]
	v_mfma_f32_16x16x32_bf16 v[38:41], v[138:141], v[174:177], v[38:41]
	v_mfma_f32_16x16x32_bf16 v[34:37], v[146:149], v[170:173], v[34:37]
	v_mfma_f32_16x16x32_bf16 v[34:37], v[154:157], v[174:177], v[34:37]
	v_mfma_f32_16x16x32_bf16 v[22:25], v[130:133], v[178:181], v[22:25]
	v_mfma_f32_16x16x32_bf16 v[22:25], v[138:141], v[182:185], v[22:25]
	v_mfma_f32_16x16x32_bf16 v[18:21], v[146:149], v[178:181], v[18:21]
	v_mfma_f32_16x16x32_bf16 v[18:21], v[154:157], v[182:185], v[18:21]
	v_mfma_f32_16x16x32_bf16 v[6:9], v[130:133], v[186:189], v[6:9]
	v_mfma_f32_16x16x32_bf16 v[6:9], v[138:141], v[190:193], v[6:9]
	v_mfma_f32_16x16x32_bf16 v[2:5], v[146:149], v[186:189], v[2:5]
	v_mfma_f32_16x16x32_bf16 v[2:5], v[154:157], v[190:193], v[2:5]
	s_setprio 0
	s_barrier
	s_add_u32 s6, s6, 0x100
	s_addc_u32 s7, s7, 0
	s_add_u32 s67, s67, 0x100
	s_addc_u32 s85, s85, 0
	s_cmp_ge_u32 vcc_lo, s69
	s_mov_b32 s8, vcc_lo
	s_cbranch_scc0 .LBB0_175
	s_branch .Lpeelx175
.LBB0_175:
	s_add_i32 vcc_lo, s8, 2
	s_add_u32 s4, s6, 0x80
	s_addc_u32 s5, s7, 0
	s_add_i32 vcc_hi, 0, 0x10000
	s_cmp_eq_u32 s13, s8
	s_cselect_b32 s9, s1, s5
	s_cselect_b32 s8, s0, s4
	s_cselect_b32 s5, s97, s85
	s_cselect_b32 s4, s96, s67
	s_add_i32 s84, 0, 0x14000
	v_add_u32_e32 v122, vcc_hi, v248
	v_add_u32_e32 v154, s84, v248
	ds_read_b128 v[98:101], v122
	ds_read_b128 v[102:105], v122 offset:1024
	ds_read_b128 v[114:117], v122 offset:2048
	ds_read_b128 v[122:125], v122 offset:3072
	ds_read_b128 v[130:133], v154
	ds_read_b128 v[138:141], v154 offset:1024
	ds_read_b128 v[146:149], v154 offset:2048
	ds_read_b128 v[154:157], v154 offset:3072
	v_lshl_add_u64 v[206:207], s[6:7], 0, v[200:201]
	s_add_i32 m0, s81, 0xc000
	ds_read_b128 v[162:165], v249
	ds_read_b128 v[166:169], v249 offset:1024
	ds_read_b128 v[170:173], v249 offset:2048
	ds_read_b128 v[174:177], v249 offset:3072
	ds_read_b128 v[178:181], v249 offset:4096
	ds_read_b128 v[182:185], v249 offset:5120
	ds_read_b128 v[186:189], v249 offset:6144
	ds_read_b128 v[190:193], v249 offset:7168
	global_load_lds_dwordx4 v[206:207], off
	v_lshl_add_u64 v[206:207], s[6:7], 0, v[210:211]
	s_add_i32 m0, s81, 0xe000
	s_nop 0
	global_load_lds_dwordx4 v[206:207], off
	s_waitcnt vmcnt(8)
	s_waitcnt lgkmcnt(0)
	s_barrier
; #define PG8_STAGE(bufoff, gbase, voff) do { _Pragma("unroll") for (int _i = 0; _i < 2; ++_i) \
;         __builtin_amdgcn_global_load_lds((const unsigned*)((const char*)(gbase) + (voff)[_i]), (PG8_LAS unsigned*)(lds + (bufoff) + ldsw + _i * 8192), 16, 0, 0); } while (0)
; #define PG8_LDA(dst, b, h) do { _Pragma("unroll") for (int m = 0; m < 4; ++m) _Pragma("unroll") for (int k = 0; k < 2; ++k) dst[m][k] = *(const PG8_LAS bf16x8*)(lds + PG8_SA(b, h) + aoff + m * 2048 + k * 1024); } while (0)
; #define PG8_MMA(ai, bj, At, Bt) do { __builtin_amdgcn_s_setprio(1); _Pragma("unroll") for (int m = 0; m < 4; ++m) _Pragma("unroll") for (int n = 0; n < 2; ++n) _Pragma("unroll") for (int k = 0; k < 2; ++k) \
;         acc[ai][bj][m][n] = mma16<Epi::I8>(Bt[n][k], At[m][k], acc[ai][bj][m][n]); __builtin_amdgcn_s_setprio(0); } while (0)
; #define PG8_WAIT_V(n) asm volatile("s_waitcnt vmcnt(" #n ")" ::: "memory")
; #define PG8_WAIT_L(n) asm volatile("s_waitcnt lgkmcnt(" #n ")" ::: "memory")
; #define PG8_BAR __builtin_amdgcn_s_barrier()
; #define PG8_SCHED __builtin_amdgcn_sched_barrier(0)
; template <class Epi, class Sched, bool ALIGN_EPI = false, bool SP2 = false>
; __device__ __forceinline__ void gemm_phase(PG8_LAS unsigned char* lds, const Gemm g, const Sched& S, const Epi& E) {
;     ...
;             PG8_WAIT_V(8); PG8_WAIT_L(0); PG8_BAR; PG8_MMA(0, 0, At, B0); PG8_MMA(0, 1, At, B1); PG8_BAR; PG8_SCHED;
;             PG8_LDA(At, 0, 1); PG8_STAGE(PG8_SB(0, 0), b2, voffB); PG8_STAGE(PG8_SB(0, 1), b2 + hstep, voffB); PG8_STAGE(PG8_SA(0, 0), a2, voffA);
;             PG8_WAIT_V(8); PG8_WAIT_L(0); PG8_BAR; PG8_MMA(1, 0, At, B0); PG8_MMA(1, 1, At, B1); PG8_BAR; PG8_SCHED;
	s_setprio 1
	s_waitcnt lgkmcnt(0)
	v_mfma_f32_16x16x32_bf16 v[158:161], v[98:101], v[162:165], v[158:161]
	v_mfma_f32_16x16x32_bf16 v[158:161], v[102:105], v[166:169], v[158:161]
	v_mfma_f32_16x16x32_bf16 v[150:153], v[114:117], v[162:165], v[150:153]
	v_mfma_f32_16x16x32_bf16 v[150:153], v[122:125], v[166:169], v[150:153]
	v_mfma_f32_16x16x32_bf16 v[126:129], v[98:101], v[170:173], v[126:129]
	v_mfma_f32_16x16x32_bf16 v[126:129], v[102:105], v[174:177], v[126:129]
	v_mfma_f32_16x16x32_bf16 v[118:121], v[114:117], v[170:173], v[118:121]
	v_mfma_f32_16x16x32_bf16 v[118:121], v[122:125], v[174:177], v[118:121]
	v_mfma_f32_16x16x32_bf16 v[94:97], v[98:101], v[178:181], v[94:97]
	v_mfma_f32_16x16x32_bf16 v[94:97], v[102:105], v[182:185], v[94:97]
	v_mfma_f32_16x16x32_bf16 v[90:93], v[114:117], v[178:181], v[90:93]
	v_mfma_f32_16x16x32_bf16 v[90:93], v[122:125], v[182:185], v[90:93]
	v_mfma_f32_16x16x32_bf16 v[78:81], v[98:101], v[186:189], v[78:81]
	v_mfma_f32_16x16x32_bf16 v[78:81], v[102:105], v[190:193], v[78:81]
	v_mfma_f32_16x16x32_bf16 v[74:77], v[114:117], v[186:189], v[74:77]
	v_mfma_f32_16x16x32_bf16 v[74:77], v[122:125], v[190:193], v[74:77]
	s_setprio 0
	s_setprio 1
	v_mfma_f32_16x16x32_bf16 v[142:145], v[130:133], v[162:165], v[142:145]
	v_mfma_f32_16x16x32_bf16 v[142:145], v[138:141], v[166:169], v[142:145]
	v_mfma_f32_16x16x32_bf16 v[134:137], v[146:149], v[162:165], v[134:137]
	v_mfma_f32_16x16x32_bf16 v[134:137], v[154:157], v[166:169], v[134:137]
	v_mfma_f32_16x16x32_bf16 v[110:113], v[130:133], v[170:173], v[110:113]
	v_mfma_f32_16x16x32_bf16 v[110:113], v[138:141], v[174:177], v[110:113]
	v_mfma_f32_16x16x32_bf16 v[106:109], v[146:149], v[170:173], v[106:109]
	v_mfma_f32_16x16x32_bf16 v[106:109], v[154:157], v[174:177], v[106:109]
	v_mfma_f32_16x16x32_bf16 v[86:89], v[130:133], v[178:181], v[86:89]
	v_mfma_f32_16x16x32_bf16 v[86:89], v[138:141], v[182:185], v[86:89]
	v_mfma_f32_16x16x32_bf16 v[82:85], v[146:149], v[178:181], v[82:85]
	v_mfma_f32_16x16x32_bf16 v[82:85], v[154:157], v[182:185], v[82:85]
	v_mfma_f32_16x16x32_bf16 v[70:73], v[130:133], v[186:189], v[70:73]
	v_mfma_f32_16x16x32_bf16 v[70:73], v[138:141], v[190:193], v[70:73]
	v_mfma_f32_16x16x32_bf16 v[66:69], v[146:149], v[186:189], v[66:69]
	v_mfma_f32_16x16x32_bf16 v[66:69], v[154:157], v[190:193], v[66:69]
	s_setprio 0
	s_barrier
	s_add_i32 vcc_hi, vcc_hi, s80
	v_lshl_add_u64 v[206:207], s[4:5], 0, v[0:1]
	s_mov_b32 m0, vcc_hi
	ds_read_b128 v[162:165], v249 offset:16384
	ds_read_b128 v[166:169], v249 offset:17408
	ds_read_b128 v[170:173], v249 offset:18432
	ds_read_b128 v[174:177], v249 offset:19456
	ds_read_b128 v[178:181], v249 offset:20480
	ds_read_b128 v[182:185], v249 offset:21504
	ds_read_b128 v[186:189], v249 offset:22528
	ds_read_b128 v[190:193], v249 offset:23552
	global_load_lds_dwordx4 v[206:207], off
	s_add_i32 m0, vcc_hi, 0x2000
	v_lshl_add_u64 v[212:213], s[4:5], 0, v[198:199]
	s_add_u32 s4, s4, s58
	s_addc_u32 s5, s5, 0
	s_add_i32 s84, s84, s80
	global_load_lds_dwordx4 v[212:213], off
	v_lshl_add_u64 v[214:215], s[4:5], 0, v[0:1]
	s_mov_b32 m0, s84
	v_lshl_add_u64 v[216:217], s[4:5], 0, v[198:199]
	global_load_lds_dwordx4 v[214:215], off
	s_add_i32 m0, s84, 0x2000
	v_lshl_add_u64 v[218:219], s[8:9], 0, v[194:195]
	global_load_lds_dwordx4 v[216:217], off
	s_mov_b32 m0, s81
	v_lshl_add_u64 v[220:221], s[8:9], 0, v[196:197]
	global_load_lds_dwordx4 v[218:219], off
	s_mov_b32 m0, s70
	s_nop 0
	global_load_lds_dwordx4 v[220:221], off
	s_waitcnt vmcnt(8)
	s_waitcnt lgkmcnt(0)
	s_barrier
	s_setprio 1
	s_waitcnt lgkmcnt(0)
	v_mfma_f32_16x16x32_bf16 v[62:65], v[98:101], v[162:165], v[62:65]
	v_mfma_f32_16x16x32_bf16 v[62:65], v[102:105], v[166:169], v[62:65]
	v_mfma_f32_16x16x32_bf16 v[58:61], v[114:117], v[162:165], v[58:61]
	v_mfma_f32_16x16x32_bf16 v[58:61], v[122:125], v[166:169], v[58:61]
	v_mfma_f32_16x16x32_bf16 v[46:49], v[98:101], v[170:173], v[46:49]
	v_mfma_f32_16x16x32_bf16 v[46:49], v[102:105], v[174:177], v[46:49]
	v_mfma_f32_16x16x32_bf16 v[42:45], v[114:117], v[170:173], v[42:45]
	v_mfma_f32_16x16x32_bf16 v[42:45], v[122:125], v[174:177], v[42:45]
	v_mfma_f32_16x16x32_bf16 v[30:33], v[98:101], v[178:181], v[30:33]
	v_mfma_f32_16x16x32_bf16 v[30:33], v[102:105], v[182:185], v[30:33]
	v_mfma_f32_16x16x32_bf16 v[26:29], v[114:117], v[178:181], v[26:29]
	v_mfma_f32_16x16x32_bf16 v[26:29], v[122:125], v[182:185], v[26:29]
	v_mfma_f32_16x16x32_bf16 v[14:17], v[98:101], v[186:189], v[14:17]
	v_mfma_f32_16x16x32_bf16 v[14:17], v[102:105], v[190:193], v[14:17]
	v_mfma_f32_16x16x32_bf16 v[10:13], v[114:117], v[186:189], v[10:13]
	v_mfma_f32_16x16x32_bf16 v[10:13], v[122:125], v[190:193], v[10:13]
	s_setprio 0
	s_setprio 1
	v_mfma_f32_16x16x32_bf16 v[54:57], v[130:133], v[162:165], v[54:57]
	v_mfma_f32_16x16x32_bf16 v[54:57], v[138:141], v[166:169], v[54:57]
	v_mfma_f32_16x16x32_bf16 v[50:53], v[146:149], v[162:165], v[50:53]
	v_mfma_f32_16x16x32_bf16 v[50:53], v[154:157], v[166:169], v[50:53]
	v_mfma_f32_16x16x32_bf16 v[38:41], v[130:133], v[170:173], v[38:41]
	v_mfma_f32_16x16x32_bf16 v[38:41], v[138:141], v[174:177], v[38:41]
	v_mfma_f32_16x16x32_bf16 v[34:37], v[146:149], v[170:173], v[34:37]
	v_mfma_f32_16x16x32_bf16 v[34:37], v[154:157], v[174:177], v[34:37]
	v_mfma_f32_16x16x32_bf16 v[22:25], v[130:133], v[178:181], v[22:25]
	v_mfma_f32_16x16x32_bf16 v[22:25], v[138:141], v[182:185], v[22:25]
	v_mfma_f32_16x16x32_bf16 v[18:21], v[146:149], v[178:181], v[18:21]
	v_mfma_f32_16x16x32_bf16 v[18:21], v[154:157], v[182:185], v[18:21]
	v_mfma_f32_16x16x32_bf16 v[6:9], v[130:133], v[186:189], v[6:9]
	v_mfma_f32_16x16x32_bf16 v[6:9], v[138:141], v[190:193], v[6:9]
	v_mfma_f32_16x16x32_bf16 v[2:5], v[146:149], v[186:189], v[2:5]
	v_mfma_f32_16x16x32_bf16 v[2:5], v[154:157], v[190:193], v[2:5]
	s_setprio 0
	s_barrier
; #define PG8_STAGE(bufoff, gbase, voff) do { _Pragma("unroll") for (int _i = 0; _i < 2; ++_i) \
;         __builtin_amdgcn_global_load_lds((const unsigned*)((const char*)(gbase) + (voff)[_i]), (PG8_LAS unsigned*)(lds + (bufoff) + ldsw + _i * 8192), 16, 0, 0); } while (0)
; #define PG8_LDA(dst, b, h) do { _Pragma("unroll") for (int m = 0; m < 4; ++m) _Pragma("unroll") for (int k = 0; k < 2; ++k) dst[m][k] = *(const PG8_LAS bf16x8*)(lds + PG8_SA(b, h) + aoff + m * 2048 + k * 1024); } while (0)
; #define PG8_LDB(dst, b, h) do { _Pragma("unroll") for (int n = 0; n < 2; ++n) _Pragma("unroll") for (int k = 0; k < 2; ++k) dst[n][k] = *(const PG8_LAS bf16x8*)(lds + PG8_SB(b, h) + boff + n * 2048 + k * 1024); } while (0)
; #define PG8_MMA(ai, bj, At, Bt) do { __builtin_amdgcn_s_setprio(1); _Pragma("unroll") for (int m = 0; m < 4; ++m) _Pragma("unroll") for (int n = 0; n < 2; ++n) _Pragma("unroll") for (int k = 0; k < 2; ++k) \
;         acc[ai][bj][m][n] = mma16<Epi::I8>(Bt[n][k], At[m][k], acc[ai][bj][m][n]); __builtin_amdgcn_s_setprio(0); } while (0)
; #define PG8_WAIT_V(n) asm volatile("s_waitcnt vmcnt(" #n ")" ::: "memory")
; #define PG8_WAIT_L(n) asm volatile("s_waitcnt lgkmcnt(" #n ")" ::: "memory")
; #define PG8_BAR __builtin_amdgcn_s_barrier()
; #define PG8_SCHED __builtin_amdgcn_sched_barrier(0)
; template <class Epi, class Sched, bool ALIGN_EPI = false, bool SP2 = false>
; __device__ __forceinline__ void gemm_phase(PG8_LAS unsigned char* lds, const Gemm g, const Sched& S, const Epi& E) {
;     ...
;             PG8_LDB(B0, 1, 0); PG8_LDB(B1, 1, 1); PG8_SCHED; PG8_LDA(At, 1, 0); PG8_STAGE(PG8_SA(0, 1), a2 + hstep, voffA);
;             PG8_WAIT_V(8); PG8_WAIT_L(0); PG8_BAR; PG8_MMA(0, 0, At, B0); PG8_MMA(0, 1, At, B1); PG8_BAR; PG8_SCHED;
	s_add_i32 s84, 0, 0x18000
	s_add_i32 vcc_hi, 0, 0x1c000
	v_add_u32_e32 v122, s84, v248
	v_add_u32_e32 v154, vcc_hi, v248
	ds_read_b128 v[98:101], v122
	ds_read_b128 v[102:105], v122 offset:1024
	ds_read_b128 v[114:117], v122 offset:2048
	ds_read_b128 v[122:125], v122 offset:3072
	ds_read_b128 v[130:133], v154
	ds_read_b128 v[138:141], v154 offset:1024
	ds_read_b128 v[146:149], v154 offset:2048
	ds_read_b128 v[154:157], v154 offset:3072
	s_add_u32 s4, s8, s58
	s_addc_u32 s5, s9, 0
	s_mov_b32 m0, s71
	v_lshl_add_u64 v[222:223], s[4:5], 0, v[194:195]
	ds_read_b128 v[162:165], v249 offset:32768
	ds_read_b128 v[166:169], v249 offset:33792
	ds_read_b128 v[170:173], v249 offset:34816
	ds_read_b128 v[174:177], v249 offset:35840
	ds_read_b128 v[178:181], v249 offset:36864
	ds_read_b128 v[182:185], v249 offset:37888
	ds_read_b128 v[186:189], v249 offset:38912
	ds_read_b128 v[190:193], v249 offset:39936
	global_load_lds_dwordx4 v[222:223], off
	v_lshl_add_u64 v[222:223], s[4:5], 0, v[196:197]
	s_mov_b32 m0, s12
	s_nop 0
	global_load_lds_dwordx4 v[222:223], off
	s_waitcnt vmcnt(8)
	s_waitcnt lgkmcnt(0)
	s_barrier
	s_setprio 1
	s_waitcnt lgkmcnt(0)
	v_mfma_f32_16x16x32_bf16 v[158:161], v[98:101], v[162:165], v[158:161]
	v_mfma_f32_16x16x32_bf16 v[158:161], v[102:105], v[166:169], v[158:161]
	v_mfma_f32_16x16x32_bf16 v[150:153], v[114:117], v[162:165], v[150:153]
	v_mfma_f32_16x16x32_bf16 v[150:153], v[122:125], v[166:169], v[150:153]
	v_mfma_f32_16x16x32_bf16 v[126:129], v[98:101], v[170:173], v[126:129]
	v_mfma_f32_16x16x32_bf16 v[126:129], v[102:105], v[174:177], v[126:129]
	v_mfma_f32_16x16x32_bf16 v[118:121], v[114:117], v[170:173], v[118:121]
	v_mfma_f32_16x16x32_bf16 v[118:121], v[122:125], v[174:177], v[118:121]
	v_mfma_f32_16x16x32_bf16 v[94:97], v[98:101], v[178:181], v[94:97]
	v_mfma_f32_16x16x32_bf16 v[94:97], v[102:105], v[182:185], v[94:97]
	v_mfma_f32_16x16x32_bf16 v[90:93], v[114:117], v[178:181], v[90:93]
	v_mfma_f32_16x16x32_bf16 v[90:93], v[122:125], v[182:185], v[90:93]
	v_mfma_f32_16x16x32_bf16 v[78:81], v[98:101], v[186:189], v[78:81]
	v_mfma_f32_16x16x32_bf16 v[78:81], v[102:105], v[190:193], v[78:81]
	v_mfma_f32_16x16x32_bf16 v[74:77], v[114:117], v[186:189], v[74:77]
	v_mfma_f32_16x16x32_bf16 v[74:77], v[122:125], v[190:193], v[74:77]
	s_setprio 0
	s_setprio 1
	v_mfma_f32_16x16x32_bf16 v[142:145], v[130:133], v[162:165], v[142:145]
	v_mfma_f32_16x16x32_bf16 v[142:145], v[138:141], v[166:169], v[142:145]
	v_mfma_f32_16x16x32_bf16 v[134:137], v[146:149], v[162:165], v[134:137]
	v_mfma_f32_16x16x32_bf16 v[134:137], v[154:157], v[166:169], v[134:137]
	v_mfma_f32_16x16x32_bf16 v[110:113], v[130:133], v[170:173], v[110:113]
	v_mfma_f32_16x16x32_bf16 v[110:113], v[138:141], v[174:177], v[110:113]
	v_mfma_f32_16x16x32_bf16 v[106:109], v[146:149], v[170:173], v[106:109]
	v_mfma_f32_16x16x32_bf16 v[106:109], v[154:157], v[174:177], v[106:109]
	v_mfma_f32_16x16x32_bf16 v[86:89], v[130:133], v[178:181], v[86:89]
	v_mfma_f32_16x16x32_bf16 v[86:89], v[138:141], v[182:185], v[86:89]
	v_mfma_f32_16x16x32_bf16 v[82:85], v[146:149], v[178:181], v[82:85]
	v_mfma_f32_16x16x32_bf16 v[82:85], v[154:157], v[182:185], v[82:85]
	v_mfma_f32_16x16x32_bf16 v[70:73], v[130:133], v[186:189], v[70:73]
	v_mfma_f32_16x16x32_bf16 v[70:73], v[138:141], v[190:193], v[70:73]
	v_mfma_f32_16x16x32_bf16 v[66:69], v[146:149], v[186:189], v[66:69]
	v_mfma_f32_16x16x32_bf16 v[66:69], v[154:157], v[190:193], v[66:69]
	s_setprio 0
	s_barrier
; #define PG8_STAGE(bufoff, gbase, voff) do { _Pragma("unroll") for (int _i = 0; _i < 2; ++_i) \
;         __builtin_amdgcn_global_load_lds((const unsigned*)((const char*)(gbase) + (voff)[_i]), (PG8_LAS unsigned*)(lds + (bufoff) + ldsw + _i * 8192), 16, 0, 0); } while (0)
; #define PG8_LDA(dst, b, h) do { _Pragma("unroll") for (int m = 0; m < 4; ++m) _Pragma("unroll") for (int k = 0; k < 2; ++k) dst[m][k] = *(const PG8_LAS bf16x8*)(lds + PG8_SA(b, h) + aoff + m * 2048 + k * 1024); } while (0)
; #define PG8_MMA(ai, bj, At, Bt) do { __builtin_amdgcn_s_setprio(1); _Pragma("unroll") for (int m = 0; m < 4; ++m) _Pragma("unroll") for (int n = 0; n < 2; ++n) _Pragma("unroll") for (int k = 0; k < 2; ++k) \
;         acc[ai][bj][m][n] = mma16<Epi::I8>(Bt[n][k], At[m][k], acc[ai][bj][m][n]); __builtin_amdgcn_s_setprio(0); } while (0)
; #define PG8_WAIT_V(n) asm volatile("s_waitcnt vmcnt(" #n ")" ::: "memory")
; #define PG8_WAIT_L(n) asm volatile("s_waitcnt lgkmcnt(" #n ")" ::: "memory")
; #define PG8_BAR __builtin_amdgcn_s_barrier()
; #define PG8_SCHED __builtin_amdgcn_sched_barrier(0)
; template <class Epi, class Sched, bool ALIGN_EPI = false, bool SP2 = false>
; __device__ __forceinline__ void gemm_phase(PG8_LAS unsigned char* lds, const Gemm g, const Sched& S, const Epi& E) {
;     ...
;             PG8_LDA(At, 1, 1); PG8_STAGE(PG8_SB(1, 0), b3, voffB); PG8_STAGE(PG8_SB(1, 1), b3 + hstep, voffB); PG8_STAGE(PG8_SA(1, 0), a3, voffA);
;             PG8_WAIT_V(8); PG8_WAIT_L(0); PG8_BAR; PG8_MMA(1, 0, At, B0); PG8_MMA(1, 1, At, B1); PG8_BAR; PG8_SCHED;
	s_add_i32 s4, s84, s80
	v_lshl_add_u64 v[206:207], v[206:207], 0, s[92:93]
	s_mov_b32 m0, s4
	ds_read_b128 v[162:165], v249 offset:49152
	ds_read_b128 v[166:169], v249 offset:50176
	ds_read_b128 v[170:173], v249 offset:51200
	ds_read_b128 v[174:177], v249 offset:52224
	ds_read_b128 v[178:181], v249 offset:53248
	ds_read_b128 v[182:185], v249 offset:54272
	ds_read_b128 v[186:189], v249 offset:55296
	ds_read_b128 v[190:193], v249 offset:56320
	global_load_lds_dwordx4 v[206:207], off
	v_lshl_add_u64 v[206:207], v[212:213], 0, s[92:93]
	s_add_i32 m0, s4, 0x2000
	s_add_i32 s4, vcc_hi, s80
	global_load_lds_dwordx4 v[206:207], off
	v_lshl_add_u64 v[206:207], v[214:215], 0, s[92:93]
	s_mov_b32 m0, s4
	s_nop 0
	global_load_lds_dwordx4 v[206:207], off
	v_lshl_add_u64 v[206:207], v[216:217], 0, s[92:93]
	s_add_i32 m0, s4, 0x2000
	s_nop 0
	global_load_lds_dwordx4 v[206:207], off
	v_lshl_add_u64 v[206:207], v[218:219], 0, s[92:93]
	s_mov_b32 m0, s10
	s_nop 0
	global_load_lds_dwordx4 v[206:207], off
	v_lshl_add_u64 v[206:207], v[220:221], 0, s[92:93]
	s_mov_b32 m0, s11
	s_nop 0
	global_load_lds_dwordx4 v[206:207], off
	s_waitcnt vmcnt(8)
	s_waitcnt lgkmcnt(0)
	s_barrier
	s_setprio 1
	s_waitcnt lgkmcnt(0)
	v_mfma_f32_16x16x32_bf16 v[62:65], v[98:101], v[162:165], v[62:65]
	v_mfma_f32_16x16x32_bf16 v[62:65], v[102:105], v[166:169], v[62:65]
	v_mfma_f32_16x16x32_bf16 v[58:61], v[114:117], v[162:165], v[58:61]
	v_mfma_f32_16x16x32_bf16 v[58:61], v[122:125], v[166:169], v[58:61]
	v_mfma_f32_16x16x32_bf16 v[46:49], v[98:101], v[170:173], v[46:49]
	v_mfma_f32_16x16x32_bf16 v[46:49], v[102:105], v[174:177], v[46:49]
	v_mfma_f32_16x16x32_bf16 v[42:45], v[114:117], v[170:173], v[42:45]
	v_mfma_f32_16x16x32_bf16 v[42:45], v[122:125], v[174:177], v[42:45]
	v_mfma_f32_16x16x32_bf16 v[30:33], v[98:101], v[178:181], v[30:33]
	v_mfma_f32_16x16x32_bf16 v[30:33], v[102:105], v[182:185], v[30:33]
	v_mfma_f32_16x16x32_bf16 v[26:29], v[114:117], v[178:181], v[26:29]
	v_mfma_f32_16x16x32_bf16 v[26:29], v[122:125], v[182:185], v[26:29]
	v_mfma_f32_16x16x32_bf16 v[14:17], v[98:101], v[186:189], v[14:17]
	v_mfma_f32_16x16x32_bf16 v[14:17], v[102:105], v[190:193], v[14:17]
	v_mfma_f32_16x16x32_bf16 v[10:13], v[114:117], v[186:189], v[10:13]
	v_mfma_f32_16x16x32_bf16 v[10:13], v[122:125], v[190:193], v[10:13]
	s_setprio 0
	s_setprio 1
	v_mfma_f32_16x16x32_bf16 v[54:57], v[130:133], v[162:165], v[54:57]
	v_mfma_f32_16x16x32_bf16 v[54:57], v[138:141], v[166:169], v[54:57]
	v_mfma_f32_16x16x32_bf16 v[50:53], v[146:149], v[162:165], v[50:53]
	v_mfma_f32_16x16x32_bf16 v[50:53], v[154:157], v[166:169], v[50:53]
	v_mfma_f32_16x16x32_bf16 v[38:41], v[130:133], v[170:173], v[38:41]
	v_mfma_f32_16x16x32_bf16 v[38:41], v[138:141], v[174:177], v[38:41]
	v_mfma_f32_16x16x32_bf16 v[34:37], v[146:149], v[170:173], v[34:37]
	v_mfma_f32_16x16x32_bf16 v[34:37], v[154:157], v[174:177], v[34:37]
	v_mfma_f32_16x16x32_bf16 v[22:25], v[130:133], v[178:181], v[22:25]
	v_mfma_f32_16x16x32_bf16 v[22:25], v[138:141], v[182:185], v[22:25]
	v_mfma_f32_16x16x32_bf16 v[18:21], v[146:149], v[178:181], v[18:21]
	v_mfma_f32_16x16x32_bf16 v[18:21], v[154:157], v[182:185], v[18:21]
	v_mfma_f32_16x16x32_bf16 v[6:9], v[130:133], v[186:189], v[6:9]
	v_mfma_f32_16x16x32_bf16 v[6:9], v[138:141], v[190:193], v[6:9]
	v_mfma_f32_16x16x32_bf16 v[2:5], v[146:149], v[186:189], v[2:5]
	v_mfma_f32_16x16x32_bf16 v[2:5], v[154:157], v[190:193], v[2:5]
	s_setprio 0
	s_barrier
	s_add_u32 s6, s6, 0x100
	s_addc_u32 s7, s7, 0
	s_add_u32 s67, s67, 0x100
	s_addc_u32 s85, s85, 0
	s_cmp_ge_u32 vcc_lo, s69
	s_mov_b32 s8, vcc_lo
	s_cbranch_scc0 .LBB0_175

; #define PG8_STAGE(bufoff, gbase, voff) do { _Pragma("unroll") for (int _i = 0; _i < 2; ++_i) \
;         __builtin_amdgcn_global_load_lds((const unsigned*)((const char*)(gbase) + (voff)[_i]), (PG8_LAS unsigned*)(lds + (bufoff) + ldsw + _i * 8192), 16, 0, 0); } while (0)
; #define PG8_LDA(dst, b, h) do { _Pragma("unroll") for (int m = 0; m < 4; ++m) _Pragma("unroll") for (int k = 0; k < 2; ++k) dst[m][k] = *(const PG8_LAS bf16x8*)(lds + PG8_SA(b, h) + aoff + m * 2048 + k * 1024); } while (0)
; #define PG8_LDB(dst, b, h) do { _Pragma("unroll") for (int n = 0; n < 2; ++n) _Pragma("unroll") for (int k = 0; k < 2; ++k) dst[n][k] = *(const PG8_LAS bf16x8*)(lds + PG8_SB(b, h) + boff + n * 2048 + k * 1024); } while (0)
; #define PG8_MMA(ai, bj, At, Bt) do { __builtin_amdgcn_s_setprio(1); _Pragma("unroll") for (int m = 0; m < 4; ++m) _Pragma("unroll") for (int n = 0; n < 2; ++n) _Pragma("unroll") for (int k = 0; k < 2; ++k) \
;         acc[ai][bj][m][n] = mma16<Epi::I8>(Bt[n][k], At[m][k], acc[ai][bj][m][n]); __builtin_amdgcn_s_setprio(0); } while (0)
; #define PG8_WAIT_V(n) asm volatile("s_waitcnt vmcnt(" #n ")" ::: "memory")
; template <class Epi, class Sched, bool ALIGN_EPI = false, bool SP2 = false>
; __device__ __forceinline__ void gemm_phase(PG8_LAS unsigned char* lds, const Gemm g, const Sched& S, const Epi& E) {
;     ...
;         const bool has_next = S.next(ui + 1, nxt);
;         const char* nA = has_next ? (const char*)g.A + (size_t)nxt.pm * tstep : cA; const char* nB = has_next ? (const char*)g.Bt + (size_t)nxt.pn * tstep : cB;
;         for (int t = 0; t < nt; t += 2) {
;             const bool last = (t == nt - 2);
;             const char* a1 = cA + (size_t)(t + 1) * kstep;
;             const char* a2 = last ? nA : cA + (size_t)(t + 2) * kstep; const char* b2 = last ? nB : cB + (size_t)(t + 2) * kstep;
;             const char* a3 = a2 + kstep; const char* b3 = b2 + kstep;
;             if (last && has_next) S.a_ready(nxt);
;             if constexpr (SP2) {
;             PG8_LDB(B0, 0, 0); PG8_LDB(B1, 0, 1); PG8_SCHED; PG8_LDA(At, 0, 0); PG8_STAGE(PG8_SA(1, 1), a1 + hstep, voffA);
;             PG8_WAIT_V(8); PG8_WAIT_L(0); PG8_BAR; PG8_MMA(0, 0, At, B0); PG8_MMA(0, 1, At, B1); PG8_BAR; PG8_SCHED;
;             PG8_LDA(At, 0, 1); PG8_STAGE(PG8_SB(0, 0), b2, voffB); PG8_STAGE(PG8_SB(0, 1), b2 + hstep, voffB); PG8_STAGE(PG8_SA(0, 0), a2, voffA);
.Lpeel291:
	s_add_u32 s84, s8, 0x100
	s_addc_u32 s85, s9, 0
	s_add_i32 s66, 0, 0x10000
	s_cmp_eq_u32 s10, 12
	s_cselect_b32 vcc_hi, s5, s85
	s_cselect_b32 vcc_lo, s7, s84
	s_cselect_b32 s97, s11, s68
	s_cselect_b32 s96, s67, s69
	s_add_i32 s70, 0, 0x14000
	v_add_u32_e32 v110, s66, v175
	v_add_u32_e32 v168, s70, v175
	s_waitcnt vmcnt(0)
	ds_read_b128 v[66:69], v110
	ds_read_b128 v[70:73], v110 offset:1024
	ds_read_b128 v[106:109], v110 offset:2048
	ds_read_b128 v[110:113], v110 offset:3072
	ds_read_b128 v[114:117], v168
	ds_read_b128 v[118:121], v168 offset:1024
	ds_read_b128 v[126:129], v168 offset:2048
	ds_read_b128 v[178:181], v168 offset:3072
	v_lshl_add_u64 v[168:169], s[8:9], 0, v[164:165]
	s_add_i32 m0, s1, 0xc000
	ds_read_b128 v[182:185], v177
	ds_read_b128 v[186:189], v177 offset:1024
	ds_read_b128 v[190:193], v177 offset:2048
	ds_read_b128 v[194:197], v177 offset:3072
	ds_read_b128 v[198:201], v177 offset:4096
	ds_read_b128 v[210:213], v177 offset:5120
	ds_read_b128 v[214:217], v177 offset:6144
	ds_read_b128 v[218:221], v177 offset:7168
	global_load_lds_dwordx4 v[168:169], off
	v_lshl_add_u64 v[168:169], s[8:9], 0, v[166:167]
	s_add_i32 m0, s1, 0xe000
	s_nop 0
	global_load_lds_dwordx4 v[168:169], off
	s_waitcnt vmcnt(8)
	s_waitcnt lgkmcnt(0)
	s_barrier
	s_setprio 1
	s_waitcnt lgkmcnt(0)
	v_mfma_i32_16x16x64_i8 v[154:157], v[66:69], v[182:185], 0
	v_mfma_i32_16x16x64_i8 v[154:157], v[70:73], v[186:189], v[154:157]
	v_mfma_i32_16x16x64_i8 v[146:149], v[106:109], v[182:185], 0
	v_mfma_i32_16x16x64_i8 v[146:149], v[110:113], v[186:189], v[146:149]
	v_mfma_i32_16x16x64_i8 v[150:153], v[66:69], v[190:193], 0
	v_mfma_i32_16x16x64_i8 v[150:153], v[70:73], v[194:197], v[150:153]
	v_mfma_i32_16x16x64_i8 v[138:141], v[106:109], v[190:193], 0
	v_mfma_i32_16x16x64_i8 v[138:141], v[110:113], v[194:197], v[138:141]
	v_mfma_i32_16x16x64_i8 v[142:145], v[66:69], v[198:201], 0
	v_mfma_i32_16x16x64_i8 v[142:145], v[70:73], v[210:213], v[142:145]
	v_mfma_i32_16x16x64_i8 v[130:133], v[106:109], v[198:201], 0
	v_mfma_i32_16x16x64_i8 v[130:133], v[110:113], v[210:213], v[130:133]
	v_mfma_i32_16x16x64_i8 v[134:137], v[66:69], v[214:217], 0
	v_mfma_i32_16x16x64_i8 v[134:137], v[70:73], v[218:221], v[134:137]
	v_mfma_i32_16x16x64_i8 v[122:125], v[106:109], v[214:217], 0
	v_mfma_i32_16x16x64_i8 v[122:125], v[110:113], v[218:221], v[122:125]
	s_setprio 0
	s_setprio 1
	v_mfma_i32_16x16x64_i8 v[102:105], v[114:117], v[182:185], 0
	v_mfma_i32_16x16x64_i8 v[102:105], v[118:121], v[186:189], v[102:105]
	v_mfma_i32_16x16x64_i8 v[94:97], v[126:129], v[182:185], 0
	v_mfma_i32_16x16x64_i8 v[94:97], v[178:181], v[186:189], v[94:97]
	v_mfma_i32_16x16x64_i8 v[98:101], v[114:117], v[190:193], 0
	v_mfma_i32_16x16x64_i8 v[98:101], v[118:121], v[194:197], v[98:101]
	v_mfma_i32_16x16x64_i8 v[86:89], v[126:129], v[190:193], 0
	v_mfma_i32_16x16x64_i8 v[86:89], v[178:181], v[194:197], v[86:89]
	v_mfma_i32_16x16x64_i8 v[90:93], v[114:117], v[198:201], 0
	v_mfma_i32_16x16x64_i8 v[90:93], v[118:121], v[210:213], v[90:93]
	v_mfma_i32_16x16x64_i8 v[78:81], v[126:129], v[198:201], 0
	v_mfma_i32_16x16x64_i8 v[78:81], v[178:181], v[210:213], v[78:81]
	v_mfma_i32_16x16x64_i8 v[82:85], v[114:117], v[214:217], 0
	v_mfma_i32_16x16x64_i8 v[82:85], v[118:121], v[218:221], v[82:85]
	v_mfma_i32_16x16x64_i8 v[74:77], v[126:129], v[214:217], 0
	v_mfma_i32_16x16x64_i8 v[74:77], v[178:181], v[218:221], v[74:77]
	s_setprio 0
	s_barrier
	s_add_i32 s8, s66, s81
	v_lshl_add_u64 v[168:169], s[96:97], 0, v[0:1]
	s_mov_b32 m0, s8
	ds_read_b128 v[182:185], v177 offset:16384
	ds_read_b128 v[186:189], v177 offset:17408
	ds_read_b128 v[190:193], v177 offset:18432
	ds_read_b128 v[194:197], v177 offset:19456
	ds_read_b128 v[198:201], v177 offset:20480
	ds_read_b128 v[210:213], v177 offset:21504
	ds_read_b128 v[214:217], v177 offset:22528
	ds_read_b128 v[218:221], v177 offset:23552
	global_load_lds_dwordx4 v[168:169], off
	s_add_i32 m0, s8, 0x2000
	s_add_u32 s8, s96, 0x40000
	v_lshl_add_u64 v[206:207], s[96:97], 0, v[158:159]
	s_addc_u32 s9, s97, 0
	s_add_i32 s66, s70, s81
	global_load_lds_dwordx4 v[206:207], off
	v_lshl_add_u64 v[222:223], s[8:9], 0, v[0:1]
	s_mov_b32 m0, s66
	v_lshl_add_u64 v[224:225], vcc, 0, v[160:161]
	global_load_lds_dwordx4 v[222:223], off
	v_lshl_add_u64 v[222:223], s[8:9], 0, v[158:159]
	s_add_i32 m0, s66, 0x2000
	s_nop 0
	global_load_lds_dwordx4 v[222:223], off
	v_lshl_add_u64 v[222:223], vcc, 0, v[162:163]
	s_mov_b32 m0, s1
	s_nop 0
	global_load_lds_dwordx4 v[222:223], off
	s_mov_b32 m0, s58
	s_nop 0
	global_load_lds_dwordx4 v[224:225], off
	s_waitcnt vmcnt(8)
	s_waitcnt lgkmcnt(0)
	s_barrier
; #define PG8_STAGE(bufoff, gbase, voff) do { _Pragma("unroll") for (int _i = 0; _i < 2; ++_i) \
;         __builtin_amdgcn_global_load_lds((const unsigned*)((const char*)(gbase) + (voff)[_i]), (PG8_LAS unsigned*)(lds + (bufoff) + ldsw + _i * 8192), 16, 0, 0); } while (0)
; #define PG8_LDA(dst, b, h) do { _Pragma("unroll") for (int m = 0; m < 4; ++m) _Pragma("unroll") for (int k = 0; k < 2; ++k) dst[m][k] = *(const PG8_LAS bf16x8*)(lds + PG8_SA(b, h) + aoff + m * 2048 + k * 1024); } while (0)
; #define PG8_LDB(dst, b, h) do { _Pragma("unroll") for (int n = 0; n < 2; ++n) _Pragma("unroll") for (int k = 0; k < 2; ++k) dst[n][k] = *(const PG8_LAS bf16x8*)(lds + PG8_SB(b, h) + boff + n * 2048 + k * 1024); } while (0)
; #define PG8_MMA(ai, bj, At, Bt) do { __builtin_amdgcn_s_setprio(1); _Pragma("unroll") for (int m = 0; m < 4; ++m) _Pragma("unroll") for (int n = 0; n < 2; ++n) _Pragma("unroll") for (int k = 0; k < 2; ++k) \
;         acc[ai][bj][m][n] = mma16<Epi::I8>(Bt[n][k], At[m][k], acc[ai][bj][m][n]); __builtin_amdgcn_s_setprio(0); } while (0)
; #define PG8_WAIT_V(n) asm volatile("s_waitcnt vmcnt(" #n ")" ::: "memory")
; #define PG8_WAIT_L(n) asm volatile("s_waitcnt lgkmcnt(" #n ")" ::: "memory")
; template <class Epi, class Sched, bool ALIGN_EPI = false, bool SP2 = false>
; __device__ __forceinline__ void gemm_phase(PG8_LAS unsigned char* lds, const Gemm g, const Sched& S, const Epi& E) {
;     ...
;             if constexpr (SP2) {
;             PG8_LDB(B0, 0, 0); PG8_LDB(B1, 0, 1); PG8_SCHED; PG8_LDA(At, 0, 0); PG8_STAGE(PG8_SA(1, 1), a1 + hstep, voffA);
;             PG8_WAIT_V(8); PG8_WAIT_L(0); PG8_BAR; PG8_MMA(0, 0, At, B0); PG8_MMA(0, 1, At, B1); PG8_BAR; PG8_SCHED;
;             PG8_LDA(At, 0, 1); PG8_STAGE(PG8_SB(0, 0), b2, voffB); PG8_STAGE(PG8_SB(0, 1), b2 + hstep, voffB); PG8_STAGE(PG8_SA(0, 0), a2, voffA);
;             PG8_WAIT_V(8); PG8_WAIT_L(0); PG8_BAR; PG8_MMA(1, 0, At, B0); PG8_MMA(1, 1, At, B1); PG8_BAR; PG8_SCHED;
;             PG8_LDB(B0, 1, 0); PG8_LDB(B1, 1, 1); PG8_SCHED; PG8_LDA(At, 1, 0); PG8_STAGE(PG8_SA(0, 1), a2 + hstep, voffA);
;             PG8_WAIT_V(8); PG8_WAIT_L(0); PG8_BAR; PG8_MMA(0, 0, At, B0); PG8_MMA(0, 1, At, B1); PG8_BAR; PG8_SCHED;
;             PG8_LDA(At, 1, 1); PG8_STAGE(PG8_SB(1, 0), b3, voffB); PG8_STAGE(PG8_SB(1, 1), b3 + hstep, voffB); PG8_STAGE(PG8_SA(1, 0), a3, voffA);
	s_setprio 1
	s_waitcnt lgkmcnt(0)
	v_mfma_i32_16x16x64_i8 v[62:65], v[66:69], v[182:185], 0
	v_mfma_i32_16x16x64_i8 v[62:65], v[70:73], v[186:189], v[62:65]
	v_mfma_i32_16x16x64_i8 v[54:57], v[106:109], v[182:185], 0
	v_mfma_i32_16x16x64_i8 v[54:57], v[110:113], v[186:189], v[54:57]
	v_mfma_i32_16x16x64_i8 v[58:61], v[66:69], v[190:193], 0
	v_mfma_i32_16x16x64_i8 v[58:61], v[70:73], v[194:197], v[58:61]
	v_mfma_i32_16x16x64_i8 v[46:49], v[106:109], v[190:193], 0
	v_mfma_i32_16x16x64_i8 v[46:49], v[110:113], v[194:197], v[46:49]
	v_mfma_i32_16x16x64_i8 v[50:53], v[66:69], v[198:201], 0
	v_mfma_i32_16x16x64_i8 v[50:53], v[70:73], v[210:213], v[50:53]
	v_mfma_i32_16x16x64_i8 v[38:41], v[106:109], v[198:201], 0
	v_mfma_i32_16x16x64_i8 v[38:41], v[110:113], v[210:213], v[38:41]
	v_mfma_i32_16x16x64_i8 v[42:45], v[66:69], v[214:217], 0
	v_mfma_i32_16x16x64_i8 v[42:45], v[70:73], v[218:221], v[42:45]
	v_mfma_i32_16x16x64_i8 v[34:37], v[106:109], v[214:217], 0
	v_mfma_i32_16x16x64_i8 v[34:37], v[110:113], v[218:221], v[34:37]
	s_setprio 0
	s_setprio 1
	v_mfma_i32_16x16x64_i8 v[30:33], v[114:117], v[182:185], 0
	v_mfma_i32_16x16x64_i8 v[30:33], v[118:121], v[186:189], v[30:33]
	v_mfma_i32_16x16x64_i8 v[22:25], v[126:129], v[182:185], 0
	v_mfma_i32_16x16x64_i8 v[22:25], v[178:181], v[186:189], v[22:25]
	v_mfma_i32_16x16x64_i8 v[26:29], v[114:117], v[190:193], 0
	v_mfma_i32_16x16x64_i8 v[26:29], v[118:121], v[194:197], v[26:29]
	v_mfma_i32_16x16x64_i8 v[14:17], v[126:129], v[190:193], 0
	v_mfma_i32_16x16x64_i8 v[14:17], v[178:181], v[194:197], v[14:17]
	v_mfma_i32_16x16x64_i8 v[18:21], v[114:117], v[198:201], 0
	v_mfma_i32_16x16x64_i8 v[18:21], v[118:121], v[210:213], v[18:21]
	v_mfma_i32_16x16x64_i8 v[6:9], v[126:129], v[198:201], 0
	v_mfma_i32_16x16x64_i8 v[6:9], v[178:181], v[210:213], v[6:9]
	v_mfma_i32_16x16x64_i8 v[10:13], v[114:117], v[214:217], 0
	v_mfma_i32_16x16x64_i8 v[10:13], v[118:121], v[218:221], v[10:13]
	v_mfma_i32_16x16x64_i8 v[2:5], v[126:129], v[214:217], 0
	v_mfma_i32_16x16x64_i8 v[2:5], v[178:181], v[218:221], v[2:5]
	s_setprio 0
	s_barrier
	s_add_i32 s66, 0, 0x18000
	s_add_i32 s70, 0, 0x1c000
	v_add_u32_e32 v110, s66, v175
	v_add_u32_e32 v170, s70, v175
	ds_read_b128 v[66:69], v110
	ds_read_b128 v[70:73], v110 offset:1024
	ds_read_b128 v[106:109], v110 offset:2048
	ds_read_b128 v[110:113], v110 offset:3072
	ds_read_b128 v[114:117], v170
	ds_read_b128 v[118:121], v170 offset:1024
	ds_read_b128 v[126:129], v170 offset:2048
	ds_read_b128 v[178:181], v170 offset:3072
	s_add_u32 s8, vcc_lo, 0x40000
	s_addc_u32 s9, vcc_hi, 0
	s_mov_b32 m0, s80
	v_lshl_add_u64 v[226:227], s[8:9], 0, v[162:163]
	ds_read_b128 v[182:185], v177 offset:32768
	ds_read_b128 v[186:189], v177 offset:33792
	ds_read_b128 v[190:193], v177 offset:34816
	ds_read_b128 v[194:197], v177 offset:35840
	ds_read_b128 v[198:201], v177 offset:36864
	ds_read_b128 v[210:213], v177 offset:37888
	ds_read_b128 v[214:217], v177 offset:38912
	ds_read_b128 v[218:221], v177 offset:39936
	global_load_lds_dwordx4 v[226:227], off
	v_lshl_add_u64 v[226:227], s[8:9], 0, v[160:161]
	s_mov_b32 m0, s0
	s_nop 0
	global_load_lds_dwordx4 v[226:227], off
	s_waitcnt vmcnt(8)
	s_waitcnt lgkmcnt(0)
	s_barrier
	s_setprio 1
	s_waitcnt lgkmcnt(0)
	v_mfma_i32_16x16x64_i8 v[154:157], v[66:69], v[182:185], v[154:157]
	v_mfma_i32_16x16x64_i8 v[154:157], v[70:73], v[186:189], v[154:157]
	v_mfma_i32_16x16x64_i8 v[146:149], v[106:109], v[182:185], v[146:149]
	v_mfma_i32_16x16x64_i8 v[146:149], v[110:113], v[186:189], v[146:149]
	v_mfma_i32_16x16x64_i8 v[150:153], v[66:69], v[190:193], v[150:153]
	v_mfma_i32_16x16x64_i8 v[150:153], v[70:73], v[194:197], v[150:153]
	v_mfma_i32_16x16x64_i8 v[138:141], v[106:109], v[190:193], v[138:141]
	v_mfma_i32_16x16x64_i8 v[138:141], v[110:113], v[194:197], v[138:141]
	v_mfma_i32_16x16x64_i8 v[142:145], v[66:69], v[198:201], v[142:145]
	v_mfma_i32_16x16x64_i8 v[142:145], v[70:73], v[210:213], v[142:145]
	v_mfma_i32_16x16x64_i8 v[130:133], v[106:109], v[198:201], v[130:133]
	v_mfma_i32_16x16x64_i8 v[130:133], v[110:113], v[210:213], v[130:133]
	v_mfma_i32_16x16x64_i8 v[134:137], v[66:69], v[214:217], v[134:137]
	v_mfma_i32_16x16x64_i8 v[134:137], v[70:73], v[218:221], v[134:137]
	v_mfma_i32_16x16x64_i8 v[122:125], v[106:109], v[214:217], v[122:125]
	v_mfma_i32_16x16x64_i8 v[122:125], v[110:113], v[218:221], v[122:125]
	s_setprio 0
	s_setprio 1
	v_mfma_i32_16x16x64_i8 v[102:105], v[114:117], v[182:185], v[102:105]
	v_mfma_i32_16x16x64_i8 v[102:105], v[118:121], v[186:189], v[102:105]
	v_mfma_i32_16x16x64_i8 v[94:97], v[126:129], v[182:185], v[94:97]
	v_mfma_i32_16x16x64_i8 v[94:97], v[178:181], v[186:189], v[94:97]
	v_mfma_i32_16x16x64_i8 v[98:101], v[114:117], v[190:193], v[98:101]
	v_mfma_i32_16x16x64_i8 v[98:101], v[118:121], v[194:197], v[98:101]
	v_mfma_i32_16x16x64_i8 v[86:89], v[126:129], v[190:193], v[86:89]
	v_mfma_i32_16x16x64_i8 v[86:89], v[178:181], v[194:197], v[86:89]
	v_mfma_i32_16x16x64_i8 v[90:93], v[114:117], v[198:201], v[90:93]
	v_mfma_i32_16x16x64_i8 v[90:93], v[118:121], v[210:213], v[90:93]
	v_mfma_i32_16x16x64_i8 v[78:81], v[126:129], v[198:201], v[78:81]
	v_mfma_i32_16x16x64_i8 v[78:81], v[178:181], v[210:213], v[78:81]
	v_mfma_i32_16x16x64_i8 v[82:85], v[114:117], v[214:217], v[82:85]
	v_mfma_i32_16x16x64_i8 v[82:85], v[118:121], v[218:221], v[82:85]
	v_mfma_i32_16x16x64_i8 v[74:77], v[126:129], v[214:217], v[74:77]
	v_mfma_i32_16x16x64_i8 v[74:77], v[178:181], v[218:221], v[74:77]
	s_setprio 0
	s_barrier
; #define PG8_STAGE(bufoff, gbase, voff) do { _Pragma("unroll") for (int _i = 0; _i < 2; ++_i) \
;         __builtin_amdgcn_global_load_lds((const unsigned*)((const char*)(gbase) + (voff)[_i]), (PG8_LAS unsigned*)(lds + (bufoff) + ldsw + _i * 8192), 16, 0, 0); } while (0)
; #define PG8_LDA(dst, b, h) do { _Pragma("unroll") for (int m = 0; m < 4; ++m) _Pragma("unroll") for (int k = 0; k < 2; ++k) dst[m][k] = *(const PG8_LAS bf16x8*)(lds + PG8_SA(b, h) + aoff + m * 2048 + k * 1024); } while (0)
; #define PG8_LDB(dst, b, h) do { _Pragma("unroll") for (int n = 0; n < 2; ++n) _Pragma("unroll") for (int k = 0; k < 2; ++k) dst[n][k] = *(const PG8_LAS bf16x8*)(lds + PG8_SB(b, h) + boff + n * 2048 + k * 1024); } while (0)
; template <class Epi, class Sched, bool ALIGN_EPI = false, bool SP2 = false>
; __device__ __forceinline__ void gemm_phase(PG8_LAS unsigned char* lds, const Gemm g, const Sched& S, const Epi& E) {
;     ...
;         for (int t = 0; t < nt; t += 2) {
;             const bool last = (t == nt - 2);
;             const char* a1 = cA + (size_t)(t + 1) * kstep;
;             const char* a2 = last ? nA : cA + (size_t)(t + 2) * kstep; const char* b2 = last ? nB : cB + (size_t)(t + 2) * kstep;
;             const char* a3 = a2 + kstep; const char* b3 = b2 + kstep;
;             if (last && has_next) S.a_ready(nxt);
;             if constexpr (SP2) {
;             PG8_LDB(B0, 0, 0); PG8_LDB(B1, 0, 1); PG8_SCHED; PG8_LDA(At, 0, 0); PG8_STAGE(PG8_SA(1, 1), a1 + hstep, voffA);
;             PG8_WAIT_V(8); PG8_WAIT_L(0); PG8_BAR; PG8_MMA(0, 0, At, B0); PG8_MMA(0, 1, At, B1); PG8_BAR; PG8_SCHED;
;             PG8_LDA(At, 0, 1); PG8_STAGE(PG8_SB(0, 0), b2, voffB); PG8_STAGE(PG8_SB(0, 1), b2 + hstep, voffB); PG8_STAGE(PG8_SA(0, 0), a2, voffA);
;             PG8_WAIT_V(8); PG8_WAIT_L(0); PG8_BAR; PG8_MMA(1, 0, At, B0); PG8_MMA(1, 1, At, B1); PG8_BAR; PG8_SCHED;
;             PG8_LDB(B0, 1, 0); PG8_LDB(B1, 1, 1); PG8_SCHED; PG8_LDA(At, 1, 0); PG8_STAGE(PG8_SA(0, 1), a2 + hstep, voffA);
;             PG8_WAIT_V(8); PG8_WAIT_L(0); PG8_BAR; PG8_MMA(0, 0, At, B0); PG8_MMA(0, 1, At, B1); PG8_BAR; PG8_SCHED;
;             PG8_LDA(At, 1, 1); PG8_STAGE(PG8_SB(1, 0), b3, voffB); PG8_STAGE(PG8_SB(1, 1), b3 + hstep, voffB); PG8_STAGE(PG8_SA(1, 0), a3, voffA);
;             PG8_WAIT_V(8); PG8_WAIT_L(0); PG8_BAR; PG8_MMA(1, 0, At, B0); PG8_MMA(1, 1, At, B1); PG8_BAR; PG8_SCHED;
	s_add_i32 s8, s66, s81
	v_lshl_add_u64 v[168:169], v[168:169], 0, s[92:93]
	s_mov_b32 m0, s8
	ds_read_b128 v[182:185], v177 offset:49152
	ds_read_b128 v[186:189], v177 offset:50176
	ds_read_b128 v[190:193], v177 offset:51200
	ds_read_b128 v[194:197], v177 offset:52224
	ds_read_b128 v[198:201], v177 offset:53248
	ds_read_b128 v[210:213], v177 offset:54272
	ds_read_b128 v[214:217], v177 offset:55296
	ds_read_b128 v[218:221], v177 offset:56320
	global_load_lds_dwordx4 v[168:169], off
	s_add_i32 m0, s8, 0x2000
	s_add_u32 s8, s96, 0x40080
	v_lshl_add_u64 v[168:169], v[206:207], 0, s[92:93]
	s_addc_u32 s9, s97, 0
	s_add_i32 s66, s70, s81
	global_load_lds_dwordx4 v[168:169], off
	v_lshl_add_u64 v[168:169], s[8:9], 0, v[0:1]
	s_mov_b32 m0, s66
	s_nop 0
	global_load_lds_dwordx4 v[168:169], off
	v_lshl_add_u64 v[168:169], s[8:9], 0, v[158:159]
	s_add_i32 m0, s66, 0x2000
	s_nop 0
	global_load_lds_dwordx4 v[168:169], off
	v_lshl_add_u64 v[168:169], v[222:223], 0, s[92:93]
	s_mov_b32 m0, s13
	s_nop 0
	global_load_lds_dwordx4 v[168:169], off
	v_lshl_add_u64 v[168:169], v[224:225], 0, s[92:93]
	s_mov_b32 m0, s12
	s_nop 0
	global_load_lds_dwordx4 v[168:169], off
	s_waitcnt vmcnt(8)
	s_waitcnt lgkmcnt(0)
	s_barrier
	s_setprio 1
	s_waitcnt lgkmcnt(0)
	v_mfma_i32_16x16x64_i8 v[62:65], v[66:69], v[182:185], v[62:65]
	v_mfma_i32_16x16x64_i8 v[62:65], v[70:73], v[186:189], v[62:65]
	v_mfma_i32_16x16x64_i8 v[54:57], v[106:109], v[182:185], v[54:57]
	v_mfma_i32_16x16x64_i8 v[54:57], v[110:113], v[186:189], v[54:57]
	v_mfma_i32_16x16x64_i8 v[58:61], v[66:69], v[190:193], v[58:61]
	v_mfma_i32_16x16x64_i8 v[58:61], v[70:73], v[194:197], v[58:61]
	v_mfma_i32_16x16x64_i8 v[46:49], v[106:109], v[190:193], v[46:49]
	v_mfma_i32_16x16x64_i8 v[46:49], v[110:113], v[194:197], v[46:49]
	v_mfma_i32_16x16x64_i8 v[50:53], v[66:69], v[198:201], v[50:53]
	v_mfma_i32_16x16x64_i8 v[50:53], v[70:73], v[210:213], v[50:53]
	v_mfma_i32_16x16x64_i8 v[38:41], v[106:109], v[198:201], v[38:41]
	v_mfma_i32_16x16x64_i8 v[38:41], v[110:113], v[210:213], v[38:41]
	v_mfma_i32_16x16x64_i8 v[42:45], v[66:69], v[214:217], v[42:45]
	v_mfma_i32_16x16x64_i8 v[42:45], v[70:73], v[218:221], v[42:45]
	v_mfma_i32_16x16x64_i8 v[34:37], v[106:109], v[214:217], v[34:37]
	v_mfma_i32_16x16x64_i8 v[34:37], v[110:113], v[218:221], v[34:37]
	s_setprio 0
	s_setprio 1
	v_mfma_i32_16x16x64_i8 v[30:33], v[114:117], v[182:185], v[30:33]
	v_mfma_i32_16x16x64_i8 v[30:33], v[118:121], v[186:189], v[30:33]
	v_mfma_i32_16x16x64_i8 v[22:25], v[126:129], v[182:185], v[22:25]
	v_mfma_i32_16x16x64_i8 v[22:25], v[178:181], v[186:189], v[22:25]
	v_mfma_i32_16x16x64_i8 v[26:29], v[114:117], v[190:193], v[26:29]
	v_mfma_i32_16x16x64_i8 v[26:29], v[118:121], v[194:197], v[26:29]
	v_mfma_i32_16x16x64_i8 v[14:17], v[126:129], v[190:193], v[14:17]
	v_mfma_i32_16x16x64_i8 v[14:17], v[178:181], v[194:197], v[14:17]
	v_mfma_i32_16x16x64_i8 v[18:21], v[114:117], v[198:201], v[18:21]
	v_mfma_i32_16x16x64_i8 v[18:21], v[118:121], v[210:213], v[18:21]
	v_mfma_i32_16x16x64_i8 v[6:9], v[126:129], v[198:201], v[6:9]
	v_mfma_i32_16x16x64_i8 v[6:9], v[178:181], v[210:213], v[6:9]
	v_mfma_i32_16x16x64_i8 v[10:13], v[114:117], v[214:217], v[10:13]
	v_mfma_i32_16x16x64_i8 v[10:13], v[118:121], v[218:221], v[10:13]
	v_mfma_i32_16x16x64_i8 v[2:5], v[126:129], v[214:217], v[2:5]
	v_mfma_i32_16x16x64_i8 v[2:5], v[178:181], v[218:221], v[2:5]
	s_setprio 0
	s_barrier
	s_add_i32 s10, s10, 2
	s_add_u32 s69, s69, 0x100
	s_addc_u32 s68, s68, 0
	s_cmp_gt_u32 s10, 13
	s_mov_b64 s[8:9], s[84:85]
	s_cbranch_scc0 .LBB0_291
	s_branch .Lpeelx291
.LBB0_291:
	s_add_u32 s84, s8, 0x100
	s_addc_u32 s85, s9, 0
	s_add_i32 s66, 0, 0x10000
	s_cmp_eq_u32 s10, 12
	s_cselect_b32 vcc_hi, s5, s85
	s_cselect_b32 vcc_lo, s7, s84
	s_cselect_b32 s97, s11, s68
	s_cselect_b32 s96, s67, s69
	s_add_i32 s70, 0, 0x14000
	v_add_u32_e32 v110, s66, v175
	v_add_u32_e32 v168, s70, v175
	s_waitcnt vmcnt(0)
	ds_read_b128 v[66:69], v110
	ds_read_b128 v[70:73], v110 offset:1024
	ds_read_b128 v[106:109], v110 offset:2048
	ds_read_b128 v[110:113], v110 offset:3072
	ds_read_b128 v[114:117], v168
	ds_read_b128 v[118:121], v168 offset:1024
	ds_read_b128 v[126:129], v168 offset:2048
	ds_read_b128 v[178:181], v168 offset:3072
	v_lshl_add_u64 v[168:169], s[8:9], 0, v[164:165]
	s_add_i32 m0, s1, 0xc000
	ds_read_b128 v[182:185], v177
	ds_read_b128 v[186:189], v177 offset:1024
	ds_read_b128 v[190:193], v177 offset:2048
	ds_read_b128 v[194:197], v177 offset:3072
	ds_read_b128 v[198:201], v177 offset:4096
	ds_read_b128 v[210:213], v177 offset:5120
	ds_read_b128 v[214:217], v177 offset:6144
	ds_read_b128 v[218:221], v177 offset:7168
	global_load_lds_dwordx4 v[168:169], off
	v_lshl_add_u64 v[168:169], s[8:9], 0, v[166:167]
	s_add_i32 m0, s1, 0xe000
	s_nop 0
	global_load_lds_dwordx4 v[168:169], off
	s_waitcnt vmcnt(8)
	s_waitcnt lgkmcnt(0)
	s_barrier
; #define PG8_STAGE(bufoff, gbase, voff) do { _Pragma("unroll") for (int _i = 0; _i < 2; ++_i) \
;         __builtin_amdgcn_global_load_lds((const unsigned*)((const char*)(gbase) + (voff)[_i]), (PG8_LAS unsigned*)(lds + (bufoff) + ldsw + _i * 8192), 16, 0, 0); } while (0)
; #define PG8_LDA(dst, b, h) do { _Pragma("unroll") for (int m = 0; m < 4; ++m) _Pragma("unroll") for (int k = 0; k < 2; ++k) dst[m][k] = *(const PG8_LAS bf16x8*)(lds + PG8_SA(b, h) + aoff + m * 2048 + k * 1024); } while (0)
; #define PG8_LDB(dst, b, h) do { _Pragma("unroll") for (int n = 0; n < 2; ++n) _Pragma("unroll") for (int k = 0; k < 2; ++k) dst[n][k] = *(const PG8_LAS bf16x8*)(lds + PG8_SB(b, h) + boff + n * 2048 + k * 1024); } while (0)
; #define PG8_MMA(ai, bj, At, Bt) do { __builtin_amdgcn_s_setprio(1); _Pragma("unroll") for (int m = 0; m < 4; ++m) _Pragma("unroll") for (int n = 0; n < 2; ++n) _Pragma("unroll") for (int k = 0; k < 2; ++k) \
;         acc[ai][bj][m][n] = mma16<Epi::I8>(Bt[n][k], At[m][k], acc[ai][bj][m][n]); __builtin_amdgcn_s_setprio(0); } while (0)
; #define PG8_WAIT_V(n) asm volatile("s_waitcnt vmcnt(" #n ")" ::: "memory")
; #define PG8_WAIT_L(n) asm volatile("s_waitcnt lgkmcnt(" #n ")" ::: "memory")
; #define PG8_BAR __builtin_amdgcn_s_barrier()
; #define PG8_SCHED __builtin_amdgcn_sched_barrier(0)
; template <class Epi, class Sched, bool ALIGN_EPI = false, bool SP2 = false>
; __device__ __forceinline__ void gemm_phase(PG8_LAS unsigned char* lds, const Gemm g, const Sched& S, const Epi& E) {
;     ...
;             if constexpr (SP2) {
;             PG8_LDB(B0, 0, 0); PG8_LDB(B1, 0, 1); PG8_SCHED; PG8_LDA(At, 0, 0); PG8_STAGE(PG8_SA(1, 1), a1 + hstep, voffA);
;             PG8_WAIT_V(8); PG8_WAIT_L(0); PG8_BAR; PG8_MMA(0, 0, At, B0); PG8_MMA(0, 1, At, B1); PG8_BAR; PG8_SCHED;
;             PG8_LDA(At, 0, 1); PG8_STAGE(PG8_SB(0, 0), b2, voffB); PG8_STAGE(PG8_SB(0, 1), b2 + hstep, voffB); PG8_STAGE(PG8_SA(0, 0), a2, voffA);
;             PG8_WAIT_V(8); PG8_WAIT_L(0); PG8_BAR; PG8_MMA(1, 0, At, B0); PG8_MMA(1, 1, At, B1); PG8_BAR; PG8_SCHED;
	s_setprio 1
	s_waitcnt lgkmcnt(0)
	v_mfma_i32_16x16x64_i8 v[154:157], v[66:69], v[182:185], v[154:157]
	v_mfma_i32_16x16x64_i8 v[154:157], v[70:73], v[186:189], v[154:157]
	v_mfma_i32_16x16x64_i8 v[146:149], v[106:109], v[182:185], v[146:149]
	v_mfma_i32_16x16x64_i8 v[146:149], v[110:113], v[186:189], v[146:149]
	v_mfma_i32_16x16x64_i8 v[150:153], v[66:69], v[190:193], v[150:153]
	v_mfma_i32_16x16x64_i8 v[150:153], v[70:73], v[194:197], v[150:153]
	v_mfma_i32_16x16x64_i8 v[138:141], v[106:109], v[190:193], v[138:141]
	v_mfma_i32_16x16x64_i8 v[138:141], v[110:113], v[194:197], v[138:141]
	v_mfma_i32_16x16x64_i8 v[142:145], v[66:69], v[198:201], v[142:145]
	v_mfma_i32_16x16x64_i8 v[142:145], v[70:73], v[210:213], v[142:145]
	v_mfma_i32_16x16x64_i8 v[130:133], v[106:109], v[198:201], v[130:133]
	v_mfma_i32_16x16x64_i8 v[130:133], v[110:113], v[210:213], v[130:133]
	v_mfma_i32_16x16x64_i8 v[134:137], v[66:69], v[214:217], v[134:137]
	v_mfma_i32_16x16x64_i8 v[134:137], v[70:73], v[218:221], v[134:137]
	v_mfma_i32_16x16x64_i8 v[122:125], v[106:109], v[214:217], v[122:125]
	v_mfma_i32_16x16x64_i8 v[122:125], v[110:113], v[218:221], v[122:125]
	s_setprio 0
	s_setprio 1
	v_mfma_i32_16x16x64_i8 v[102:105], v[114:117], v[182:185], v[102:105]
	v_mfma_i32_16x16x64_i8 v[102:105], v[118:121], v[186:189], v[102:105]
	v_mfma_i32_16x16x64_i8 v[94:97], v[126:129], v[182:185], v[94:97]
	v_mfma_i32_16x16x64_i8 v[94:97], v[178:181], v[186:189], v[94:97]
	v_mfma_i32_16x16x64_i8 v[98:101], v[114:117], v[190:193], v[98:101]
	v_mfma_i32_16x16x64_i8 v[98:101], v[118:121], v[194:197], v[98:101]
	v_mfma_i32_16x16x64_i8 v[86:89], v[126:129], v[190:193], v[86:89]
	v_mfma_i32_16x16x64_i8 v[86:89], v[178:181], v[194:197], v[86:89]
	v_mfma_i32_16x16x64_i8 v[90:93], v[114:117], v[198:201], v[90:93]
	v_mfma_i32_16x16x64_i8 v[90:93], v[118:121], v[210:213], v[90:93]
	v_mfma_i32_16x16x64_i8 v[78:81], v[126:129], v[198:201], v[78:81]
	v_mfma_i32_16x16x64_i8 v[78:81], v[178:181], v[210:213], v[78:81]
	v_mfma_i32_16x16x64_i8 v[82:85], v[114:117], v[214:217], v[82:85]
	v_mfma_i32_16x16x64_i8 v[82:85], v[118:121], v[218:221], v[82:85]
	v_mfma_i32_16x16x64_i8 v[74:77], v[126:129], v[214:217], v[74:77]
	v_mfma_i32_16x16x64_i8 v[74:77], v[178:181], v[218:221], v[74:77]
	s_setprio 0
	s_barrier
	s_add_i32 s8, s66, s81
	v_lshl_add_u64 v[168:169], s[96:97], 0, v[0:1]
	s_mov_b32 m0, s8
	ds_read_b128 v[182:185], v177 offset:16384
	ds_read_b128 v[186:189], v177 offset:17408
	ds_read_b128 v[190:193], v177 offset:18432
	ds_read_b128 v[194:197], v177 offset:19456
	ds_read_b128 v[198:201], v177 offset:20480
	ds_read_b128 v[210:213], v177 offset:21504
	ds_read_b128 v[214:217], v177 offset:22528
	ds_read_b128 v[218:221], v177 offset:23552
	global_load_lds_dwordx4 v[168:169], off
	s_add_i32 m0, s8, 0x2000
	s_add_u32 s8, s96, 0x40000
	v_lshl_add_u64 v[206:207], s[96:97], 0, v[158:159]
	s_addc_u32 s9, s97, 0
	s_add_i32 s66, s70, s81
	global_load_lds_dwordx4 v[206:207], off
	v_lshl_add_u64 v[222:223], s[8:9], 0, v[0:1]
	s_mov_b32 m0, s66
	v_lshl_add_u64 v[224:225], vcc, 0, v[160:161]
	global_load_lds_dwordx4 v[222:223], off
	v_lshl_add_u64 v[222:223], s[8:9], 0, v[158:159]
	s_add_i32 m0, s66, 0x2000
	s_nop 0
	global_load_lds_dwordx4 v[222:223], off
	v_lshl_add_u64 v[222:223], vcc, 0, v[162:163]
	s_mov_b32 m0, s1
	s_nop 0
	global_load_lds_dwordx4 v[222:223], off
	s_mov_b32 m0, s58
	s_nop 0
	global_load_lds_dwordx4 v[224:225], off
	s_waitcnt vmcnt(8)
	s_waitcnt lgkmcnt(0)
	s_barrier
	s_setprio 1
	s_waitcnt lgkmcnt(0)
	v_mfma_i32_16x16x64_i8 v[62:65], v[66:69], v[182:185], v[62:65]
	v_mfma_i32_16x16x64_i8 v[62:65], v[70:73], v[186:189], v[62:65]
	v_mfma_i32_16x16x64_i8 v[54:57], v[106:109], v[182:185], v[54:57]
	v_mfma_i32_16x16x64_i8 v[54:57], v[110:113], v[186:189], v[54:57]
	v_mfma_i32_16x16x64_i8 v[58:61], v[66:69], v[190:193], v[58:61]
	v_mfma_i32_16x16x64_i8 v[58:61], v[70:73], v[194:197], v[58:61]
	v_mfma_i32_16x16x64_i8 v[46:49], v[106:109], v[190:193], v[46:49]
	v_mfma_i32_16x16x64_i8 v[46:49], v[110:113], v[194:197], v[46:49]
	v_mfma_i32_16x16x64_i8 v[50:53], v[66:69], v[198:201], v[50:53]
	v_mfma_i32_16x16x64_i8 v[50:53], v[70:73], v[210:213], v[50:53]
	v_mfma_i32_16x16x64_i8 v[38:41], v[106:109], v[198:201], v[38:41]
	v_mfma_i32_16x16x64_i8 v[38:41], v[110:113], v[210:213], v[38:41]
	v_mfma_i32_16x16x64_i8 v[42:45], v[66:69], v[214:217], v[42:45]
	v_mfma_i32_16x16x64_i8 v[42:45], v[70:73], v[218:221], v[42:45]
	v_mfma_i32_16x16x64_i8 v[34:37], v[106:109], v[214:217], v[34:37]
	v_mfma_i32_16x16x64_i8 v[34:37], v[110:113], v[218:221], v[34:37]
	s_setprio 0
	s_setprio 1
	v_mfma_i32_16x16x64_i8 v[30:33], v[114:117], v[182:185], v[30:33]
	v_mfma_i32_16x16x64_i8 v[30:33], v[118:121], v[186:189], v[30:33]
	v_mfma_i32_16x16x64_i8 v[22:25], v[126:129], v[182:185], v[22:25]
	v_mfma_i32_16x16x64_i8 v[22:25], v[178:181], v[186:189], v[22:25]
	v_mfma_i32_16x16x64_i8 v[26:29], v[114:117], v[190:193], v[26:29]
	v_mfma_i32_16x16x64_i8 v[26:29], v[118:121], v[194:197], v[26:29]
	v_mfma_i32_16x16x64_i8 v[14:17], v[126:129], v[190:193], v[14:17]
	v_mfma_i32_16x16x64_i8 v[14:17], v[178:181], v[194:197], v[14:17]
	v_mfma_i32_16x16x64_i8 v[18:21], v[114:117], v[198:201], v[18:21]
	v_mfma_i32_16x16x64_i8 v[18:21], v[118:121], v[210:213], v[18:21]
	v_mfma_i32_16x16x64_i8 v[6:9], v[126:129], v[198:201], v[6:9]
	v_mfma_i32_16x16x64_i8 v[6:9], v[178:181], v[210:213], v[6:9]
	v_mfma_i32_16x16x64_i8 v[10:13], v[114:117], v[214:217], v[10:13]
	v_mfma_i32_16x16x64_i8 v[10:13], v[118:121], v[218:221], v[10:13]
	v_mfma_i32_16x16x64_i8 v[2:5], v[126:129], v[214:217], v[2:5]
	v_mfma_i32_16x16x64_i8 v[2:5], v[178:181], v[218:221], v[2:5]
	s_setprio 0
	s_barrier
; #define PG8_STAGE(bufoff, gbase, voff) do { _Pragma("unroll") for (int _i = 0; _i < 2; ++_i) \
;         __builtin_amdgcn_global_load_lds((const unsigned*)((const char*)(gbase) + (voff)[_i]), (PG8_LAS unsigned*)(lds + (bufoff) + ldsw + _i * 8192), 16, 0, 0); } while (0)
; #define PG8_LDA(dst, b, h) do { _Pragma("unroll") for (int m = 0; m < 4; ++m) _Pragma("unroll") for (int k = 0; k < 2; ++k) dst[m][k] = *(const PG8_LAS bf16x8*)(lds + PG8_SA(b, h) + aoff + m * 2048 + k * 1024); } while (0)
; #define PG8_LDB(dst, b, h) do { _Pragma("unroll") for (int n = 0; n < 2; ++n) _Pragma("unroll") for (int k = 0; k < 2; ++k) dst[n][k] = *(const PG8_LAS bf16x8*)(lds + PG8_SB(b, h) + boff + n * 2048 + k * 1024); } while (0)
; #define PG8_MMA(ai, bj, At, Bt) do { __builtin_amdgcn_s_setprio(1); _Pragma("unroll") for (int m = 0; m < 4; ++m) _Pragma("unroll") for (int n = 0; n < 2; ++n) _Pragma("unroll") for (int k = 0; k < 2; ++k) \
;         acc[ai][bj][m][n] = mma16<Epi::I8>(Bt[n][k], At[m][k], acc[ai][bj][m][n]); __builtin_amdgcn_s_setprio(0); } while (0)
; #define PG8_WAIT_V(n) asm volatile("s_waitcnt vmcnt(" #n ")" ::: "memory")
; #define PG8_WAIT_L(n) asm volatile("s_waitcnt lgkmcnt(" #n ")" ::: "memory")
; #define PG8_BAR __builtin_amdgcn_s_barrier()
; #define PG8_SCHED __builtin_amdgcn_sched_barrier(0)
; template <class Epi, class Sched, bool ALIGN_EPI = false, bool SP2 = false>
; __device__ __forceinline__ void gemm_phase(PG8_LAS unsigned char* lds, const Gemm g, const Sched& S, const Epi& E) {
;     ...
;             PG8_LDB(B0, 1, 0); PG8_LDB(B1, 1, 1); PG8_SCHED; PG8_LDA(At, 1, 0); PG8_STAGE(PG8_SA(0, 1), a2 + hstep, voffA);
;             PG8_WAIT_V(8); PG8_WAIT_L(0); PG8_BAR; PG8_MMA(0, 0, At, B0); PG8_MMA(0, 1, At, B1); PG8_BAR; PG8_SCHED;
;             PG8_LDA(At, 1, 1); PG8_STAGE(PG8_SB(1, 0), b3, voffB); PG8_STAGE(PG8_SB(1, 1), b3 + hstep, voffB); PG8_STAGE(PG8_SA(1, 0), a3, voffA);
;             PG8_WAIT_V(8); PG8_WAIT_L(0); PG8_BAR; PG8_MMA(1, 0, At, B0); PG8_MMA(1, 1, At, B1); PG8_BAR; PG8_SCHED;
	s_add_i32 s66, 0, 0x18000
	s_add_i32 s70, 0, 0x1c000
	v_add_u32_e32 v110, s66, v175
	v_add_u32_e32 v170, s70, v175
	ds_read_b128 v[66:69], v110
	ds_read_b128 v[70:73], v110 offset:1024
	ds_read_b128 v[106:109], v110 offset:2048
	ds_read_b128 v[110:113], v110 offset:3072
	ds_read_b128 v[114:117], v170
	ds_read_b128 v[118:121], v170 offset:1024
	ds_read_b128 v[126:129], v170 offset:2048
	ds_read_b128 v[178:181], v170 offset:3072
	s_add_u32 s8, vcc_lo, 0x40000
	s_addc_u32 s9, vcc_hi, 0
	s_mov_b32 m0, s80
	v_lshl_add_u64 v[226:227], s[8:9], 0, v[162:163]
	ds_read_b128 v[182:185], v177 offset:32768
	ds_read_b128 v[186:189], v177 offset:33792
	ds_read_b128 v[190:193], v177 offset:34816
	ds_read_b128 v[194:197], v177 offset:35840
	ds_read_b128 v[198:201], v177 offset:36864
	ds_read_b128 v[210:213], v177 offset:37888
	ds_read_b128 v[214:217], v177 offset:38912
	ds_read_b128 v[218:221], v177 offset:39936
	global_load_lds_dwordx4 v[226:227], off
	v_lshl_add_u64 v[226:227], s[8:9], 0, v[160:161]
	s_mov_b32 m0, s0
	s_nop 0
	global_load_lds_dwordx4 v[226:227], off
	s_waitcnt vmcnt(8)
	s_waitcnt lgkmcnt(0)
	s_barrier
	s_setprio 1
	s_waitcnt lgkmcnt(0)
	v_mfma_i32_16x16x64_i8 v[154:157], v[66:69], v[182:185], v[154:157]
	v_mfma_i32_16x16x64_i8 v[154:157], v[70:73], v[186:189], v[154:157]
	v_mfma_i32_16x16x64_i8 v[146:149], v[106:109], v[182:185], v[146:149]
	v_mfma_i32_16x16x64_i8 v[146:149], v[110:113], v[186:189], v[146:149]
	v_mfma_i32_16x16x64_i8 v[150:153], v[66:69], v[190:193], v[150:153]
	v_mfma_i32_16x16x64_i8 v[150:153], v[70:73], v[194:197], v[150:153]
	v_mfma_i32_16x16x64_i8 v[138:141], v[106:109], v[190:193], v[138:141]
	v_mfma_i32_16x16x64_i8 v[138:141], v[110:113], v[194:197], v[138:141]
	v_mfma_i32_16x16x64_i8 v[142:145], v[66:69], v[198:201], v[142:145]
	v_mfma_i32_16x16x64_i8 v[142:145], v[70:73], v[210:213], v[142:145]
	v_mfma_i32_16x16x64_i8 v[130:133], v[106:109], v[198:201], v[130:133]
	v_mfma_i32_16x16x64_i8 v[130:133], v[110:113], v[210:213], v[130:133]
	v_mfma_i32_16x16x64_i8 v[134:137], v[66:69], v[214:217], v[134:137]
	v_mfma_i32_16x16x64_i8 v[134:137], v[70:73], v[218:221], v[134:137]
	v_mfma_i32_16x16x64_i8 v[122:125], v[106:109], v[214:217], v[122:125]
	v_mfma_i32_16x16x64_i8 v[122:125], v[110:113], v[218:221], v[122:125]
	s_setprio 0
	s_setprio 1
	v_mfma_i32_16x16x64_i8 v[102:105], v[114:117], v[182:185], v[102:105]
	v_mfma_i32_16x16x64_i8 v[102:105], v[118:121], v[186:189], v[102:105]
	v_mfma_i32_16x16x64_i8 v[94:97], v[126:129], v[182:185], v[94:97]
	v_mfma_i32_16x16x64_i8 v[94:97], v[178:181], v[186:189], v[94:97]
	v_mfma_i32_16x16x64_i8 v[98:101], v[114:117], v[190:193], v[98:101]
	v_mfma_i32_16x16x64_i8 v[98:101], v[118:121], v[194:197], v[98:101]
	v_mfma_i32_16x16x64_i8 v[86:89], v[126:129], v[190:193], v[86:89]
	v_mfma_i32_16x16x64_i8 v[86:89], v[178:181], v[194:197], v[86:89]
	v_mfma_i32_16x16x64_i8 v[90:93], v[114:117], v[198:201], v[90:93]
	v_mfma_i32_16x16x64_i8 v[90:93], v[118:121], v[210:213], v[90:93]
	v_mfma_i32_16x16x64_i8 v[78:81], v[126:129], v[198:201], v[78:81]
	v_mfma_i32_16x16x64_i8 v[78:81], v[178:181], v[210:213], v[78:81]
	v_mfma_i32_16x16x64_i8 v[82:85], v[114:117], v[214:217], v[82:85]
	v_mfma_i32_16x16x64_i8 v[82:85], v[118:121], v[218:221], v[82:85]
	v_mfma_i32_16x16x64_i8 v[74:77], v[126:129], v[214:217], v[74:77]
	v_mfma_i32_16x16x64_i8 v[74:77], v[178:181], v[218:221], v[74:77]
	s_setprio 0
	s_barrier
	s_add_i32 s8, s66, s81
	v_lshl_add_u64 v[168:169], v[168:169], 0, s[92:93]
	s_mov_b32 m0, s8
	ds_read_b128 v[182:185], v177 offset:49152
	ds_read_b128 v[186:189], v177 offset:50176
	ds_read_b128 v[190:193], v177 offset:51200
	ds_read_b128 v[194:197], v177 offset:52224
	ds_read_b128 v[198:201], v177 offset:53248
	ds_read_b128 v[210:213], v177 offset:54272
	ds_read_b128 v[214:217], v177 offset:55296
	ds_read_b128 v[218:221], v177 offset:56320
	global_load_lds_dwordx4 v[168:169], off
	s_add_i32 m0, s8, 0x2000
	s_add_u32 s8, s96, 0x40080
	v_lshl_add_u64 v[168:169], v[206:207], 0, s[92:93]
	s_addc_u32 s9, s97, 0
	s_add_i32 s66, s70, s81
	global_load_lds_dwordx4 v[168:169], off
	v_lshl_add_u64 v[168:169], s[8:9], 0, v[0:1]
	s_mov_b32 m0, s66
	s_nop 0
	global_load_lds_dwordx4 v[168:169], off
	v_lshl_add_u64 v[168:169], s[8:9], 0, v[158:159]
	s_add_i32 m0, s66, 0x2000
	s_nop 0
	global_load_lds_dwordx4 v[168:169], off
	v_lshl_add_u64 v[168:169], v[222:223], 0, s[92:93]
	s_mov_b32 m0, s13
	s_nop 0
	global_load_lds_dwordx4 v[168:169], off
	v_lshl_add_u64 v[168:169], v[224:225], 0, s[92:93]
	s_mov_b32 m0, s12
	s_nop 0
	global_load_lds_dwordx4 v[168:169], off
	s_waitcnt vmcnt(8)
	s_waitcnt lgkmcnt(0)
	s_barrier
	s_setprio 1
	s_waitcnt lgkmcnt(0)
	v_mfma_i32_16x16x64_i8 v[62:65], v[66:69], v[182:185], v[62:65]
	v_mfma_i32_16x16x64_i8 v[62:65], v[70:73], v[186:189], v[62:65]
	v_mfma_i32_16x16x64_i8 v[54:57], v[106:109], v[182:185], v[54:57]
	v_mfma_i32_16x16x64_i8 v[54:57], v[110:113], v[186:189], v[54:57]
	v_mfma_i32_16x16x64_i8 v[58:61], v[66:69], v[190:193], v[58:61]
	v_mfma_i32_16x16x64_i8 v[58:61], v[70:73], v[194:197], v[58:61]
	v_mfma_i32_16x16x64_i8 v[46:49], v[106:109], v[190:193], v[46:49]
	v_mfma_i32_16x16x64_i8 v[46:49], v[110:113], v[194:197], v[46:49]
	v_mfma_i32_16x16x64_i8 v[50:53], v[66:69], v[198:201], v[50:53]
	v_mfma_i32_16x16x64_i8 v[50:53], v[70:73], v[210:213], v[50:53]
	v_mfma_i32_16x16x64_i8 v[38:41], v[106:109], v[198:201], v[38:41]
	v_mfma_i32_16x16x64_i8 v[38:41], v[110:113], v[210:213], v[38:41]
	v_mfma_i32_16x16x64_i8 v[42:45], v[66:69], v[214:217], v[42:45]
	v_mfma_i32_16x16x64_i8 v[42:45], v[70:73], v[218:221], v[42:45]
	v_mfma_i32_16x16x64_i8 v[34:37], v[106:109], v[214:217], v[34:37]
	v_mfma_i32_16x16x64_i8 v[34:37], v[110:113], v[218:221], v[34:37]
	s_setprio 0
	s_setprio 1
	v_mfma_i32_16x16x64_i8 v[30:33], v[114:117], v[182:185], v[30:33]
	v_mfma_i32_16x16x64_i8 v[30:33], v[118:121], v[186:189], v[30:33]
	v_mfma_i32_16x16x64_i8 v[22:25], v[126:129], v[182:185], v[22:25]
	v_mfma_i32_16x16x64_i8 v[22:25], v[178:181], v[186:189], v[22:25]
	v_mfma_i32_16x16x64_i8 v[26:29], v[114:117], v[190:193], v[26:29]
	v_mfma_i32_16x16x64_i8 v[26:29], v[118:121], v[194:197], v[26:29]
	v_mfma_i32_16x16x64_i8 v[14:17], v[126:129], v[190:193], v[14:17]
	v_mfma_i32_16x16x64_i8 v[14:17], v[178:181], v[194:197], v[14:17]
	v_mfma_i32_16x16x64_i8 v[18:21], v[114:117], v[198:201], v[18:21]
	v_mfma_i32_16x16x64_i8 v[18:21], v[118:121], v[210:213], v[18:21]
	v_mfma_i32_16x16x64_i8 v[6:9], v[126:129], v[198:201], v[6:9]
	v_mfma_i32_16x16x64_i8 v[6:9], v[178:181], v[210:213], v[6:9]
	v_mfma_i32_16x16x64_i8 v[10:13], v[114:117], v[214:217], v[10:13]
	v_mfma_i32_16x16x64_i8 v[10:13], v[118:121], v[218:221], v[10:13]
	v_mfma_i32_16x16x64_i8 v[2:5], v[126:129], v[214:217], v[2:5]
	v_mfma_i32_16x16x64_i8 v[2:5], v[178:181], v[218:221], v[2:5]
	s_setprio 0
	s_barrier
	s_add_i32 s10, s10, 2
	s_add_u32 s69, s69, 0x100
	s_addc_u32 s68, s68, 0
	s_cmp_gt_u32 s10, 13
	s_mov_b64 s[8:9], s[84:85]
	s_cbranch_scc0 .LBB0_291

; #define PG8_STAGE(bufoff, gbase, voff) do { _Pragma("unroll") for (int _i = 0; _i < 2; ++_i) \
;         __builtin_amdgcn_global_load_lds((const unsigned*)((const char*)(gbase) + (voff)[_i]), (PG8_LAS unsigned*)(lds + (bufoff) + ldsw + _i * 8192), 16, 0, 0); } while (0)
; #define PG8_LDA(dst, b, h) do { _Pragma("unroll") for (int m = 0; m < 4; ++m) _Pragma("unroll") for (int k = 0; k < 2; ++k) dst[m][k] = *(const PG8_LAS bf16x8*)(lds + PG8_SA(b, h) + aoff + m * 2048 + k * 1024); } while (0)
; #define PG8_LDB(dst, b, h) do { _Pragma("unroll") for (int n = 0; n < 2; ++n) _Pragma("unroll") for (int k = 0; k < 2; ++k) dst[n][k] = *(const PG8_LAS bf16x8*)(lds + PG8_SB(b, h) + boff + n * 2048 + k * 1024); } while (0)
; #define PG8_MMA(ai, bj, At, Bt) do { __builtin_amdgcn_s_setprio(1); _Pragma("unroll") for (int m = 0; m < 4; ++m) _Pragma("unroll") for (int n = 0; n < 2; ++n) _Pragma("unroll") for (int k = 0; k < 2; ++k) \
;         acc[ai][bj][m][n] = mma16<Epi::I8>(Bt[n][k], At[m][k], acc[ai][bj][m][n]); __builtin_amdgcn_s_setprio(0); } while (0)
; #define PG8_WAIT_V(n) asm volatile("s_waitcnt vmcnt(" #n ")" ::: "memory")
; template <class Epi, class Sched, bool ALIGN_EPI = false, bool SP2 = false>
; __device__ __forceinline__ void gemm_phase(PG8_LAS unsigned char* lds, const Gemm g, const Sched& S, const Epi& E) {
;     ...
;         const bool has_next = S.next(ui + 1, nxt);
;         const char* nA = has_next ? (const char*)g.A + (size_t)nxt.pm * tstep : cA; const char* nB = has_next ? (const char*)g.Bt + (size_t)nxt.pn * tstep : cB;
;         for (int t = 0; t < nt; t += 2) {
;             const bool last = (t == nt - 2);
;             const char* a1 = cA + (size_t)(t + 1) * kstep;
;             const char* a2 = last ? nA : cA + (size_t)(t + 2) * kstep; const char* b2 = last ? nB : cB + (size_t)(t + 2) * kstep;
;             const char* a3 = a2 + kstep; const char* b3 = b2 + kstep;
;             if (last && has_next) S.a_ready(nxt);
;             if constexpr (SP2) {
;             PG8_LDB(B0, 0, 0); PG8_LDB(B1, 0, 1); PG8_SCHED; PG8_LDA(At, 0, 0); PG8_STAGE(PG8_SA(1, 1), a1 + hstep, voffA);
;             PG8_WAIT_V(8); PG8_WAIT_L(0); PG8_BAR; PG8_MMA(0, 0, At, B0); PG8_MMA(0, 1, At, B1); PG8_BAR; PG8_SCHED;
;             PG8_LDA(At, 0, 1); PG8_STAGE(PG8_SB(0, 0), b2, voffB); PG8_STAGE(PG8_SB(0, 1), b2 + hstep, voffB); PG8_STAGE(PG8_SA(0, 0), a2, voffA);
.Lpeel327:
	s_add_u32 s68, s8, 0x100
	s_addc_u32 s69, s9, 0
	s_add_i32 s84, 0, 0x10000
	s_cmp_eq_u32 s4, 28
	s_cselect_b32 vcc_hi, s1, s69
	s_cselect_b32 vcc_lo, s5, s68
	v_add_u32_e32 v0, s84, v188
	s_cselect_b32 s71, s7, s96
	s_cselect_b32 s70, s85, s97
	s_add_i32 s10, 0, 0x14000
	ds_read_b128 v[52:55], v0
	ds_read_b128 v[56:59], v0 offset:1024
	ds_read_b128 v[76:79], v0 offset:2048
	ds_read_b128 v[80:83], v0 offset:3072
	v_add_u32_e32 v0, s10, v188
	ds_read_b128 v[116:119], v0
	ds_read_b128 v[120:123], v0 offset:1024
	ds_read_b128 v[168:171], v0 offset:2048
	ds_read_b128 v[172:175], v0 offset:3072
	v_lshl_add_u64 v[2:3], s[8:9], 0, v[164:165]
	s_add_i32 m0, s58, 0xc000
	ds_read_b128 v[176:179], v189
	ds_read_b128 v[180:183], v189 offset:1024
	ds_read_b128 v[190:193], v189 offset:2048
	ds_read_b128 v[194:197], v189 offset:3072
	ds_read_b128 v[198:201], v189 offset:4096
	ds_read_b128 v[210:213], v189 offset:5120
	ds_read_b128 v[214:217], v189 offset:6144
	ds_read_b128 v[218:221], v189 offset:7168
	global_load_lds_dwordx4 v[2:3], off
	v_lshl_add_u64 v[2:3], s[8:9], 0, v[166:167]
	s_add_i32 m0, s58, 0xe000
	s_nop 0
	global_load_lds_dwordx4 v[2:3], off
	s_waitcnt vmcnt(8)
	s_waitcnt lgkmcnt(0)
	s_barrier
	s_setprio 1
	s_waitcnt lgkmcnt(0)
	v_mfma_f32_16x16x32_bf16 v[152:155], v[52:55], v[176:179], 0
	v_mfma_f32_16x16x32_bf16 v[152:155], v[56:59], v[180:183], v[152:155]
	v_mfma_f32_16x16x32_bf16 v[144:147], v[76:79], v[176:179], 0
	v_mfma_f32_16x16x32_bf16 v[144:147], v[80:83], v[180:183], v[144:147]
	v_mfma_f32_16x16x32_bf16 v[148:151], v[52:55], v[190:193], 0
	v_mfma_f32_16x16x32_bf16 v[148:151], v[56:59], v[194:197], v[148:151]
	v_mfma_f32_16x16x32_bf16 v[140:143], v[76:79], v[190:193], 0
	v_mfma_f32_16x16x32_bf16 v[140:143], v[80:83], v[194:197], v[140:143]
	v_mfma_f32_16x16x32_bf16 v[136:139], v[52:55], v[198:201], 0
	v_mfma_f32_16x16x32_bf16 v[136:139], v[56:59], v[210:213], v[136:139]
	v_mfma_f32_16x16x32_bf16 v[132:135], v[76:79], v[198:201], 0
	v_mfma_f32_16x16x32_bf16 v[132:135], v[80:83], v[210:213], v[132:135]
	v_mfma_f32_16x16x32_bf16 v[128:131], v[52:55], v[214:217], 0
	v_mfma_f32_16x16x32_bf16 v[128:131], v[56:59], v[218:221], v[128:131]
	v_mfma_f32_16x16x32_bf16 v[124:127], v[76:79], v[214:217], 0
	v_mfma_f32_16x16x32_bf16 v[124:127], v[80:83], v[218:221], v[124:127]
	s_setprio 0
	s_setprio 1
	v_mfma_f32_16x16x32_bf16 v[112:115], v[116:119], v[176:179], 0
	v_mfma_f32_16x16x32_bf16 v[112:115], v[120:123], v[180:183], v[112:115]
	v_mfma_f32_16x16x32_bf16 v[104:107], v[168:171], v[176:179], 0
	v_mfma_f32_16x16x32_bf16 v[104:107], v[172:175], v[180:183], v[104:107]
	v_mfma_f32_16x16x32_bf16 v[108:111], v[116:119], v[190:193], 0
	v_mfma_f32_16x16x32_bf16 v[108:111], v[120:123], v[194:197], v[108:111]
	v_mfma_f32_16x16x32_bf16 v[100:103], v[168:171], v[190:193], 0
	v_mfma_f32_16x16x32_bf16 v[100:103], v[172:175], v[194:197], v[100:103]
	v_mfma_f32_16x16x32_bf16 v[96:99], v[116:119], v[198:201], 0
	v_mfma_f32_16x16x32_bf16 v[96:99], v[120:123], v[210:213], v[96:99]
	v_mfma_f32_16x16x32_bf16 v[92:95], v[168:171], v[198:201], 0
	v_mfma_f32_16x16x32_bf16 v[92:95], v[172:175], v[210:213], v[92:95]
	v_mfma_f32_16x16x32_bf16 v[88:91], v[116:119], v[214:217], 0
	v_mfma_f32_16x16x32_bf16 v[88:91], v[120:123], v[218:221], v[88:91]
	v_mfma_f32_16x16x32_bf16 v[84:87], v[168:171], v[214:217], 0
	v_mfma_f32_16x16x32_bf16 v[84:87], v[172:175], v[218:221], v[84:87]
	s_setprio 0
	s_barrier
	s_add_i32 s8, s84, s80
	v_lshl_add_u64 v[184:185], s[70:71], 0, v[158:159]
	s_mov_b32 m0, s8
	ds_read_b128 v[176:179], v189 offset:16384
	ds_read_b128 v[180:183], v189 offset:17408
	ds_read_b128 v[190:193], v189 offset:18432
	ds_read_b128 v[194:197], v189 offset:19456
	ds_read_b128 v[198:201], v189 offset:20480
	ds_read_b128 v[210:213], v189 offset:21504
	ds_read_b128 v[214:217], v189 offset:22528
	ds_read_b128 v[218:221], v189 offset:23552
	global_load_lds_dwordx4 v[184:185], off
	s_add_i32 m0, s8, 0x2000
	s_add_u32 s8, s70, 0x80000
	v_lshl_add_u64 v[206:207], s[70:71], 0, v[162:163]
	s_addc_u32 s9, s71, 0
	s_add_i32 s10, s10, s80
	global_load_lds_dwordx4 v[206:207], off
	v_lshl_add_u64 v[2:3], s[8:9], 0, v[158:159]
	s_mov_b32 m0, s10
	v_lshl_add_u64 v[222:223], vcc, 0, v[156:157]
	global_load_lds_dwordx4 v[2:3], off
	v_lshl_add_u64 v[2:3], s[8:9], 0, v[162:163]
	s_add_i32 m0, s10, 0x2000
	v_lshl_add_u64 v[224:225], vcc, 0, v[160:161]
	global_load_lds_dwordx4 v[2:3], off
	s_mov_b32 m0, s58
	s_nop 0
	global_load_lds_dwordx4 v[222:223], off
	s_mov_b32 m0, s12
	s_nop 0
	global_load_lds_dwordx4 v[224:225], off
	s_waitcnt vmcnt(8)
	s_waitcnt lgkmcnt(0)
	s_barrier
; #define PG8_STAGE(bufoff, gbase, voff) do { _Pragma("unroll") for (int _i = 0; _i < 2; ++_i) \
;         __builtin_amdgcn_global_load_lds((const unsigned*)((const char*)(gbase) + (voff)[_i]), (PG8_LAS unsigned*)(lds + (bufoff) + ldsw + _i * 8192), 16, 0, 0); } while (0)
; #define PG8_LDA(dst, b, h) do { _Pragma("unroll") for (int m = 0; m < 4; ++m) _Pragma("unroll") for (int k = 0; k < 2; ++k) dst[m][k] = *(const PG8_LAS bf16x8*)(lds + PG8_SA(b, h) + aoff + m * 2048 + k * 1024); } while (0)
; #define PG8_LDB(dst, b, h) do { _Pragma("unroll") for (int n = 0; n < 2; ++n) _Pragma("unroll") for (int k = 0; k < 2; ++k) dst[n][k] = *(const PG8_LAS bf16x8*)(lds + PG8_SB(b, h) + boff + n * 2048 + k * 1024); } while (0)
; #define PG8_MMA(ai, bj, At, Bt) do { __builtin_amdgcn_s_setprio(1); _Pragma("unroll") for (int m = 0; m < 4; ++m) _Pragma("unroll") for (int n = 0; n < 2; ++n) _Pragma("unroll") for (int k = 0; k < 2; ++k) \
;         acc[ai][bj][m][n] = mma16<Epi::I8>(Bt[n][k], At[m][k], acc[ai][bj][m][n]); __builtin_amdgcn_s_setprio(0); } while (0)
; #define PG8_WAIT_V(n) asm volatile("s_waitcnt vmcnt(" #n ")" ::: "memory")
; #define PG8_WAIT_L(n) asm volatile("s_waitcnt lgkmcnt(" #n ")" ::: "memory")
; #define PG8_BAR __builtin_amdgcn_s_barrier()
; #define PG8_SCHED __builtin_amdgcn_sched_barrier(0)
; template <class Epi, class Sched, bool ALIGN_EPI = false, bool SP2 = false>
; __device__ __forceinline__ void gemm_phase(PG8_LAS unsigned char* lds, const Gemm g, const Sched& S, const Epi& E) {
;     ...
;             PG8_LDA(At, 0, 1); PG8_STAGE(PG8_SB(0, 0), b2, voffB); PG8_STAGE(PG8_SB(0, 1), b2 + hstep, voffB); PG8_STAGE(PG8_SA(0, 0), a2, voffA);
;             PG8_WAIT_V(8); PG8_WAIT_L(0); PG8_BAR; PG8_MMA(1, 0, At, B0); PG8_MMA(1, 1, At, B1); PG8_BAR; PG8_SCHED;
;             PG8_LDB(B0, 1, 0); PG8_LDB(B1, 1, 1); PG8_SCHED; PG8_LDA(At, 1, 0); PG8_STAGE(PG8_SA(0, 1), a2 + hstep, voffA);
;             PG8_WAIT_V(8); PG8_WAIT_L(0); PG8_BAR; PG8_MMA(0, 0, At, B0); PG8_MMA(0, 1, At, B1); PG8_BAR; PG8_SCHED;
	s_setprio 1
	s_waitcnt lgkmcnt(0)
	v_mfma_f32_16x16x32_bf16 v[72:75], v[52:55], v[176:179], 0
	v_mfma_f32_16x16x32_bf16 v[72:75], v[56:59], v[180:183], v[72:75]
	v_mfma_f32_16x16x32_bf16 v[64:67], v[76:79], v[176:179], 0
	v_mfma_f32_16x16x32_bf16 v[64:67], v[80:83], v[180:183], v[64:67]
	v_mfma_f32_16x16x32_bf16 v[68:71], v[52:55], v[190:193], 0
	v_mfma_f32_16x16x32_bf16 v[68:71], v[56:59], v[194:197], v[68:71]
	v_mfma_f32_16x16x32_bf16 v[60:63], v[76:79], v[190:193], 0
	v_mfma_f32_16x16x32_bf16 v[60:63], v[80:83], v[194:197], v[60:63]
	v_mfma_f32_16x16x32_bf16 v[48:51], v[52:55], v[198:201], 0
	v_mfma_f32_16x16x32_bf16 v[48:51], v[56:59], v[210:213], v[48:51]
	v_mfma_f32_16x16x32_bf16 v[44:47], v[76:79], v[198:201], 0
	v_mfma_f32_16x16x32_bf16 v[44:47], v[80:83], v[210:213], v[44:47]
	v_mfma_f32_16x16x32_bf16 v[40:43], v[52:55], v[214:217], 0
	v_mfma_f32_16x16x32_bf16 v[40:43], v[56:59], v[218:221], v[40:43]
	v_mfma_f32_16x16x32_bf16 v[36:39], v[76:79], v[214:217], 0
	v_mfma_f32_16x16x32_bf16 v[36:39], v[80:83], v[218:221], v[36:39]
	s_setprio 0
	s_setprio 1
	v_mfma_f32_16x16x32_bf16 v[32:35], v[116:119], v[176:179], 0
	v_mfma_f32_16x16x32_bf16 v[32:35], v[120:123], v[180:183], v[32:35]
	v_mfma_f32_16x16x32_bf16 v[24:27], v[168:171], v[176:179], 0
	v_mfma_f32_16x16x32_bf16 v[24:27], v[172:175], v[180:183], v[24:27]
	v_mfma_f32_16x16x32_bf16 v[28:31], v[116:119], v[190:193], 0
	v_mfma_f32_16x16x32_bf16 v[28:31], v[120:123], v[194:197], v[28:31]
	v_mfma_f32_16x16x32_bf16 v[20:23], v[168:171], v[190:193], 0
	v_mfma_f32_16x16x32_bf16 v[20:23], v[172:175], v[194:197], v[20:23]
	v_mfma_f32_16x16x32_bf16 v[16:19], v[116:119], v[198:201], 0
	v_mfma_f32_16x16x32_bf16 v[16:19], v[120:123], v[210:213], v[16:19]
	v_mfma_f32_16x16x32_bf16 v[12:15], v[168:171], v[198:201], 0
	v_mfma_f32_16x16x32_bf16 v[12:15], v[172:175], v[210:213], v[12:15]
	v_mfma_f32_16x16x32_bf16 v[8:11], v[116:119], v[214:217], 0
	v_mfma_f32_16x16x32_bf16 v[8:11], v[120:123], v[218:221], v[8:11]
	v_mfma_f32_16x16x32_bf16 v[2:5], v[168:171], v[214:217], 0
	v_mfma_f32_16x16x32_bf16 v[2:5], v[172:175], v[218:221], v[2:5]
	s_setprio 0
	s_barrier
	s_add_i32 s10, 0, 0x18000
	v_add_u32_e32 v0, s10, v188
	s_add_i32 s11, 0, 0x1c000
	ds_read_b128 v[52:55], v0
	ds_read_b128 v[56:59], v0 offset:1024
	ds_read_b128 v[76:79], v0 offset:2048
	ds_read_b128 v[80:83], v0 offset:3072
	v_add_u32_e32 v0, s11, v188
	ds_read_b128 v[116:119], v0
	ds_read_b128 v[120:123], v0 offset:1024
	ds_read_b128 v[168:171], v0 offset:2048
	ds_read_b128 v[172:175], v0 offset:3072
	s_add_u32 s8, vcc_lo, 0x80000
	s_addc_u32 s9, vcc_hi, 0
	s_mov_b32 m0, s13
	v_lshl_add_u64 v[6:7], s[8:9], 0, v[156:157]
	ds_read_b128 v[176:179], v189 offset:32768
	ds_read_b128 v[180:183], v189 offset:33792
	ds_read_b128 v[190:193], v189 offset:34816
	ds_read_b128 v[194:197], v189 offset:35840
	ds_read_b128 v[198:201], v189 offset:36864
	ds_read_b128 v[210:213], v189 offset:37888
	ds_read_b128 v[214:217], v189 offset:38912
	ds_read_b128 v[218:221], v189 offset:39936
	global_load_lds_dwordx4 v[6:7], off
	v_lshl_add_u64 v[6:7], s[8:9], 0, v[160:161]
	s_mov_b32 m0, s66
	s_nop 0
	global_load_lds_dwordx4 v[6:7], off
	s_waitcnt vmcnt(8)
	s_waitcnt lgkmcnt(0)
	s_barrier
	s_setprio 1
	s_waitcnt lgkmcnt(0)
	v_mfma_f32_16x16x32_bf16 v[152:155], v[52:55], v[176:179], v[152:155]
	v_mfma_f32_16x16x32_bf16 v[152:155], v[56:59], v[180:183], v[152:155]
	v_mfma_f32_16x16x32_bf16 v[144:147], v[76:79], v[176:179], v[144:147]
	v_mfma_f32_16x16x32_bf16 v[144:147], v[80:83], v[180:183], v[144:147]
	v_mfma_f32_16x16x32_bf16 v[148:151], v[52:55], v[190:193], v[148:151]
	v_mfma_f32_16x16x32_bf16 v[148:151], v[56:59], v[194:197], v[148:151]
	v_mfma_f32_16x16x32_bf16 v[140:143], v[76:79], v[190:193], v[140:143]
	v_mfma_f32_16x16x32_bf16 v[140:143], v[80:83], v[194:197], v[140:143]
	v_mfma_f32_16x16x32_bf16 v[136:139], v[52:55], v[198:201], v[136:139]
	v_mfma_f32_16x16x32_bf16 v[136:139], v[56:59], v[210:213], v[136:139]
	v_mfma_f32_16x16x32_bf16 v[132:135], v[76:79], v[198:201], v[132:135]
	v_mfma_f32_16x16x32_bf16 v[132:135], v[80:83], v[210:213], v[132:135]
	v_mfma_f32_16x16x32_bf16 v[128:131], v[52:55], v[214:217], v[128:131]
	v_mfma_f32_16x16x32_bf16 v[128:131], v[56:59], v[218:221], v[128:131]
	v_mfma_f32_16x16x32_bf16 v[124:127], v[76:79], v[214:217], v[124:127]
	v_mfma_f32_16x16x32_bf16 v[124:127], v[80:83], v[218:221], v[124:127]
	s_setprio 0
	s_setprio 1
	v_mfma_f32_16x16x32_bf16 v[112:115], v[116:119], v[176:179], v[112:115]
	v_mfma_f32_16x16x32_bf16 v[112:115], v[120:123], v[180:183], v[112:115]
	v_mfma_f32_16x16x32_bf16 v[104:107], v[168:171], v[176:179], v[104:107]
	v_mfma_f32_16x16x32_bf16 v[104:107], v[172:175], v[180:183], v[104:107]
	v_mfma_f32_16x16x32_bf16 v[108:111], v[116:119], v[190:193], v[108:111]
	v_mfma_f32_16x16x32_bf16 v[108:111], v[120:123], v[194:197], v[108:111]
	v_mfma_f32_16x16x32_bf16 v[100:103], v[168:171], v[190:193], v[100:103]
	v_mfma_f32_16x16x32_bf16 v[100:103], v[172:175], v[194:197], v[100:103]
	v_mfma_f32_16x16x32_bf16 v[96:99], v[116:119], v[198:201], v[96:99]
	v_mfma_f32_16x16x32_bf16 v[96:99], v[120:123], v[210:213], v[96:99]
	v_mfma_f32_16x16x32_bf16 v[92:95], v[168:171], v[198:201], v[92:95]
	v_mfma_f32_16x16x32_bf16 v[92:95], v[172:175], v[210:213], v[92:95]
	v_mfma_f32_16x16x32_bf16 v[88:91], v[116:119], v[214:217], v[88:91]
	v_mfma_f32_16x16x32_bf16 v[88:91], v[120:123], v[218:221], v[88:91]
	v_mfma_f32_16x16x32_bf16 v[84:87], v[168:171], v[214:217], v[84:87]
	v_mfma_f32_16x16x32_bf16 v[84:87], v[172:175], v[218:221], v[84:87]
	s_setprio 0
	s_barrier
; #define PG8_STAGE(bufoff, gbase, voff) do { _Pragma("unroll") for (int _i = 0; _i < 2; ++_i) \
;         __builtin_amdgcn_global_load_lds((const unsigned*)((const char*)(gbase) + (voff)[_i]), (PG8_LAS unsigned*)(lds + (bufoff) + ldsw + _i * 8192), 16, 0, 0); } while (0)
; #define PG8_LDA(dst, b, h) do { _Pragma("unroll") for (int m = 0; m < 4; ++m) _Pragma("unroll") for (int k = 0; k < 2; ++k) dst[m][k] = *(const PG8_LAS bf16x8*)(lds + PG8_SA(b, h) + aoff + m * 2048 + k * 1024); } while (0)
; #define PG8_MMA(ai, bj, At, Bt) do { __builtin_amdgcn_s_setprio(1); _Pragma("unroll") for (int m = 0; m < 4; ++m) _Pragma("unroll") for (int n = 0; n < 2; ++n) _Pragma("unroll") for (int k = 0; k < 2; ++k) \
;         acc[ai][bj][m][n] = mma16<Epi::I8>(Bt[n][k], At[m][k], acc[ai][bj][m][n]); __builtin_amdgcn_s_setprio(0); } while (0)
; #define PG8_WAIT_V(n) asm volatile("s_waitcnt vmcnt(" #n ")" ::: "memory")
; #define PG8_WAIT_L(n) asm volatile("s_waitcnt lgkmcnt(" #n ")" ::: "memory")
; #define PG8_BAR __builtin_amdgcn_s_barrier()
; #define PG8_SCHED __builtin_amdgcn_sched_barrier(0)
; template <class Epi, class Sched, bool ALIGN_EPI = false, bool SP2 = false>
; __device__ __forceinline__ void gemm_phase(PG8_LAS unsigned char* lds, const Gemm g, const Sched& S, const Epi& E) {
;     ...
;         for (int t = 0; t < nt; t += 2) {
;     ...
;             PG8_WAIT_V(8); PG8_WAIT_L(0); PG8_BAR; PG8_MMA(0, 0, At, B0); PG8_MMA(0, 1, At, B1); PG8_BAR; PG8_SCHED;
;             PG8_LDA(At, 1, 1); PG8_STAGE(PG8_SB(1, 0), b3, voffB); PG8_STAGE(PG8_SB(1, 1), b3 + hstep, voffB); PG8_STAGE(PG8_SA(1, 0), a3, voffA);
;             PG8_WAIT_V(8); PG8_WAIT_L(0); PG8_BAR; PG8_MMA(1, 0, At, B0); PG8_MMA(1, 1, At, B1); PG8_BAR; PG8_SCHED;
	s_add_i32 s8, s10, s80
	v_lshl_add_u64 v[6:7], v[184:185], 0, s[92:93]
	s_mov_b32 m0, s8
	ds_read_b128 v[176:179], v189 offset:49152
	ds_read_b128 v[180:183], v189 offset:50176
	ds_read_b128 v[190:193], v189 offset:51200
	ds_read_b128 v[194:197], v189 offset:52224
	ds_read_b128 v[198:201], v189 offset:53248
	ds_read_b128 v[210:213], v189 offset:54272
	ds_read_b128 v[214:217], v189 offset:55296
	ds_read_b128 v[218:221], v189 offset:56320
	global_load_lds_dwordx4 v[6:7], off
	s_add_i32 m0, s8, 0x2000
	s_add_u32 s8, s70, 0x80080
	v_lshl_add_u64 v[6:7], v[206:207], 0, s[92:93]
	s_addc_u32 s9, s71, 0
	s_add_i32 s10, s11, s80
	global_load_lds_dwordx4 v[6:7], off
	v_lshl_add_u64 v[6:7], s[8:9], 0, v[158:159]
	s_mov_b32 m0, s10
	s_nop 0
	global_load_lds_dwordx4 v[6:7], off
	v_lshl_add_u64 v[6:7], s[8:9], 0, v[162:163]
	s_add_i32 m0, s10, 0x2000
	s_nop 0
	global_load_lds_dwordx4 v[6:7], off
	v_lshl_add_u64 v[6:7], v[222:223], 0, s[92:93]
	s_mov_b32 m0, s67
	s_nop 0
	global_load_lds_dwordx4 v[6:7], off
	v_lshl_add_u64 v[6:7], v[224:225], 0, s[92:93]
	s_mov_b32 m0, s81
	s_nop 0
	global_load_lds_dwordx4 v[6:7], off
	s_waitcnt vmcnt(8)
	s_waitcnt lgkmcnt(0)
	s_barrier
	s_setprio 1
	s_waitcnt lgkmcnt(0)
	v_mfma_f32_16x16x32_bf16 v[72:75], v[52:55], v[176:179], v[72:75]
	v_mfma_f32_16x16x32_bf16 v[72:75], v[56:59], v[180:183], v[72:75]
	v_mfma_f32_16x16x32_bf16 v[64:67], v[76:79], v[176:179], v[64:67]
	v_mfma_f32_16x16x32_bf16 v[64:67], v[80:83], v[180:183], v[64:67]
	v_mfma_f32_16x16x32_bf16 v[68:71], v[52:55], v[190:193], v[68:71]
	v_mfma_f32_16x16x32_bf16 v[68:71], v[56:59], v[194:197], v[68:71]
	v_mfma_f32_16x16x32_bf16 v[60:63], v[76:79], v[190:193], v[60:63]
	v_mfma_f32_16x16x32_bf16 v[60:63], v[80:83], v[194:197], v[60:63]
	v_mfma_f32_16x16x32_bf16 v[48:51], v[52:55], v[198:201], v[48:51]
	v_mfma_f32_16x16x32_bf16 v[48:51], v[56:59], v[210:213], v[48:51]
	v_mfma_f32_16x16x32_bf16 v[44:47], v[76:79], v[198:201], v[44:47]
	v_mfma_f32_16x16x32_bf16 v[44:47], v[80:83], v[210:213], v[44:47]
	v_mfma_f32_16x16x32_bf16 v[40:43], v[52:55], v[214:217], v[40:43]
	v_mfma_f32_16x16x32_bf16 v[40:43], v[56:59], v[218:221], v[40:43]
	v_mfma_f32_16x16x32_bf16 v[36:39], v[76:79], v[214:217], v[36:39]
	v_mfma_f32_16x16x32_bf16 v[36:39], v[80:83], v[218:221], v[36:39]
	s_setprio 0
	s_setprio 1
	v_mfma_f32_16x16x32_bf16 v[32:35], v[116:119], v[176:179], v[32:35]
	v_mfma_f32_16x16x32_bf16 v[32:35], v[120:123], v[180:183], v[32:35]
	v_mfma_f32_16x16x32_bf16 v[24:27], v[168:171], v[176:179], v[24:27]
	v_mfma_f32_16x16x32_bf16 v[24:27], v[172:175], v[180:183], v[24:27]
	v_mfma_f32_16x16x32_bf16 v[28:31], v[116:119], v[190:193], v[28:31]
	v_mfma_f32_16x16x32_bf16 v[28:31], v[120:123], v[194:197], v[28:31]
	v_mfma_f32_16x16x32_bf16 v[20:23], v[168:171], v[190:193], v[20:23]
	v_mfma_f32_16x16x32_bf16 v[20:23], v[172:175], v[194:197], v[20:23]
	v_mfma_f32_16x16x32_bf16 v[16:19], v[116:119], v[198:201], v[16:19]
	v_mfma_f32_16x16x32_bf16 v[16:19], v[120:123], v[210:213], v[16:19]
	v_mfma_f32_16x16x32_bf16 v[12:15], v[168:171], v[198:201], v[12:15]
	v_mfma_f32_16x16x32_bf16 v[12:15], v[172:175], v[210:213], v[12:15]
	v_mfma_f32_16x16x32_bf16 v[6:9], v[116:119], v[214:217], v[8:11]
	v_mfma_f32_16x16x32_bf16 v[8:11], v[120:123], v[218:221], v[6:9]
	v_mfma_f32_16x16x32_bf16 v[2:5], v[168:171], v[214:217], v[2:5]
	v_mfma_f32_16x16x32_bf16 v[4:7], v[172:175], v[218:221], v[2:5]
	s_setprio 0
	s_barrier
	s_add_i32 s4, s4, 2
	s_add_u32 s97, s97, 0x100
	s_addc_u32 s96, s96, 0
	s_cmp_gt_u32 s4, 29
	s_mov_b64 s[8:9], s[68:69]
	s_cbranch_scc0 .LBB0_327
	s_branch .Lpeelx327
.LBB0_327:
	s_add_u32 s68, s8, 0x100
	s_addc_u32 s69, s9, 0
	s_add_i32 s84, 0, 0x10000
	s_cmp_eq_u32 s4, 28
	s_cselect_b32 vcc_hi, s1, s69
	s_cselect_b32 vcc_lo, s5, s68
	v_add_u32_e32 v0, s84, v188
	s_cselect_b32 s71, s7, s96
	s_cselect_b32 s70, s85, s97
	s_add_i32 s10, 0, 0x14000
	ds_read_b128 v[52:55], v0
	ds_read_b128 v[56:59], v0 offset:1024
	ds_read_b128 v[76:79], v0 offset:2048
	ds_read_b128 v[80:83], v0 offset:3072
	v_add_u32_e32 v0, s10, v188
	ds_read_b128 v[116:119], v0
	ds_read_b128 v[120:123], v0 offset:1024
	ds_read_b128 v[168:171], v0 offset:2048
	ds_read_b128 v[172:175], v0 offset:3072
	v_lshl_add_u64 v[2:3], s[8:9], 0, v[164:165]
	s_add_i32 m0, s58, 0xc000
	ds_read_b128 v[176:179], v189
	ds_read_b128 v[180:183], v189 offset:1024
	ds_read_b128 v[190:193], v189 offset:2048
	ds_read_b128 v[194:197], v189 offset:3072
	ds_read_b128 v[198:201], v189 offset:4096
	ds_read_b128 v[210:213], v189 offset:5120
	ds_read_b128 v[214:217], v189 offset:6144
	ds_read_b128 v[218:221], v189 offset:7168
	global_load_lds_dwordx4 v[2:3], off
	v_lshl_add_u64 v[2:3], s[8:9], 0, v[166:167]
	s_add_i32 m0, s58, 0xe000
	s_nop 0
	global_load_lds_dwordx4 v[2:3], off
	s_waitcnt vmcnt(8)
	s_waitcnt lgkmcnt(0)
	s_barrier
; #define PG8_STAGE(bufoff, gbase, voff) do { _Pragma("unroll") for (int _i = 0; _i < 2; ++_i) \
;         __builtin_amdgcn_global_load_lds((const unsigned*)((const char*)(gbase) + (voff)[_i]), (PG8_LAS unsigned*)(lds + (bufoff) + ldsw + _i * 8192), 16, 0, 0); } while (0)
; #define PG8_LDA(dst, b, h) do { _Pragma("unroll") for (int m = 0; m < 4; ++m) _Pragma("unroll") for (int k = 0; k < 2; ++k) dst[m][k] = *(const PG8_LAS bf16x8*)(lds + PG8_SA(b, h) + aoff + m * 2048 + k * 1024); } while (0)
; #define PG8_LDB(dst, b, h) do { _Pragma("unroll") for (int n = 0; n < 2; ++n) _Pragma("unroll") for (int k = 0; k < 2; ++k) dst[n][k] = *(const PG8_LAS bf16x8*)(lds + PG8_SB(b, h) + boff + n * 2048 + k * 1024); } while (0)
; #define PG8_MMA(ai, bj, At, Bt) do { __builtin_amdgcn_s_setprio(1); _Pragma("unroll") for (int m = 0; m < 4; ++m) _Pragma("unroll") for (int n = 0; n < 2; ++n) _Pragma("unroll") for (int k = 0; k < 2; ++k) \
;         acc[ai][bj][m][n] = mma16<Epi::I8>(Bt[n][k], At[m][k], acc[ai][bj][m][n]); __builtin_amdgcn_s_setprio(0); } while (0)
; #define PG8_WAIT_V(n) asm volatile("s_waitcnt vmcnt(" #n ")" ::: "memory")
; #define PG8_WAIT_L(n) asm volatile("s_waitcnt lgkmcnt(" #n ")" ::: "memory")
; #define PG8_BAR __builtin_amdgcn_s_barrier()
; #define PG8_SCHED __builtin_amdgcn_sched_barrier(0)
; template <class Epi, class Sched, bool ALIGN_EPI = false, bool SP2 = false>
; __device__ __forceinline__ void gemm_phase(PG8_LAS unsigned char* lds, const Gemm g, const Sched& S, const Epi& E) {
;     ...
;             if constexpr (SP2) {
;             PG8_LDB(B0, 0, 0); PG8_LDB(B1, 0, 1); PG8_SCHED; PG8_LDA(At, 0, 0); PG8_STAGE(PG8_SA(1, 1), a1 + hstep, voffA);
;             PG8_WAIT_V(8); PG8_WAIT_L(0); PG8_BAR; PG8_MMA(0, 0, At, B0); PG8_MMA(0, 1, At, B1); PG8_BAR; PG8_SCHED;
;             PG8_LDA(At, 0, 1); PG8_STAGE(PG8_SB(0, 0), b2, voffB); PG8_STAGE(PG8_SB(0, 1), b2 + hstep, voffB); PG8_STAGE(PG8_SA(0, 0), a2, voffA);
;             PG8_WAIT_V(8); PG8_WAIT_L(0); PG8_BAR; PG8_MMA(1, 0, At, B0); PG8_MMA(1, 1, At, B1); PG8_BAR; PG8_SCHED;
	s_setprio 1
	s_waitcnt lgkmcnt(0)
	v_mfma_f32_16x16x32_bf16 v[152:155], v[52:55], v[176:179], v[152:155]
	v_mfma_f32_16x16x32_bf16 v[152:155], v[56:59], v[180:183], v[152:155]
	v_mfma_f32_16x16x32_bf16 v[144:147], v[76:79], v[176:179], v[144:147]
	v_mfma_f32_16x16x32_bf16 v[144:147], v[80:83], v[180:183], v[144:147]
	v_mfma_f32_16x16x32_bf16 v[148:151], v[52:55], v[190:193], v[148:151]
	v_mfma_f32_16x16x32_bf16 v[148:151], v[56:59], v[194:197], v[148:151]
	v_mfma_f32_16x16x32_bf16 v[140:143], v[76:79], v[190:193], v[140:143]
	v_mfma_f32_16x16x32_bf16 v[140:143], v[80:83], v[194:197], v[140:143]
	v_mfma_f32_16x16x32_bf16 v[136:139], v[52:55], v[198:201], v[136:139]
	v_mfma_f32_16x16x32_bf16 v[136:139], v[56:59], v[210:213], v[136:139]
	v_mfma_f32_16x16x32_bf16 v[132:135], v[76:79], v[198:201], v[132:135]
	v_mfma_f32_16x16x32_bf16 v[132:135], v[80:83], v[210:213], v[132:135]
	v_mfma_f32_16x16x32_bf16 v[128:131], v[52:55], v[214:217], v[128:131]
	v_mfma_f32_16x16x32_bf16 v[128:131], v[56:59], v[218:221], v[128:131]
	v_mfma_f32_16x16x32_bf16 v[124:127], v[76:79], v[214:217], v[124:127]
	v_mfma_f32_16x16x32_bf16 v[124:127], v[80:83], v[218:221], v[124:127]
	s_setprio 0
	s_setprio 1
	v_mfma_f32_16x16x32_bf16 v[112:115], v[116:119], v[176:179], v[112:115]
	v_mfma_f32_16x16x32_bf16 v[112:115], v[120:123], v[180:183], v[112:115]
	v_mfma_f32_16x16x32_bf16 v[104:107], v[168:171], v[176:179], v[104:107]
	v_mfma_f32_16x16x32_bf16 v[104:107], v[172:175], v[180:183], v[104:107]
	v_mfma_f32_16x16x32_bf16 v[108:111], v[116:119], v[190:193], v[108:111]
	v_mfma_f32_16x16x32_bf16 v[108:111], v[120:123], v[194:197], v[108:111]
	v_mfma_f32_16x16x32_bf16 v[100:103], v[168:171], v[190:193], v[100:103]
	v_mfma_f32_16x16x32_bf16 v[100:103], v[172:175], v[194:197], v[100:103]
	v_mfma_f32_16x16x32_bf16 v[96:99], v[116:119], v[198:201], v[96:99]
	v_mfma_f32_16x16x32_bf16 v[96:99], v[120:123], v[210:213], v[96:99]
	v_mfma_f32_16x16x32_bf16 v[92:95], v[168:171], v[198:201], v[92:95]
	v_mfma_f32_16x16x32_bf16 v[92:95], v[172:175], v[210:213], v[92:95]
	v_mfma_f32_16x16x32_bf16 v[88:91], v[116:119], v[214:217], v[88:91]
	v_mfma_f32_16x16x32_bf16 v[88:91], v[120:123], v[218:221], v[88:91]
	v_mfma_f32_16x16x32_bf16 v[84:87], v[168:171], v[214:217], v[84:87]
	v_mfma_f32_16x16x32_bf16 v[84:87], v[172:175], v[218:221], v[84:87]
	s_setprio 0
	s_barrier
	s_add_i32 s8, s84, s80
	v_lshl_add_u64 v[184:185], s[70:71], 0, v[158:159]
	s_mov_b32 m0, s8
	ds_read_b128 v[176:179], v189 offset:16384
	ds_read_b128 v[180:183], v189 offset:17408
	ds_read_b128 v[190:193], v189 offset:18432
	ds_read_b128 v[194:197], v189 offset:19456
	ds_read_b128 v[198:201], v189 offset:20480
	ds_read_b128 v[210:213], v189 offset:21504
	ds_read_b128 v[214:217], v189 offset:22528
	ds_read_b128 v[218:221], v189 offset:23552
	global_load_lds_dwordx4 v[184:185], off
	s_add_i32 m0, s8, 0x2000
	s_add_u32 s8, s70, 0x80000
	v_lshl_add_u64 v[206:207], s[70:71], 0, v[162:163]
	s_addc_u32 s9, s71, 0
	s_add_i32 s10, s10, s80
	global_load_lds_dwordx4 v[206:207], off
	v_lshl_add_u64 v[2:3], s[8:9], 0, v[158:159]
	s_mov_b32 m0, s10
	v_lshl_add_u64 v[222:223], vcc, 0, v[156:157]
	global_load_lds_dwordx4 v[2:3], off
	v_lshl_add_u64 v[2:3], s[8:9], 0, v[162:163]
	s_add_i32 m0, s10, 0x2000
	v_lshl_add_u64 v[224:225], vcc, 0, v[160:161]
	global_load_lds_dwordx4 v[2:3], off
	s_mov_b32 m0, s58
	s_nop 0
	global_load_lds_dwordx4 v[222:223], off
	s_mov_b32 m0, s12
	s_nop 0
	global_load_lds_dwordx4 v[224:225], off
	s_waitcnt vmcnt(8)
	s_waitcnt lgkmcnt(0)
	s_barrier
	s_setprio 1
	s_waitcnt lgkmcnt(0)
	v_mfma_f32_16x16x32_bf16 v[72:75], v[52:55], v[176:179], v[72:75]
	v_mfma_f32_16x16x32_bf16 v[72:75], v[56:59], v[180:183], v[72:75]
	v_mfma_f32_16x16x32_bf16 v[64:67], v[76:79], v[176:179], v[64:67]
	v_mfma_f32_16x16x32_bf16 v[64:67], v[80:83], v[180:183], v[64:67]
	v_mfma_f32_16x16x32_bf16 v[68:71], v[52:55], v[190:193], v[68:71]
	v_mfma_f32_16x16x32_bf16 v[68:71], v[56:59], v[194:197], v[68:71]
	v_mfma_f32_16x16x32_bf16 v[60:63], v[76:79], v[190:193], v[60:63]
	v_mfma_f32_16x16x32_bf16 v[60:63], v[80:83], v[194:197], v[60:63]
	v_mfma_f32_16x16x32_bf16 v[48:51], v[52:55], v[198:201], v[48:51]
	v_mfma_f32_16x16x32_bf16 v[48:51], v[56:59], v[210:213], v[48:51]
	v_mfma_f32_16x16x32_bf16 v[44:47], v[76:79], v[198:201], v[44:47]
	v_mfma_f32_16x16x32_bf16 v[44:47], v[80:83], v[210:213], v[44:47]
	v_mfma_f32_16x16x32_bf16 v[40:43], v[52:55], v[214:217], v[40:43]
	v_mfma_f32_16x16x32_bf16 v[40:43], v[56:59], v[218:221], v[40:43]
	v_mfma_f32_16x16x32_bf16 v[36:39], v[76:79], v[214:217], v[36:39]
	v_mfma_f32_16x16x32_bf16 v[36:39], v[80:83], v[218:221], v[36:39]
	s_setprio 0
	s_setprio 1
	v_mfma_f32_16x16x32_bf16 v[32:35], v[116:119], v[176:179], v[32:35]
	v_mfma_f32_16x16x32_bf16 v[32:35], v[120:123], v[180:183], v[32:35]
	v_mfma_f32_16x16x32_bf16 v[24:27], v[168:171], v[176:179], v[24:27]
	v_mfma_f32_16x16x32_bf16 v[24:27], v[172:175], v[180:183], v[24:27]
	v_mfma_f32_16x16x32_bf16 v[28:31], v[116:119], v[190:193], v[28:31]
	v_mfma_f32_16x16x32_bf16 v[28:31], v[120:123], v[194:197], v[28:31]
	v_mfma_f32_16x16x32_bf16 v[20:23], v[168:171], v[190:193], v[20:23]
	v_mfma_f32_16x16x32_bf16 v[20:23], v[172:175], v[194:197], v[20:23]
	v_mfma_f32_16x16x32_bf16 v[16:19], v[116:119], v[198:201], v[16:19]
	v_mfma_f32_16x16x32_bf16 v[16:19], v[120:123], v[210:213], v[16:19]
	v_mfma_f32_16x16x32_bf16 v[12:15], v[168:171], v[198:201], v[12:15]
	v_mfma_f32_16x16x32_bf16 v[12:15], v[172:175], v[210:213], v[12:15]
	v_mfma_f32_16x16x32_bf16 v[8:11], v[116:119], v[214:217], v[8:11]
	v_mfma_f32_16x16x32_bf16 v[8:11], v[120:123], v[218:221], v[8:11]
	v_mfma_f32_16x16x32_bf16 v[2:5], v[168:171], v[214:217], v[4:7]
	v_mfma_f32_16x16x32_bf16 v[2:5], v[172:175], v[218:221], v[2:5]
	s_setprio 0
	s_barrier
; #define PG8_STAGE(bufoff, gbase, voff) do { _Pragma("unroll") for (int _i = 0; _i < 2; ++_i) \
;         __builtin_amdgcn_global_load_lds((const unsigned*)((const char*)(gbase) + (voff)[_i]), (PG8_LAS unsigned*)(lds + (bufoff) + ldsw + _i * 8192), 16, 0, 0); } while (0)
; #define PG8_LDA(dst, b, h) do { _Pragma("unroll") for (int m = 0; m < 4; ++m) _Pragma("unroll") for (int k = 0; k < 2; ++k) dst[m][k] = *(const PG8_LAS bf16x8*)(lds + PG8_SA(b, h) + aoff + m * 2048 + k * 1024); } while (0)
; #define PG8_LDB(dst, b, h) do { _Pragma("unroll") for (int n = 0; n < 2; ++n) _Pragma("unroll") for (int k = 0; k < 2; ++k) dst[n][k] = *(const PG8_LAS bf16x8*)(lds + PG8_SB(b, h) + boff + n * 2048 + k * 1024); } while (0)
; #define PG8_MMA(ai, bj, At, Bt) do { __builtin_amdgcn_s_setprio(1); _Pragma("unroll") for (int m = 0; m < 4; ++m) _Pragma("unroll") for (int n = 0; n < 2; ++n) _Pragma("unroll") for (int k = 0; k < 2; ++k) \
;         acc[ai][bj][m][n] = mma16<Epi::I8>(Bt[n][k], At[m][k], acc[ai][bj][m][n]); __builtin_amdgcn_s_setprio(0); } while (0)
; #define PG8_WAIT_V(n) asm volatile("s_waitcnt vmcnt(" #n ")" ::: "memory")
; #define PG8_WAIT_L(n) asm volatile("s_waitcnt lgkmcnt(" #n ")" ::: "memory")
; #define PG8_BAR __builtin_amdgcn_s_barrier()
; #define PG8_SCHED __builtin_amdgcn_sched_barrier(0)
; template <class Epi, class Sched, bool ALIGN_EPI = false, bool SP2 = false>
; __device__ __forceinline__ void gemm_phase(PG8_LAS unsigned char* lds, const Gemm g, const Sched& S, const Epi& E) {
;     ...
;             PG8_LDB(B0, 1, 0); PG8_LDB(B1, 1, 1); PG8_SCHED; PG8_LDA(At, 1, 0); PG8_STAGE(PG8_SA(0, 1), a2 + hstep, voffA);
;             PG8_WAIT_V(8); PG8_WAIT_L(0); PG8_BAR; PG8_MMA(0, 0, At, B0); PG8_MMA(0, 1, At, B1); PG8_BAR; PG8_SCHED;
;             PG8_LDA(At, 1, 1); PG8_STAGE(PG8_SB(1, 0), b3, voffB); PG8_STAGE(PG8_SB(1, 1), b3 + hstep, voffB); PG8_STAGE(PG8_SA(1, 0), a3, voffA);
;             PG8_WAIT_V(8); PG8_WAIT_L(0); PG8_BAR; PG8_MMA(1, 0, At, B0); PG8_MMA(1, 1, At, B1); PG8_BAR; PG8_SCHED;
	s_add_i32 s10, 0, 0x18000
	v_add_u32_e32 v0, s10, v188
	s_add_i32 s11, 0, 0x1c000
	ds_read_b128 v[52:55], v0
	ds_read_b128 v[56:59], v0 offset:1024
	ds_read_b128 v[76:79], v0 offset:2048
	ds_read_b128 v[80:83], v0 offset:3072
	v_add_u32_e32 v0, s11, v188
	ds_read_b128 v[116:119], v0
	ds_read_b128 v[120:123], v0 offset:1024
	ds_read_b128 v[168:171], v0 offset:2048
	ds_read_b128 v[172:175], v0 offset:3072
	s_add_u32 s8, vcc_lo, 0x80000
	s_addc_u32 s9, vcc_hi, 0
	s_mov_b32 m0, s13
	v_lshl_add_u64 v[6:7], s[8:9], 0, v[156:157]
	ds_read_b128 v[176:179], v189 offset:32768
	ds_read_b128 v[180:183], v189 offset:33792
	ds_read_b128 v[190:193], v189 offset:34816
	ds_read_b128 v[194:197], v189 offset:35840
	ds_read_b128 v[198:201], v189 offset:36864
	ds_read_b128 v[210:213], v189 offset:37888
	ds_read_b128 v[214:217], v189 offset:38912
	ds_read_b128 v[218:221], v189 offset:39936
	global_load_lds_dwordx4 v[6:7], off
	v_lshl_add_u64 v[6:7], s[8:9], 0, v[160:161]
	s_mov_b32 m0, s66
	s_nop 0
	global_load_lds_dwordx4 v[6:7], off
	s_waitcnt vmcnt(8)
	s_waitcnt lgkmcnt(0)
	s_barrier
	s_setprio 1
	s_waitcnt lgkmcnt(0)
	v_mfma_f32_16x16x32_bf16 v[152:155], v[52:55], v[176:179], v[152:155]
	v_mfma_f32_16x16x32_bf16 v[152:155], v[56:59], v[180:183], v[152:155]
	v_mfma_f32_16x16x32_bf16 v[144:147], v[76:79], v[176:179], v[144:147]
	v_mfma_f32_16x16x32_bf16 v[144:147], v[80:83], v[180:183], v[144:147]
	v_mfma_f32_16x16x32_bf16 v[148:151], v[52:55], v[190:193], v[148:151]
	v_mfma_f32_16x16x32_bf16 v[148:151], v[56:59], v[194:197], v[148:151]
	v_mfma_f32_16x16x32_bf16 v[140:143], v[76:79], v[190:193], v[140:143]
	v_mfma_f32_16x16x32_bf16 v[140:143], v[80:83], v[194:197], v[140:143]
	v_mfma_f32_16x16x32_bf16 v[136:139], v[52:55], v[198:201], v[136:139]
	v_mfma_f32_16x16x32_bf16 v[136:139], v[56:59], v[210:213], v[136:139]
	v_mfma_f32_16x16x32_bf16 v[132:135], v[76:79], v[198:201], v[132:135]
	v_mfma_f32_16x16x32_bf16 v[132:135], v[80:83], v[210:213], v[132:135]
	v_mfma_f32_16x16x32_bf16 v[128:131], v[52:55], v[214:217], v[128:131]
	v_mfma_f32_16x16x32_bf16 v[128:131], v[56:59], v[218:221], v[128:131]
	v_mfma_f32_16x16x32_bf16 v[124:127], v[76:79], v[214:217], v[124:127]
	v_mfma_f32_16x16x32_bf16 v[124:127], v[80:83], v[218:221], v[124:127]
	s_setprio 0
	s_setprio 1
	v_mfma_f32_16x16x32_bf16 v[112:115], v[116:119], v[176:179], v[112:115]
	v_mfma_f32_16x16x32_bf16 v[112:115], v[120:123], v[180:183], v[112:115]
	v_mfma_f32_16x16x32_bf16 v[104:107], v[168:171], v[176:179], v[104:107]
	v_mfma_f32_16x16x32_bf16 v[104:107], v[172:175], v[180:183], v[104:107]
	v_mfma_f32_16x16x32_bf16 v[108:111], v[116:119], v[190:193], v[108:111]
	v_mfma_f32_16x16x32_bf16 v[108:111], v[120:123], v[194:197], v[108:111]
	v_mfma_f32_16x16x32_bf16 v[100:103], v[168:171], v[190:193], v[100:103]
	v_mfma_f32_16x16x32_bf16 v[100:103], v[172:175], v[194:197], v[100:103]
	v_mfma_f32_16x16x32_bf16 v[96:99], v[116:119], v[198:201], v[96:99]
	v_mfma_f32_16x16x32_bf16 v[96:99], v[120:123], v[210:213], v[96:99]
	v_mfma_f32_16x16x32_bf16 v[92:95], v[168:171], v[198:201], v[92:95]
	v_mfma_f32_16x16x32_bf16 v[92:95], v[172:175], v[210:213], v[92:95]
	v_mfma_f32_16x16x32_bf16 v[88:91], v[116:119], v[214:217], v[88:91]
	v_mfma_f32_16x16x32_bf16 v[88:91], v[120:123], v[218:221], v[88:91]
	v_mfma_f32_16x16x32_bf16 v[84:87], v[168:171], v[214:217], v[84:87]
	v_mfma_f32_16x16x32_bf16 v[84:87], v[172:175], v[218:221], v[84:87]
	s_setprio 0
	s_barrier
	s_add_i32 s8, s10, s80
	v_lshl_add_u64 v[6:7], v[184:185], 0, s[92:93]
	s_mov_b32 m0, s8
	ds_read_b128 v[176:179], v189 offset:49152
	ds_read_b128 v[180:183], v189 offset:50176
	ds_read_b128 v[190:193], v189 offset:51200
	ds_read_b128 v[194:197], v189 offset:52224
	ds_read_b128 v[198:201], v189 offset:53248
	ds_read_b128 v[210:213], v189 offset:54272
	ds_read_b128 v[214:217], v189 offset:55296
	ds_read_b128 v[218:221], v189 offset:56320
	global_load_lds_dwordx4 v[6:7], off
	s_add_i32 m0, s8, 0x2000
	s_add_u32 s8, s70, 0x80080
	v_lshl_add_u64 v[6:7], v[206:207], 0, s[92:93]
	s_addc_u32 s9, s71, 0
	s_add_i32 s10, s11, s80
	global_load_lds_dwordx4 v[6:7], off
	v_lshl_add_u64 v[6:7], s[8:9], 0, v[158:159]
	s_mov_b32 m0, s10
	s_nop 0
	global_load_lds_dwordx4 v[6:7], off
	v_lshl_add_u64 v[6:7], s[8:9], 0, v[162:163]
	s_add_i32 m0, s10, 0x2000
	s_nop 0
	global_load_lds_dwordx4 v[6:7], off
	v_lshl_add_u64 v[6:7], v[222:223], 0, s[92:93]
	s_mov_b32 m0, s67
	s_nop 0
	global_load_lds_dwordx4 v[6:7], off
	v_lshl_add_u64 v[6:7], v[224:225], 0, s[92:93]
	s_mov_b32 m0, s81
	s_nop 0
	global_load_lds_dwordx4 v[6:7], off
	s_waitcnt vmcnt(8)
	s_waitcnt lgkmcnt(0)
	s_barrier
	s_setprio 1
	s_waitcnt lgkmcnt(0)
	v_mfma_f32_16x16x32_bf16 v[72:75], v[52:55], v[176:179], v[72:75]
	v_mfma_f32_16x16x32_bf16 v[72:75], v[56:59], v[180:183], v[72:75]
	v_mfma_f32_16x16x32_bf16 v[64:67], v[76:79], v[176:179], v[64:67]
	v_mfma_f32_16x16x32_bf16 v[64:67], v[80:83], v[180:183], v[64:67]
	v_mfma_f32_16x16x32_bf16 v[68:71], v[52:55], v[190:193], v[68:71]
	v_mfma_f32_16x16x32_bf16 v[68:71], v[56:59], v[194:197], v[68:71]
	v_mfma_f32_16x16x32_bf16 v[60:63], v[76:79], v[190:193], v[60:63]
	v_mfma_f32_16x16x32_bf16 v[60:63], v[80:83], v[194:197], v[60:63]
	v_mfma_f32_16x16x32_bf16 v[48:51], v[52:55], v[198:201], v[48:51]
	v_mfma_f32_16x16x32_bf16 v[48:51], v[56:59], v[210:213], v[48:51]
	v_mfma_f32_16x16x32_bf16 v[44:47], v[76:79], v[198:201], v[44:47]
	v_mfma_f32_16x16x32_bf16 v[44:47], v[80:83], v[210:213], v[44:47]
	v_mfma_f32_16x16x32_bf16 v[40:43], v[52:55], v[214:217], v[40:43]
	v_mfma_f32_16x16x32_bf16 v[40:43], v[56:59], v[218:221], v[40:43]
	v_mfma_f32_16x16x32_bf16 v[36:39], v[76:79], v[214:217], v[36:39]
	v_mfma_f32_16x16x32_bf16 v[36:39], v[80:83], v[218:221], v[36:39]
	s_setprio 0
	s_setprio 1
	v_mfma_f32_16x16x32_bf16 v[32:35], v[116:119], v[176:179], v[32:35]
	v_mfma_f32_16x16x32_bf16 v[32:35], v[120:123], v[180:183], v[32:35]
	v_mfma_f32_16x16x32_bf16 v[24:27], v[168:171], v[176:179], v[24:27]
	v_mfma_f32_16x16x32_bf16 v[24:27], v[172:175], v[180:183], v[24:27]
	v_mfma_f32_16x16x32_bf16 v[28:31], v[116:119], v[190:193], v[28:31]
	v_mfma_f32_16x16x32_bf16 v[28:31], v[120:123], v[194:197], v[28:31]
	v_mfma_f32_16x16x32_bf16 v[20:23], v[168:171], v[190:193], v[20:23]
	v_mfma_f32_16x16x32_bf16 v[20:23], v[172:175], v[194:197], v[20:23]
	v_mfma_f32_16x16x32_bf16 v[16:19], v[116:119], v[198:201], v[16:19]
	v_mfma_f32_16x16x32_bf16 v[16:19], v[120:123], v[210:213], v[16:19]
	v_mfma_f32_16x16x32_bf16 v[12:15], v[168:171], v[198:201], v[12:15]
	v_mfma_f32_16x16x32_bf16 v[12:15], v[172:175], v[210:213], v[12:15]
	v_mfma_f32_16x16x32_bf16 v[6:9], v[116:119], v[214:217], v[8:11]
	v_mfma_f32_16x16x32_bf16 v[8:11], v[120:123], v[218:221], v[6:9]
	v_mfma_f32_16x16x32_bf16 v[2:5], v[168:171], v[214:217], v[2:5]
	v_mfma_f32_16x16x32_bf16 v[4:7], v[172:175], v[218:221], v[2:5]
	s_setprio 0
	s_barrier
	s_add_i32 s4, s4, 2
	s_add_u32 s97, s97, 0x100
	s_addc_u32 s96, s96, 0
	s_cmp_gt_u32 s4, 29
	s_mov_b64 s[8:9], s[68:69]
	s_cbranch_scc0 .LBB0_327

; #define PG8_STAGE(bufoff, gbase, voff) do { _Pragma("unroll") for (int _i = 0; _i < 2; ++_i) \
;         __builtin_amdgcn_global_load_lds((const unsigned*)((const char*)(gbase) + (voff)[_i]), (PG8_LAS unsigned*)(lds + (bufoff) + ldsw + _i * 8192), 16, 0, 0); } while (0)
; #define PG8_LDA(dst, b, h) do { _Pragma("unroll") for (int m = 0; m < 4; ++m) _Pragma("unroll") for (int k = 0; k < 2; ++k) dst[m][k] = *(const PG8_LAS bf16x8*)(lds + PG8_SA(b, h) + aoff + m * 2048 + k * 1024); } while (0)
; #define PG8_LDB(dst, b, h) do { _Pragma("unroll") for (int n = 0; n < 2; ++n) _Pragma("unroll") for (int k = 0; k < 2; ++k) dst[n][k] = *(const PG8_LAS bf16x8*)(lds + PG8_SB(b, h) + boff + n * 2048 + k * 1024); } while (0)
; #define PG8_WAIT_V(n) asm volatile("s_waitcnt vmcnt(" #n ")" ::: "memory")
; #define PG8_WAIT_L(n) asm volatile("s_waitcnt lgkmcnt(" #n ")" ::: "memory")
; template <class Epi, class Sched, bool ALIGN_EPI = false, bool SP2 = false>
; __device__ __forceinline__ void gemm_phase(PG8_LAS unsigned char* lds, const Gemm g, const Sched& S, const Epi& E) {
;     ...
;         const bool has_next = S.next(ui + 1, nxt);
;         const char* nA = has_next ? (const char*)g.A + (size_t)nxt.pm * tstep : cA; const char* nB = has_next ? (const char*)g.Bt + (size_t)nxt.pn * tstep : cB;
;         for (int t = 0; t < nt; t += 2) {
;             const bool last = (t == nt - 2);
;             const char* a1 = cA + (size_t)(t + 1) * kstep;
;             const char* a2 = last ? nA : cA + (size_t)(t + 2) * kstep; const char* b2 = last ? nB : cB + (size_t)(t + 2) * kstep;
;             const char* a3 = a2 + kstep; const char* b3 = b2 + kstep;
;             if (last && has_next) S.a_ready(nxt);
;             if constexpr (SP2) {
;             PG8_LDB(B0, 0, 0); PG8_LDB(B1, 0, 1); PG8_SCHED; PG8_LDA(At, 0, 0); PG8_STAGE(PG8_SA(1, 1), a1 + hstep, voffA);
;             PG8_WAIT_V(8); PG8_WAIT_L(0); PG8_BAR; PG8_MMA(0, 0, At, B0); PG8_MMA(0, 1, At, B1); PG8_BAR; PG8_SCHED;
;             PG8_LDA(At, 0, 1); PG8_STAGE(PG8_SB(0, 0), b2, voffB); PG8_STAGE(PG8_SB(0, 1), b2 + hstep, voffB); PG8_STAGE(PG8_SA(0, 0), a2, voffA);
;             PG8_WAIT_V(8); PG8_WAIT_L(0); PG8_BAR; PG8_MMA(1, 0, At, B0); PG8_MMA(1, 1, At, B1); PG8_BAR; PG8_SCHED;
;             PG8_LDB(B0, 1, 0); PG8_LDB(B1, 1, 1); PG8_SCHED; PG8_LDA(At, 1, 0); PG8_STAGE(PG8_SA(0, 1), a2 + hstep, voffA);
.Lpeel385:
	s_add_u32 s70, s8, 0x100
	s_addc_u32 s71, s9, 0
	s_add_i32 s84, 0, 0x10000
	s_cmp_eq_u32 s5, 12
	s_cselect_b32 vcc_hi, s1, s71
	s_cselect_b32 vcc_lo, s7, s70
	v_add_u32_e32 v0, s84, v214
	s_cselect_b32 s83, s69, s68
	s_cselect_b32 s82, s81, s85
	s_add_i32 s10, 0, 0x14000
	ds_read_b128 v[44:47], v0
	ds_read_b128 v[52:55], v0 offset:1024
	ds_read_b128 v[60:63], v0 offset:2048
	ds_read_b128 v[64:67], v0 offset:3072
	v_add_u32_e32 v0, s10, v214
	ds_read_b128 v[84:87], v0
	ds_read_b128 v[88:91], v0 offset:1024
	ds_read_b128 v[92:95], v0 offset:2048
	ds_read_b128 v[100:103], v0 offset:3072
	v_lshl_add_u64 v[2:3], s[8:9], 0, v[184:185]
	s_add_i32 m0, s13, 0xc000
	ds_read_b128 v[124:127], v215
	ds_read_b128 v[128:131], v215 offset:1024
	ds_read_b128 v[140:143], v215 offset:2048
	ds_read_b128 v[188:191], v215 offset:3072
	ds_read_b128 v[192:195], v215 offset:4096
	ds_read_b128 v[196:199], v215 offset:5120
	ds_read_b128 v[216:219], v215 offset:6144
	ds_read_b128 v[220:223], v215 offset:7168
	global_load_lds_dwordx4 v[2:3], off
	v_lshl_add_u64 v[2:3], s[8:9], 0, v[186:187]
	s_add_i32 m0, s13, 0xe000
	s_nop 0
	global_load_lds_dwordx4 v[2:3], off
	s_waitcnt vmcnt(8)
	s_waitcnt lgkmcnt(0)
	s_barrier
	s_setprio 1
	s_waitcnt lgkmcnt(0)
	v_mfma_i32_16x16x64_i8 v[172:175], v[44:47], v[124:127], 0
	v_mfma_i32_16x16x64_i8 v[172:175], v[52:55], v[128:131], v[172:175]
	v_mfma_i32_16x16x64_i8 v[164:167], v[60:63], v[124:127], 0
	v_mfma_i32_16x16x64_i8 v[164:167], v[64:67], v[128:131], v[164:167]
	v_mfma_i32_16x16x64_i8 v[168:171], v[44:47], v[140:143], 0
	v_mfma_i32_16x16x64_i8 v[168:171], v[52:55], v[188:191], v[168:171]
	v_mfma_i32_16x16x64_i8 v[160:163], v[60:63], v[140:143], 0
	v_mfma_i32_16x16x64_i8 v[160:163], v[64:67], v[188:191], v[160:163]
	v_mfma_i32_16x16x64_i8 v[156:159], v[44:47], v[192:195], 0
	v_mfma_i32_16x16x64_i8 v[156:159], v[52:55], v[196:199], v[156:159]
	v_mfma_i32_16x16x64_i8 v[152:155], v[60:63], v[192:195], 0
	v_mfma_i32_16x16x64_i8 v[152:155], v[64:67], v[196:199], v[152:155]
	v_mfma_i32_16x16x64_i8 v[148:151], v[44:47], v[216:219], 0
	v_mfma_i32_16x16x64_i8 v[148:151], v[52:55], v[220:223], v[148:151]
	v_mfma_i32_16x16x64_i8 v[144:147], v[60:63], v[216:219], 0
	v_mfma_i32_16x16x64_i8 v[144:147], v[64:67], v[220:223], v[144:147]
	s_setprio 0
	s_setprio 1
	v_mfma_i32_16x16x64_i8 v[136:139], v[84:87], v[124:127], 0
	v_mfma_i32_16x16x64_i8 v[136:139], v[88:91], v[128:131], v[136:139]
	v_mfma_i32_16x16x64_i8 v[120:123], v[92:95], v[124:127], 0
	v_mfma_i32_16x16x64_i8 v[120:123], v[100:103], v[128:131], v[120:123]
	v_mfma_i32_16x16x64_i8 v[116:119], v[92:95], v[140:143], 0
	v_mfma_i32_16x16x64_i8 v[116:119], v[100:103], v[188:191], v[116:119]
	v_mfma_i32_16x16x64_i8 v[112:115], v[84:87], v[192:195], 0
	v_mfma_i32_16x16x64_i8 v[112:115], v[88:91], v[196:199], v[112:115]
	v_mfma_i32_16x16x64_i8 v[108:111], v[92:95], v[192:195], 0
	v_mfma_i32_16x16x64_i8 v[108:111], v[100:103], v[196:199], v[108:111]
	v_mfma_i32_16x16x64_i8 v[104:107], v[84:87], v[216:219], 0
	v_mfma_i32_16x16x64_i8 v[104:107], v[88:91], v[220:223], v[104:107]
	v_mfma_i32_16x16x64_i8 v[96:99], v[92:95], v[216:219], 0
	v_mfma_i32_16x16x64_i8 v[96:99], v[100:103], v[220:223], v[96:99]
	v_mfma_i32_16x16x64_i8 v[124:127], v[84:87], v[140:143], 0
	v_mfma_i32_16x16x64_i8 v[124:127], v[88:91], v[188:191], v[124:127]
	s_setprio 0
	s_barrier
	s_add_i32 s8, s84, s12
	v_lshl_add_u64 v[200:201], s[82:83], 0, v[178:179]
	s_mov_b32 m0, s8
	ds_read_b128 v[128:131], v215 offset:16384
	ds_read_b128 v[132:135], v215 offset:17408
	ds_read_b128 v[140:143], v215 offset:18432
	ds_read_b128 v[188:191], v215 offset:19456
	ds_read_b128 v[192:195], v215 offset:20480
	ds_read_b128 v[196:199], v215 offset:21504
	ds_read_b128 v[216:219], v215 offset:22528
	ds_read_b128 v[220:223], v215 offset:23552
	global_load_lds_dwordx4 v[200:201], off
	s_add_i32 m0, s8, 0x2000
	s_add_u32 s8, s82, 0x40000
	v_lshl_add_u64 v[206:207], s[82:83], 0, v[182:183]
	s_addc_u32 s9, s83, 0
	s_add_i32 s10, s10, s12
	global_load_lds_dwordx4 v[206:207], off
	v_lshl_add_u64 v[2:3], s[8:9], 0, v[178:179]
	s_mov_b32 m0, s10
	v_lshl_add_u64 v[210:211], vcc, 0, v[176:177]
	global_load_lds_dwordx4 v[2:3], off
	v_lshl_add_u64 v[2:3], s[8:9], 0, v[182:183]
	s_add_i32 m0, s10, 0x2000
	v_lshl_add_u64 v[224:225], vcc, 0, v[180:181]
	global_load_lds_dwordx4 v[2:3], off
	s_mov_b32 m0, s13
	s_nop 0
	global_load_lds_dwordx4 v[210:211], off
	s_mov_b32 m0, s66
	s_nop 0
	global_load_lds_dwordx4 v[224:225], off
	s_waitcnt vmcnt(8)
	s_waitcnt lgkmcnt(0)
	s_barrier
	s_setprio 1
	s_waitcnt lgkmcnt(0)
	v_mfma_i32_16x16x64_i8 v[80:83], v[44:47], v[128:131], 0
	v_mfma_i32_16x16x64_i8 v[80:83], v[52:55], v[132:135], v[80:83]
	v_mfma_i32_16x16x64_i8 v[72:75], v[60:63], v[128:131], 0
	v_mfma_i32_16x16x64_i8 v[72:75], v[64:67], v[132:135], v[72:75]
	v_mfma_i32_16x16x64_i8 v[76:79], v[44:47], v[140:143], 0
	v_mfma_i32_16x16x64_i8 v[76:79], v[52:55], v[188:191], v[76:79]
	v_mfma_i32_16x16x64_i8 v[68:71], v[60:63], v[140:143], 0
	v_mfma_i32_16x16x64_i8 v[68:71], v[64:67], v[188:191], v[68:71]
	v_mfma_i32_16x16x64_i8 v[56:59], v[44:47], v[192:195], 0
	v_mfma_i32_16x16x64_i8 v[56:59], v[52:55], v[196:199], v[56:59]
	v_mfma_i32_16x16x64_i8 v[48:51], v[60:63], v[192:195], 0
	v_mfma_i32_16x16x64_i8 v[48:51], v[64:67], v[196:199], v[48:51]
	v_mfma_i32_16x16x64_i8 v[40:43], v[44:47], v[216:219], 0
	v_mfma_i32_16x16x64_i8 v[40:43], v[52:55], v[220:223], v[40:43]
	v_mfma_i32_16x16x64_i8 v[36:39], v[60:63], v[216:219], 0
	v_mfma_i32_16x16x64_i8 v[36:39], v[64:67], v[220:223], v[36:39]
	s_setprio 0
	s_setprio 1
	v_mfma_i32_16x16x64_i8 v[32:35], v[84:87], v[128:131], 0
	v_mfma_i32_16x16x64_i8 v[32:35], v[88:91], v[132:135], v[32:35]
	v_mfma_i32_16x16x64_i8 v[24:27], v[92:95], v[128:131], 0
	v_mfma_i32_16x16x64_i8 v[24:27], v[100:103], v[132:135], v[24:27]
	v_mfma_i32_16x16x64_i8 v[28:31], v[84:87], v[140:143], 0
	v_mfma_i32_16x16x64_i8 v[28:31], v[88:91], v[188:191], v[28:31]
	v_mfma_i32_16x16x64_i8 v[20:23], v[92:95], v[140:143], 0
	v_mfma_i32_16x16x64_i8 v[20:23], v[100:103], v[188:191], v[20:23]
	v_mfma_i32_16x16x64_i8 v[16:19], v[84:87], v[192:195], 0
	v_mfma_i32_16x16x64_i8 v[16:19], v[88:91], v[196:199], v[16:19]
	v_mfma_i32_16x16x64_i8 v[12:15], v[92:95], v[192:195], 0
	v_mfma_i32_16x16x64_i8 v[12:15], v[100:103], v[196:199], v[12:15]
	v_mfma_i32_16x16x64_i8 v[8:11], v[84:87], v[216:219], 0
	v_mfma_i32_16x16x64_i8 v[8:11], v[88:91], v[220:223], v[8:11]
	v_mfma_i32_16x16x64_i8 v[2:5], v[92:95], v[216:219], 0
	v_mfma_i32_16x16x64_i8 v[2:5], v[100:103], v[220:223], v[2:5]
	s_setprio 0
	s_barrier
; #define PG8_STAGE(bufoff, gbase, voff) do { _Pragma("unroll") for (int _i = 0; _i < 2; ++_i) \
;         __builtin_amdgcn_global_load_lds((const unsigned*)((const char*)(gbase) + (voff)[_i]), (PG8_LAS unsigned*)(lds + (bufoff) + ldsw + _i * 8192), 16, 0, 0); } while (0)
; #define PG8_LDA(dst, b, h) do { _Pragma("unroll") for (int m = 0; m < 4; ++m) _Pragma("unroll") for (int k = 0; k < 2; ++k) dst[m][k] = *(const PG8_LAS bf16x8*)(lds + PG8_SA(b, h) + aoff + m * 2048 + k * 1024); } while (0)
; #define PG8_LDB(dst, b, h) do { _Pragma("unroll") for (int n = 0; n < 2; ++n) _Pragma("unroll") for (int k = 0; k < 2; ++k) dst[n][k] = *(const PG8_LAS bf16x8*)(lds + PG8_SB(b, h) + boff + n * 2048 + k * 1024); } while (0)
; #define PG8_MMA(ai, bj, At, Bt) do { __builtin_amdgcn_s_setprio(1); _Pragma("unroll") for (int m = 0; m < 4; ++m) _Pragma("unroll") for (int n = 0; n < 2; ++n) _Pragma("unroll") for (int k = 0; k < 2; ++k) \
;         acc[ai][bj][m][n] = mma16<Epi::I8>(Bt[n][k], At[m][k], acc[ai][bj][m][n]); __builtin_amdgcn_s_setprio(0); } while (0)
; #define PG8_WAIT_V(n) asm volatile("s_waitcnt vmcnt(" #n ")" ::: "memory")
; #define PG8_WAIT_L(n) asm volatile("s_waitcnt lgkmcnt(" #n ")" ::: "memory")
; #define PG8_BAR __builtin_amdgcn_s_barrier()
; #define PG8_SCHED __builtin_amdgcn_sched_barrier(0)
; template <class Epi, class Sched, bool ALIGN_EPI = false, bool SP2 = false>
; __device__ __forceinline__ void gemm_phase(PG8_LAS unsigned char* lds, const Gemm g, const Sched& S, const Epi& E) {
;     ...
;             PG8_LDB(B0, 1, 0); PG8_LDB(B1, 1, 1); PG8_SCHED; PG8_LDA(At, 1, 0); PG8_STAGE(PG8_SA(0, 1), a2 + hstep, voffA);
;             PG8_WAIT_V(8); PG8_WAIT_L(0); PG8_BAR; PG8_MMA(0, 0, At, B0); PG8_MMA(0, 1, At, B1); PG8_BAR; PG8_SCHED;
;             PG8_LDA(At, 1, 1); PG8_STAGE(PG8_SB(1, 0), b3, voffB); PG8_STAGE(PG8_SB(1, 1), b3 + hstep, voffB); PG8_STAGE(PG8_SA(1, 0), a3, voffA);
;             PG8_WAIT_V(8); PG8_WAIT_L(0); PG8_BAR; PG8_MMA(1, 0, At, B0); PG8_MMA(1, 1, At, B1); PG8_BAR; PG8_SCHED;
	s_add_i32 s10, 0, 0x18000
	v_add_u32_e32 v0, s10, v214
	s_add_i32 s11, 0, 0x1c000
	ds_read_b128 v[44:47], v0
	ds_read_b128 v[52:55], v0 offset:1024
	ds_read_b128 v[60:63], v0 offset:2048
	ds_read_b128 v[64:67], v0 offset:3072
	v_add_u32_e32 v0, s11, v214
	ds_read_b128 v[84:87], v0
	ds_read_b128 v[88:91], v0 offset:1024
	ds_read_b128 v[92:95], v0 offset:2048
	ds_read_b128 v[100:103], v0 offset:3072
	s_add_u32 s8, vcc_lo, 0x40000
	s_addc_u32 s9, vcc_hi, 0
	s_mov_b32 m0, s67
	v_lshl_add_u64 v[6:7], s[8:9], 0, v[176:177]
	ds_read_b128 v[128:131], v215 offset:32768
	ds_read_b128 v[132:135], v215 offset:33792
	ds_read_b128 v[140:143], v215 offset:34816
	ds_read_b128 v[188:191], v215 offset:35840
	ds_read_b128 v[192:195], v215 offset:36864
	ds_read_b128 v[196:199], v215 offset:37888
	ds_read_b128 v[216:219], v215 offset:38912
	ds_read_b128 v[220:223], v215 offset:39936
	global_load_lds_dwordx4 v[6:7], off
	v_lshl_add_u64 v[6:7], s[8:9], 0, v[180:181]
	s_mov_b32 m0, s80
	s_nop 0
	global_load_lds_dwordx4 v[6:7], off
	s_waitcnt vmcnt(8)
	s_waitcnt lgkmcnt(0)
	s_barrier
	s_setprio 1
	s_waitcnt lgkmcnt(0)
	v_mfma_i32_16x16x64_i8 v[172:175], v[44:47], v[128:131], v[172:175]
	v_mfma_i32_16x16x64_i8 v[172:175], v[52:55], v[132:135], v[172:175]
	v_mfma_i32_16x16x64_i8 v[164:167], v[60:63], v[128:131], v[164:167]
	v_mfma_i32_16x16x64_i8 v[164:167], v[64:67], v[132:135], v[164:167]
	v_mfma_i32_16x16x64_i8 v[168:171], v[44:47], v[140:143], v[168:171]
	v_mfma_i32_16x16x64_i8 v[168:171], v[52:55], v[188:191], v[168:171]
	v_mfma_i32_16x16x64_i8 v[160:163], v[60:63], v[140:143], v[160:163]
	v_mfma_i32_16x16x64_i8 v[160:163], v[64:67], v[188:191], v[160:163]
	v_mfma_i32_16x16x64_i8 v[156:159], v[44:47], v[192:195], v[156:159]
	v_mfma_i32_16x16x64_i8 v[156:159], v[52:55], v[196:199], v[156:159]
	v_mfma_i32_16x16x64_i8 v[152:155], v[60:63], v[192:195], v[152:155]
	v_mfma_i32_16x16x64_i8 v[152:155], v[64:67], v[196:199], v[152:155]
	v_mfma_i32_16x16x64_i8 v[148:151], v[44:47], v[216:219], v[148:151]
	v_mfma_i32_16x16x64_i8 v[148:151], v[52:55], v[220:223], v[148:151]
	v_mfma_i32_16x16x64_i8 v[144:147], v[60:63], v[216:219], v[144:147]
	v_mfma_i32_16x16x64_i8 v[144:147], v[64:67], v[220:223], v[144:147]
	s_setprio 0
	s_setprio 1
	v_mfma_i32_16x16x64_i8 v[136:139], v[84:87], v[128:131], v[136:139]
	v_mfma_i32_16x16x64_i8 v[136:139], v[88:91], v[132:135], v[136:139]
	v_mfma_i32_16x16x64_i8 v[120:123], v[92:95], v[128:131], v[120:123]
	v_mfma_i32_16x16x64_i8 v[120:123], v[100:103], v[132:135], v[120:123]
	v_mfma_i32_16x16x64_i8 v[124:127], v[84:87], v[140:143], v[124:127]
	v_mfma_i32_16x16x64_i8 v[132:135], v[88:91], v[188:191], v[124:127]
	v_mfma_i32_16x16x64_i8 v[116:119], v[92:95], v[140:143], v[116:119]
	v_mfma_i32_16x16x64_i8 v[116:119], v[100:103], v[188:191], v[116:119]
	v_mfma_i32_16x16x64_i8 v[112:115], v[84:87], v[192:195], v[112:115]
	v_mfma_i32_16x16x64_i8 v[112:115], v[88:91], v[196:199], v[112:115]
	v_mfma_i32_16x16x64_i8 v[108:111], v[92:95], v[192:195], v[108:111]
	v_mfma_i32_16x16x64_i8 v[108:111], v[100:103], v[196:199], v[108:111]
	v_mfma_i32_16x16x64_i8 v[104:107], v[84:87], v[216:219], v[104:107]
	v_mfma_i32_16x16x64_i8 v[104:107], v[88:91], v[220:223], v[104:107]
	v_mfma_i32_16x16x64_i8 v[96:99], v[92:95], v[216:219], v[96:99]
	v_mfma_i32_16x16x64_i8 v[96:99], v[100:103], v[220:223], v[96:99]
	s_setprio 0
	s_barrier
	s_add_i32 s8, s10, s12
	v_lshl_add_u64 v[6:7], v[200:201], 0, s[92:93]
	s_mov_b32 m0, s8
	ds_read_b128 v[124:127], v215 offset:49152
	ds_read_b128 v[128:131], v215 offset:50176
	ds_read_b128 v[140:143], v215 offset:51200
	ds_read_b128 v[188:191], v215 offset:52224
	ds_read_b128 v[192:195], v215 offset:53248
	ds_read_b128 v[196:199], v215 offset:54272
	ds_read_b128 v[216:219], v215 offset:55296
	ds_read_b128 v[220:223], v215 offset:56320
	global_load_lds_dwordx4 v[6:7], off
	s_add_i32 m0, s8, 0x2000
	s_add_u32 s8, s82, 0x40080
	v_lshl_add_u64 v[6:7], v[206:207], 0, s[92:93]
	s_addc_u32 s9, s83, 0
	s_add_i32 s10, s11, s12
	global_load_lds_dwordx4 v[6:7], off
	v_lshl_add_u64 v[6:7], s[8:9], 0, v[178:179]
	s_mov_b32 m0, s10
	s_nop 0
	global_load_lds_dwordx4 v[6:7], off
	v_lshl_add_u64 v[6:7], s[8:9], 0, v[182:183]
	s_add_i32 m0, s10, 0x2000
	s_nop 0
	global_load_lds_dwordx4 v[6:7], off
	v_lshl_add_u64 v[6:7], v[210:211], 0, s[92:93]
	s_mov_b32 m0, s58
	s_nop 0
	global_load_lds_dwordx4 v[6:7], off
	v_lshl_add_u64 v[6:7], v[224:225], 0, s[92:93]
	s_mov_b32 m0, s4
	s_nop 0
	global_load_lds_dwordx4 v[6:7], off
	s_waitcnt vmcnt(8)
	s_waitcnt lgkmcnt(0)
	s_barrier
	s_setprio 1
	s_waitcnt lgkmcnt(0)
	v_mfma_i32_16x16x64_i8 v[80:83], v[44:47], v[124:127], v[80:83]
	v_mfma_i32_16x16x64_i8 v[80:83], v[52:55], v[128:131], v[80:83]
	v_mfma_i32_16x16x64_i8 v[72:75], v[60:63], v[124:127], v[72:75]
	v_mfma_i32_16x16x64_i8 v[72:75], v[64:67], v[128:131], v[72:75]
	v_mfma_i32_16x16x64_i8 v[76:79], v[44:47], v[140:143], v[76:79]
	v_mfma_i32_16x16x64_i8 v[76:79], v[52:55], v[188:191], v[76:79]
	v_mfma_i32_16x16x64_i8 v[68:71], v[60:63], v[140:143], v[68:71]
	v_mfma_i32_16x16x64_i8 v[68:71], v[64:67], v[188:191], v[68:71]
	v_mfma_i32_16x16x64_i8 v[56:59], v[44:47], v[192:195], v[56:59]
	v_mfma_i32_16x16x64_i8 v[56:59], v[52:55], v[196:199], v[56:59]
	v_mfma_i32_16x16x64_i8 v[48:51], v[60:63], v[192:195], v[48:51]
	v_mfma_i32_16x16x64_i8 v[48:51], v[64:67], v[196:199], v[48:51]
	v_mfma_i32_16x16x64_i8 v[40:43], v[44:47], v[216:219], v[40:43]
	v_mfma_i32_16x16x64_i8 v[40:43], v[52:55], v[220:223], v[40:43]
	v_mfma_i32_16x16x64_i8 v[36:39], v[60:63], v[216:219], v[36:39]
	v_mfma_i32_16x16x64_i8 v[36:39], v[64:67], v[220:223], v[36:39]
	s_setprio 0
	s_setprio 1
	v_mfma_i32_16x16x64_i8 v[32:35], v[84:87], v[124:127], v[32:35]
	v_mfma_i32_16x16x64_i8 v[32:35], v[88:91], v[128:131], v[32:35]
	v_mfma_i32_16x16x64_i8 v[24:27], v[92:95], v[124:127], v[24:27]
	v_mfma_i32_16x16x64_i8 v[24:27], v[100:103], v[128:131], v[24:27]
	v_mfma_i32_16x16x64_i8 v[28:31], v[84:87], v[140:143], v[28:31]
	v_mfma_i32_16x16x64_i8 v[28:31], v[88:91], v[188:191], v[28:31]
	v_mfma_i32_16x16x64_i8 v[20:23], v[92:95], v[140:143], v[20:23]
	v_mfma_i32_16x16x64_i8 v[20:23], v[100:103], v[188:191], v[20:23]
	v_mfma_i32_16x16x64_i8 v[16:19], v[84:87], v[192:195], v[16:19]
	v_mfma_i32_16x16x64_i8 v[16:19], v[88:91], v[196:199], v[16:19]
	v_mfma_i32_16x16x64_i8 v[12:15], v[92:95], v[192:195], v[12:15]
	v_mfma_i32_16x16x64_i8 v[12:15], v[100:103], v[196:199], v[12:15]
	v_mfma_i32_16x16x64_i8 v[6:9], v[84:87], v[216:219], v[8:11]
	v_mfma_i32_16x16x64_i8 v[8:11], v[88:91], v[220:223], v[6:9]
	v_mfma_i32_16x16x64_i8 v[2:5], v[92:95], v[216:219], v[2:5]
	v_mfma_i32_16x16x64_i8 v[4:7], v[100:103], v[220:223], v[2:5]
	s_setprio 0
	s_barrier
	s_add_i32 s5, s5, 2
	s_add_u32 s85, s85, 0x100
	s_addc_u32 s68, s68, 0
	s_cmp_gt_u32 s5, 13
	s_mov_b64 s[8:9], s[70:71]
	s_cbranch_scc0 .LBB0_385
	s_branch .Lpeelx385
; #define PG8_STAGE(bufoff, gbase, voff) do { _Pragma("unroll") for (int _i = 0; _i < 2; ++_i) \
;         __builtin_amdgcn_global_load_lds((const unsigned*)((const char*)(gbase) + (voff)[_i]), (PG8_LAS unsigned*)(lds + (bufoff) + ldsw + _i * 8192), 16, 0, 0); } while (0)
; #define PG8_LDA(dst, b, h) do { _Pragma("unroll") for (int m = 0; m < 4; ++m) _Pragma("unroll") for (int k = 0; k < 2; ++k) dst[m][k] = *(const PG8_LAS bf16x8*)(lds + PG8_SA(b, h) + aoff + m * 2048 + k * 1024); } while (0)
; #define PG8_LDB(dst, b, h) do { _Pragma("unroll") for (int n = 0; n < 2; ++n) _Pragma("unroll") for (int k = 0; k < 2; ++k) dst[n][k] = *(const PG8_LAS bf16x8*)(lds + PG8_SB(b, h) + boff + n * 2048 + k * 1024); } while (0)
; #define PG8_MMA(ai, bj, At, Bt) do { __builtin_amdgcn_s_setprio(1); _Pragma("unroll") for (int m = 0; m < 4; ++m) _Pragma("unroll") for (int n = 0; n < 2; ++n) _Pragma("unroll") for (int k = 0; k < 2; ++k) \
;         acc[ai][bj][m][n] = mma16<Epi::I8>(Bt[n][k], At[m][k], acc[ai][bj][m][n]); __builtin_amdgcn_s_setprio(0); } while (0)
; #define PG8_WAIT_V(n) asm volatile("s_waitcnt vmcnt(" #n ")" ::: "memory")
; template <class Epi, class Sched, bool ALIGN_EPI = false, bool SP2 = false>
; __device__ __forceinline__ void gemm_phase(PG8_LAS unsigned char* lds, const Gemm g, const Sched& S, const Epi& E) {
;     ...
;         const bool has_next = S.next(ui + 1, nxt);
;         const char* nA = has_next ? (const char*)g.A + (size_t)nxt.pm * tstep : cA; const char* nB = has_next ? (const char*)g.Bt + (size_t)nxt.pn * tstep : cB;
;         for (int t = 0; t < nt; t += 2) {
;             const bool last = (t == nt - 2);
;             const char* a1 = cA + (size_t)(t + 1) * kstep;
;             const char* a2 = last ? nA : cA + (size_t)(t + 2) * kstep; const char* b2 = last ? nB : cB + (size_t)(t + 2) * kstep;
;             const char* a3 = a2 + kstep; const char* b3 = b2 + kstep;
;             if (last && has_next) S.a_ready(nxt);
;             if constexpr (SP2) {
;             PG8_LDB(B0, 0, 0); PG8_LDB(B1, 0, 1); PG8_SCHED; PG8_LDA(At, 0, 0); PG8_STAGE(PG8_SA(1, 1), a1 + hstep, voffA);
;             PG8_WAIT_V(8); PG8_WAIT_L(0); PG8_BAR; PG8_MMA(0, 0, At, B0); PG8_MMA(0, 1, At, B1); PG8_BAR; PG8_SCHED;
;             PG8_LDA(At, 0, 1); PG8_STAGE(PG8_SB(0, 0), b2, voffB); PG8_STAGE(PG8_SB(0, 1), b2 + hstep, voffB); PG8_STAGE(PG8_SA(0, 0), a2, voffA);
.LBB0_385:
	s_add_u32 s70, s8, 0x100
	s_addc_u32 s71, s9, 0
	s_add_i32 s84, 0, 0x10000
	s_cmp_eq_u32 s5, 12
	s_cselect_b32 vcc_hi, s1, s71
	s_cselect_b32 vcc_lo, s7, s70
	v_add_u32_e32 v0, s84, v214
	s_cselect_b32 s83, s69, s68
	s_cselect_b32 s82, s81, s85
	s_add_i32 s10, 0, 0x14000
	ds_read_b128 v[44:47], v0
	ds_read_b128 v[52:55], v0 offset:1024
	ds_read_b128 v[60:63], v0 offset:2048
	ds_read_b128 v[64:67], v0 offset:3072
	v_add_u32_e32 v0, s10, v214
	ds_read_b128 v[84:87], v0
	ds_read_b128 v[88:91], v0 offset:1024
	ds_read_b128 v[92:95], v0 offset:2048
	ds_read_b128 v[100:103], v0 offset:3072
	v_lshl_add_u64 v[2:3], s[8:9], 0, v[184:185]
	s_add_i32 m0, s13, 0xc000
	ds_read_b128 v[124:127], v215
	ds_read_b128 v[128:131], v215 offset:1024
	ds_read_b128 v[140:143], v215 offset:2048
	ds_read_b128 v[188:191], v215 offset:3072
	ds_read_b128 v[192:195], v215 offset:4096
	ds_read_b128 v[196:199], v215 offset:5120
	ds_read_b128 v[216:219], v215 offset:6144
	ds_read_b128 v[220:223], v215 offset:7168
	global_load_lds_dwordx4 v[2:3], off
	v_lshl_add_u64 v[2:3], s[8:9], 0, v[186:187]
	s_add_i32 m0, s13, 0xe000
	s_nop 0
	global_load_lds_dwordx4 v[2:3], off
	s_waitcnt vmcnt(8)
	s_waitcnt lgkmcnt(0)
	s_barrier
	s_setprio 1
	s_waitcnt lgkmcnt(0)
	v_mfma_i32_16x16x64_i8 v[172:175], v[44:47], v[124:127], v[172:175]
	v_mfma_i32_16x16x64_i8 v[172:175], v[52:55], v[128:131], v[172:175]
	v_mfma_i32_16x16x64_i8 v[164:167], v[60:63], v[124:127], v[164:167]
	v_mfma_i32_16x16x64_i8 v[164:167], v[64:67], v[128:131], v[164:167]
	v_mfma_i32_16x16x64_i8 v[168:171], v[44:47], v[140:143], v[168:171]
	v_mfma_i32_16x16x64_i8 v[168:171], v[52:55], v[188:191], v[168:171]
	v_mfma_i32_16x16x64_i8 v[160:163], v[60:63], v[140:143], v[160:163]
	v_mfma_i32_16x16x64_i8 v[160:163], v[64:67], v[188:191], v[160:163]
	v_mfma_i32_16x16x64_i8 v[156:159], v[44:47], v[192:195], v[156:159]
	v_mfma_i32_16x16x64_i8 v[156:159], v[52:55], v[196:199], v[156:159]
	v_mfma_i32_16x16x64_i8 v[152:155], v[60:63], v[192:195], v[152:155]
	v_mfma_i32_16x16x64_i8 v[152:155], v[64:67], v[196:199], v[152:155]
	v_mfma_i32_16x16x64_i8 v[148:151], v[44:47], v[216:219], v[148:151]
	v_mfma_i32_16x16x64_i8 v[148:151], v[52:55], v[220:223], v[148:151]
	v_mfma_i32_16x16x64_i8 v[144:147], v[60:63], v[216:219], v[144:147]
	v_mfma_i32_16x16x64_i8 v[144:147], v[64:67], v[220:223], v[144:147]
	s_setprio 0
	s_setprio 1
	v_mfma_i32_16x16x64_i8 v[136:139], v[84:87], v[124:127], v[136:139]
	v_mfma_i32_16x16x64_i8 v[136:139], v[88:91], v[128:131], v[136:139]
	v_mfma_i32_16x16x64_i8 v[120:123], v[92:95], v[124:127], v[120:123]
	v_mfma_i32_16x16x64_i8 v[120:123], v[100:103], v[128:131], v[120:123]
	v_mfma_i32_16x16x64_i8 v[116:119], v[92:95], v[140:143], v[116:119]
	v_mfma_i32_16x16x64_i8 v[116:119], v[100:103], v[188:191], v[116:119]
	v_mfma_i32_16x16x64_i8 v[112:115], v[84:87], v[192:195], v[112:115]
	v_mfma_i32_16x16x64_i8 v[112:115], v[88:91], v[196:199], v[112:115]
	v_mfma_i32_16x16x64_i8 v[108:111], v[92:95], v[192:195], v[108:111]
	v_mfma_i32_16x16x64_i8 v[108:111], v[100:103], v[196:199], v[108:111]
	v_mfma_i32_16x16x64_i8 v[104:107], v[84:87], v[216:219], v[104:107]
	v_mfma_i32_16x16x64_i8 v[104:107], v[88:91], v[220:223], v[104:107]
	v_mfma_i32_16x16x64_i8 v[96:99], v[92:95], v[216:219], v[96:99]
	v_mfma_i32_16x16x64_i8 v[96:99], v[100:103], v[220:223], v[96:99]
	v_mfma_i32_16x16x64_i8 v[124:127], v[84:87], v[140:143], v[132:135]
	v_mfma_i32_16x16x64_i8 v[124:127], v[88:91], v[188:191], v[124:127]
	s_setprio 0
	s_barrier
	s_add_i32 s8, s84, s12
	v_lshl_add_u64 v[200:201], s[82:83], 0, v[178:179]
	s_mov_b32 m0, s8
	ds_read_b128 v[128:131], v215 offset:16384
	ds_read_b128 v[132:135], v215 offset:17408
	ds_read_b128 v[140:143], v215 offset:18432
	ds_read_b128 v[188:191], v215 offset:19456
	ds_read_b128 v[192:195], v215 offset:20480
	ds_read_b128 v[196:199], v215 offset:21504
	ds_read_b128 v[216:219], v215 offset:22528
	ds_read_b128 v[220:223], v215 offset:23552
	global_load_lds_dwordx4 v[200:201], off
	s_add_i32 m0, s8, 0x2000
	s_add_u32 s8, s82, 0x40000
	v_lshl_add_u64 v[206:207], s[82:83], 0, v[182:183]
	s_addc_u32 s9, s83, 0
	s_add_i32 s10, s10, s12
	global_load_lds_dwordx4 v[206:207], off
	v_lshl_add_u64 v[2:3], s[8:9], 0, v[178:179]
	s_mov_b32 m0, s10
	v_lshl_add_u64 v[210:211], vcc, 0, v[176:177]
	global_load_lds_dwordx4 v[2:3], off
	v_lshl_add_u64 v[2:3], s[8:9], 0, v[182:183]
	s_add_i32 m0, s10, 0x2000
	v_lshl_add_u64 v[224:225], vcc, 0, v[180:181]
	global_load_lds_dwordx4 v[2:3], off
	s_mov_b32 m0, s13
	s_nop 0
	global_load_lds_dwordx4 v[210:211], off
	s_mov_b32 m0, s66
	s_nop 0
	global_load_lds_dwordx4 v[224:225], off
	s_waitcnt vmcnt(8)
	s_waitcnt lgkmcnt(0)
	s_barrier
; #define PG8_STAGE(bufoff, gbase, voff) do { _Pragma("unroll") for (int _i = 0; _i < 2; ++_i) \
;         __builtin_amdgcn_global_load_lds((const unsigned*)((const char*)(gbase) + (voff)[_i]), (PG8_LAS unsigned*)(lds + (bufoff) + ldsw + _i * 8192), 16, 0, 0); } while (0)
; #define PG8_LDA(dst, b, h) do { _Pragma("unroll") for (int m = 0; m < 4; ++m) _Pragma("unroll") for (int k = 0; k < 2; ++k) dst[m][k] = *(const PG8_LAS bf16x8*)(lds + PG8_SA(b, h) + aoff + m * 2048 + k * 1024); } while (0)
; #define PG8_LDB(dst, b, h) do { _Pragma("unroll") for (int n = 0; n < 2; ++n) _Pragma("unroll") for (int k = 0; k < 2; ++k) dst[n][k] = *(const PG8_LAS bf16x8*)(lds + PG8_SB(b, h) + boff + n * 2048 + k * 1024); } while (0)
; #define PG8_MMA(ai, bj, At, Bt) do { __builtin_amdgcn_s_setprio(1); _Pragma("unroll") for (int m = 0; m < 4; ++m) _Pragma("unroll") for (int n = 0; n < 2; ++n) _Pragma("unroll") for (int k = 0; k < 2; ++k) \
;         acc[ai][bj][m][n] = mma16<Epi::I8>(Bt[n][k], At[m][k], acc[ai][bj][m][n]); __builtin_amdgcn_s_setprio(0); } while (0)
; #define PG8_WAIT_V(n) asm volatile("s_waitcnt vmcnt(" #n ")" ::: "memory")
; #define PG8_WAIT_L(n) asm volatile("s_waitcnt lgkmcnt(" #n ")" ::: "memory")
; #define PG8_BAR __builtin_amdgcn_s_barrier()
; #define PG8_SCHED __builtin_amdgcn_sched_barrier(0)
; template <class Epi, class Sched, bool ALIGN_EPI = false, bool SP2 = false>
; __device__ __forceinline__ void gemm_phase(PG8_LAS unsigned char* lds, const Gemm g, const Sched& S, const Epi& E) {
;     ...
;             PG8_WAIT_V(8); PG8_WAIT_L(0); PG8_BAR; PG8_MMA(1, 0, At, B0); PG8_MMA(1, 1, At, B1); PG8_BAR; PG8_SCHED;
;             PG8_LDB(B0, 1, 0); PG8_LDB(B1, 1, 1); PG8_SCHED; PG8_LDA(At, 1, 0); PG8_STAGE(PG8_SA(0, 1), a2 + hstep, voffA);
;             PG8_WAIT_V(8); PG8_WAIT_L(0); PG8_BAR; PG8_MMA(0, 0, At, B0); PG8_MMA(0, 1, At, B1); PG8_BAR; PG8_SCHED;
;             PG8_LDA(At, 1, 1); PG8_STAGE(PG8_SB(1, 0), b3, voffB); PG8_STAGE(PG8_SB(1, 1), b3 + hstep, voffB); PG8_STAGE(PG8_SA(1, 0), a3, voffA);
	s_setprio 1
	s_waitcnt lgkmcnt(0)
	v_mfma_i32_16x16x64_i8 v[80:83], v[44:47], v[128:131], v[80:83]
	v_mfma_i32_16x16x64_i8 v[80:83], v[52:55], v[132:135], v[80:83]
	v_mfma_i32_16x16x64_i8 v[72:75], v[60:63], v[128:131], v[72:75]
	v_mfma_i32_16x16x64_i8 v[72:75], v[64:67], v[132:135], v[72:75]
	v_mfma_i32_16x16x64_i8 v[76:79], v[44:47], v[140:143], v[76:79]
	v_mfma_i32_16x16x64_i8 v[76:79], v[52:55], v[188:191], v[76:79]
	v_mfma_i32_16x16x64_i8 v[68:71], v[60:63], v[140:143], v[68:71]
	v_mfma_i32_16x16x64_i8 v[68:71], v[64:67], v[188:191], v[68:71]
	v_mfma_i32_16x16x64_i8 v[56:59], v[44:47], v[192:195], v[56:59]
	v_mfma_i32_16x16x64_i8 v[56:59], v[52:55], v[196:199], v[56:59]
	v_mfma_i32_16x16x64_i8 v[48:51], v[60:63], v[192:195], v[48:51]
	v_mfma_i32_16x16x64_i8 v[48:51], v[64:67], v[196:199], v[48:51]
	v_mfma_i32_16x16x64_i8 v[40:43], v[44:47], v[216:219], v[40:43]
	v_mfma_i32_16x16x64_i8 v[40:43], v[52:55], v[220:223], v[40:43]
	v_mfma_i32_16x16x64_i8 v[36:39], v[60:63], v[216:219], v[36:39]
	v_mfma_i32_16x16x64_i8 v[36:39], v[64:67], v[220:223], v[36:39]
	s_setprio 0
	s_setprio 1
	v_mfma_i32_16x16x64_i8 v[32:35], v[84:87], v[128:131], v[32:35]
	v_mfma_i32_16x16x64_i8 v[32:35], v[88:91], v[132:135], v[32:35]
	v_mfma_i32_16x16x64_i8 v[24:27], v[92:95], v[128:131], v[24:27]
	v_mfma_i32_16x16x64_i8 v[24:27], v[100:103], v[132:135], v[24:27]
	v_mfma_i32_16x16x64_i8 v[28:31], v[84:87], v[140:143], v[28:31]
	v_mfma_i32_16x16x64_i8 v[28:31], v[88:91], v[188:191], v[28:31]
	v_mfma_i32_16x16x64_i8 v[20:23], v[92:95], v[140:143], v[20:23]
	v_mfma_i32_16x16x64_i8 v[20:23], v[100:103], v[188:191], v[20:23]
	v_mfma_i32_16x16x64_i8 v[16:19], v[84:87], v[192:195], v[16:19]
	v_mfma_i32_16x16x64_i8 v[16:19], v[88:91], v[196:199], v[16:19]
	v_mfma_i32_16x16x64_i8 v[12:15], v[92:95], v[192:195], v[12:15]
	v_mfma_i32_16x16x64_i8 v[12:15], v[100:103], v[196:199], v[12:15]
	v_mfma_i32_16x16x64_i8 v[8:11], v[84:87], v[216:219], v[8:11]
	v_mfma_i32_16x16x64_i8 v[8:11], v[88:91], v[220:223], v[8:11]
	v_mfma_i32_16x16x64_i8 v[2:5], v[92:95], v[216:219], v[4:7]
	v_mfma_i32_16x16x64_i8 v[2:5], v[100:103], v[220:223], v[2:5]
	s_setprio 0
	s_barrier
	s_add_i32 s10, 0, 0x18000
	v_add_u32_e32 v0, s10, v214
	s_add_i32 s11, 0, 0x1c000
	ds_read_b128 v[44:47], v0
	ds_read_b128 v[52:55], v0 offset:1024
	ds_read_b128 v[60:63], v0 offset:2048
	ds_read_b128 v[64:67], v0 offset:3072
	v_add_u32_e32 v0, s11, v214
	ds_read_b128 v[84:87], v0
	ds_read_b128 v[88:91], v0 offset:1024
	ds_read_b128 v[92:95], v0 offset:2048
	ds_read_b128 v[100:103], v0 offset:3072
	s_add_u32 s8, vcc_lo, 0x40000
	s_addc_u32 s9, vcc_hi, 0
	s_mov_b32 m0, s67
	v_lshl_add_u64 v[6:7], s[8:9], 0, v[176:177]
	ds_read_b128 v[128:131], v215 offset:32768
	ds_read_b128 v[132:135], v215 offset:33792
	ds_read_b128 v[140:143], v215 offset:34816
	ds_read_b128 v[188:191], v215 offset:35840
	ds_read_b128 v[192:195], v215 offset:36864
	ds_read_b128 v[196:199], v215 offset:37888
	ds_read_b128 v[216:219], v215 offset:38912
	ds_read_b128 v[220:223], v215 offset:39936
	global_load_lds_dwordx4 v[6:7], off
	v_lshl_add_u64 v[6:7], s[8:9], 0, v[180:181]
	s_mov_b32 m0, s80
	s_nop 0
	global_load_lds_dwordx4 v[6:7], off
	s_waitcnt vmcnt(8)
	s_waitcnt lgkmcnt(0)
	s_barrier
	s_setprio 1
	s_waitcnt lgkmcnt(0)
	v_mfma_i32_16x16x64_i8 v[172:175], v[44:47], v[128:131], v[172:175]
	v_mfma_i32_16x16x64_i8 v[172:175], v[52:55], v[132:135], v[172:175]
	v_mfma_i32_16x16x64_i8 v[164:167], v[60:63], v[128:131], v[164:167]
	v_mfma_i32_16x16x64_i8 v[164:167], v[64:67], v[132:135], v[164:167]
	v_mfma_i32_16x16x64_i8 v[168:171], v[44:47], v[140:143], v[168:171]
	v_mfma_i32_16x16x64_i8 v[168:171], v[52:55], v[188:191], v[168:171]
	v_mfma_i32_16x16x64_i8 v[160:163], v[60:63], v[140:143], v[160:163]
	v_mfma_i32_16x16x64_i8 v[160:163], v[64:67], v[188:191], v[160:163]
	v_mfma_i32_16x16x64_i8 v[156:159], v[44:47], v[192:195], v[156:159]
	v_mfma_i32_16x16x64_i8 v[156:159], v[52:55], v[196:199], v[156:159]
	v_mfma_i32_16x16x64_i8 v[152:155], v[60:63], v[192:195], v[152:155]
	v_mfma_i32_16x16x64_i8 v[152:155], v[64:67], v[196:199], v[152:155]
	v_mfma_i32_16x16x64_i8 v[148:151], v[44:47], v[216:219], v[148:151]
	v_mfma_i32_16x16x64_i8 v[148:151], v[52:55], v[220:223], v[148:151]
	v_mfma_i32_16x16x64_i8 v[144:147], v[60:63], v[216:219], v[144:147]
	v_mfma_i32_16x16x64_i8 v[144:147], v[64:67], v[220:223], v[144:147]
	s_setprio 0
	s_setprio 1
	v_mfma_i32_16x16x64_i8 v[136:139], v[84:87], v[128:131], v[136:139]
	v_mfma_i32_16x16x64_i8 v[136:139], v[88:91], v[132:135], v[136:139]
	v_mfma_i32_16x16x64_i8 v[120:123], v[92:95], v[128:131], v[120:123]
	v_mfma_i32_16x16x64_i8 v[120:123], v[100:103], v[132:135], v[120:123]
	v_mfma_i32_16x16x64_i8 v[124:127], v[84:87], v[140:143], v[124:127]
	v_mfma_i32_16x16x64_i8 v[132:135], v[88:91], v[188:191], v[124:127]
	v_mfma_i32_16x16x64_i8 v[116:119], v[92:95], v[140:143], v[116:119]
	v_mfma_i32_16x16x64_i8 v[116:119], v[100:103], v[188:191], v[116:119]
	v_mfma_i32_16x16x64_i8 v[112:115], v[84:87], v[192:195], v[112:115]
	v_mfma_i32_16x16x64_i8 v[112:115], v[88:91], v[196:199], v[112:115]
	v_mfma_i32_16x16x64_i8 v[108:111], v[92:95], v[192:195], v[108:111]
	v_mfma_i32_16x16x64_i8 v[108:111], v[100:103], v[196:199], v[108:111]
	v_mfma_i32_16x16x64_i8 v[104:107], v[84:87], v[216:219], v[104:107]
	v_mfma_i32_16x16x64_i8 v[104:107], v[88:91], v[220:223], v[104:107]
	v_mfma_i32_16x16x64_i8 v[96:99], v[92:95], v[216:219], v[96:99]
	v_mfma_i32_16x16x64_i8 v[96:99], v[100:103], v[220:223], v[96:99]
	s_setprio 0
	s_barrier
; #define PG8_STAGE(bufoff, gbase, voff) do { _Pragma("unroll") for (int _i = 0; _i < 2; ++_i) \
;         __builtin_amdgcn_global_load_lds((const unsigned*)((const char*)(gbase) + (voff)[_i]), (PG8_LAS unsigned*)(lds + (bufoff) + ldsw + _i * 8192), 16, 0, 0); } while (0)
; #define PG8_LDA(dst, b, h) do { _Pragma("unroll") for (int m = 0; m < 4; ++m) _Pragma("unroll") for (int k = 0; k < 2; ++k) dst[m][k] = *(const PG8_LAS bf16x8*)(lds + PG8_SA(b, h) + aoff + m * 2048 + k * 1024); } while (0)
; #define PG8_MMA(ai, bj, At, Bt) do { __builtin_amdgcn_s_setprio(1); _Pragma("unroll") for (int m = 0; m < 4; ++m) _Pragma("unroll") for (int n = 0; n < 2; ++n) _Pragma("unroll") for (int k = 0; k < 2; ++k) \
;         acc[ai][bj][m][n] = mma16<Epi::I8>(Bt[n][k], At[m][k], acc[ai][bj][m][n]); __builtin_amdgcn_s_setprio(0); } while (0)
; #define PG8_WAIT_V(n) asm volatile("s_waitcnt vmcnt(" #n ")" ::: "memory")
; #define PG8_WAIT_L(n) asm volatile("s_waitcnt lgkmcnt(" #n ")" ::: "memory")
; #define PG8_BAR __builtin_amdgcn_s_barrier()
; #define PG8_SCHED __builtin_amdgcn_sched_barrier(0)
; template <class Epi, class Sched, bool ALIGN_EPI = false, bool SP2 = false>
; __device__ __forceinline__ void gemm_phase(PG8_LAS unsigned char* lds, const Gemm g, const Sched& S, const Epi& E) {
;     ...
;             PG8_LDA(At, 1, 1); PG8_STAGE(PG8_SB(1, 0), b3, voffB); PG8_STAGE(PG8_SB(1, 1), b3 + hstep, voffB); PG8_STAGE(PG8_SA(1, 0), a3, voffA);
;             PG8_WAIT_V(8); PG8_WAIT_L(0); PG8_BAR; PG8_MMA(1, 0, At, B0); PG8_MMA(1, 1, At, B1); PG8_BAR; PG8_SCHED;
	s_add_i32 s8, s10, s12
	v_lshl_add_u64 v[6:7], v[200:201], 0, s[92:93]
	s_mov_b32 m0, s8
	ds_read_b128 v[124:127], v215 offset:49152
	ds_read_b128 v[128:131], v215 offset:50176
	ds_read_b128 v[140:143], v215 offset:51200
	ds_read_b128 v[188:191], v215 offset:52224
	ds_read_b128 v[192:195], v215 offset:53248
	ds_read_b128 v[196:199], v215 offset:54272
	ds_read_b128 v[216:219], v215 offset:55296
	ds_read_b128 v[220:223], v215 offset:56320
	global_load_lds_dwordx4 v[6:7], off
	s_add_i32 m0, s8, 0x2000
	s_add_u32 s8, s82, 0x40080
	v_lshl_add_u64 v[6:7], v[206:207], 0, s[92:93]
	s_addc_u32 s9, s83, 0
	s_add_i32 s10, s11, s12
	global_load_lds_dwordx4 v[6:7], off
	v_lshl_add_u64 v[6:7], s[8:9], 0, v[178:179]
	s_mov_b32 m0, s10
	s_nop 0
	global_load_lds_dwordx4 v[6:7], off
	v_lshl_add_u64 v[6:7], s[8:9], 0, v[182:183]
	s_add_i32 m0, s10, 0x2000
	s_nop 0
	global_load_lds_dwordx4 v[6:7], off
	v_lshl_add_u64 v[6:7], v[210:211], 0, s[92:93]
	s_mov_b32 m0, s58
	s_nop 0
	global_load_lds_dwordx4 v[6:7], off
	v_lshl_add_u64 v[6:7], v[224:225], 0, s[92:93]
	s_mov_b32 m0, s4
	s_nop 0
	global_load_lds_dwordx4 v[6:7], off
	s_waitcnt vmcnt(8)
	s_waitcnt lgkmcnt(0)
	s_barrier
	s_setprio 1
	s_waitcnt lgkmcnt(0)
	v_mfma_i32_16x16x64_i8 v[80:83], v[44:47], v[124:127], v[80:83]
	v_mfma_i32_16x16x64_i8 v[80:83], v[52:55], v[128:131], v[80:83]
	v_mfma_i32_16x16x64_i8 v[72:75], v[60:63], v[124:127], v[72:75]
	v_mfma_i32_16x16x64_i8 v[72:75], v[64:67], v[128:131], v[72:75]
	v_mfma_i32_16x16x64_i8 v[76:79], v[44:47], v[140:143], v[76:79]
	v_mfma_i32_16x16x64_i8 v[76:79], v[52:55], v[188:191], v[76:79]
	v_mfma_i32_16x16x64_i8 v[68:71], v[60:63], v[140:143], v[68:71]
	v_mfma_i32_16x16x64_i8 v[68:71], v[64:67], v[188:191], v[68:71]
	v_mfma_i32_16x16x64_i8 v[56:59], v[44:47], v[192:195], v[56:59]
	v_mfma_i32_16x16x64_i8 v[56:59], v[52:55], v[196:199], v[56:59]
	v_mfma_i32_16x16x64_i8 v[48:51], v[60:63], v[192:195], v[48:51]
	v_mfma_i32_16x16x64_i8 v[48:51], v[64:67], v[196:199], v[48:51]
	v_mfma_i32_16x16x64_i8 v[40:43], v[44:47], v[216:219], v[40:43]
	v_mfma_i32_16x16x64_i8 v[40:43], v[52:55], v[220:223], v[40:43]
	v_mfma_i32_16x16x64_i8 v[36:39], v[60:63], v[216:219], v[36:39]
	v_mfma_i32_16x16x64_i8 v[36:39], v[64:67], v[220:223], v[36:39]
	s_setprio 0
	s_setprio 1
	v_mfma_i32_16x16x64_i8 v[32:35], v[84:87], v[124:127], v[32:35]
	v_mfma_i32_16x16x64_i8 v[32:35], v[88:91], v[128:131], v[32:35]
	v_mfma_i32_16x16x64_i8 v[24:27], v[92:95], v[124:127], v[24:27]
	v_mfma_i32_16x16x64_i8 v[24:27], v[100:103], v[128:131], v[24:27]
	v_mfma_i32_16x16x64_i8 v[28:31], v[84:87], v[140:143], v[28:31]
	v_mfma_i32_16x16x64_i8 v[28:31], v[88:91], v[188:191], v[28:31]
	v_mfma_i32_16x16x64_i8 v[20:23], v[92:95], v[140:143], v[20:23]
	v_mfma_i32_16x16x64_i8 v[20:23], v[100:103], v[188:191], v[20:23]
	v_mfma_i32_16x16x64_i8 v[16:19], v[84:87], v[192:195], v[16:19]
	v_mfma_i32_16x16x64_i8 v[16:19], v[88:91], v[196:199], v[16:19]
	v_mfma_i32_16x16x64_i8 v[12:15], v[92:95], v[192:195], v[12:15]
	v_mfma_i32_16x16x64_i8 v[12:15], v[100:103], v[196:199], v[12:15]
	v_mfma_i32_16x16x64_i8 v[6:9], v[84:87], v[216:219], v[8:11]
	v_mfma_i32_16x16x64_i8 v[8:11], v[88:91], v[220:223], v[6:9]
	v_mfma_i32_16x16x64_i8 v[2:5], v[92:95], v[216:219], v[2:5]
	v_mfma_i32_16x16x64_i8 v[4:7], v[100:103], v[220:223], v[2:5]
	s_setprio 0
	s_barrier
	s_add_i32 s5, s5, 2
	s_add_u32 s85, s85, 0x100
	s_addc_u32 s68, s68, 0
	s_cmp_gt_u32 s5, 13
	s_mov_b64 s[8:9], s[70:71]
	s_cbranch_scc0 .LBB0_385
